# K-loops: address SALU moved out of the LDS-read segments, saddr-form LDS-DMA in phases 1 and 3
# baseline (speedup 1.0000x reference)
; #define PG8_STAGE(bufoff, gbase, voff) do { _Pragma("unroll") for (int _i = 0; _i < 2; ++_i) \
;         __builtin_amdgcn_global_load_lds((const unsigned*)((const char*)(gbase) + (voff)[_i]), (LAS unsigned*)(lds + (bufoff) + ldsw + _i * 8192), 16, 0, 0); } while (0)
; #define PG8_LDA(dst, b, h) do { _Pragma("unroll") for (int m = 0; m < 4; ++m) _Pragma("unroll") for (int k = 0; k < 2; ++k) dst[m][k] = *(const LAS bf16x8*)(lds + PG8_SA(b, h) + aoff + m * 2048 + k * 1024); } while (0)
; #define PG8_LDB(dst, b, h) do { _Pragma("unroll") for (int n = 0; n < 2; ++n) _Pragma("unroll") for (int k = 0; k < 2; ++k) dst[n][k] = *(const LAS bf16x8*)(lds + PG8_SB(b, h) + boff + n * 2048 + k * 1024); } while (0)
; #define PG8_WAIT_V(n) asm volatile("s_waitcnt vmcnt(" #n ")" ::: "memory")
; #define PG8_WAIT_L(n) asm volatile("s_waitcnt lgkmcnt(" #n ")" ::: "memory")
; #define PG8_BAR __builtin_amdgcn_s_barrier()
; #define PG8_SCHED __builtin_amdgcn_sched_barrier(0)
; template <bool F16, class Sched, class Epi>
; __device__ __forceinline__ void gemm_phase(LAS unsigned char* lds, const Gemm g, const Sched& S, const Epi& E, int wave_s) {
;     ...
;             const char* a1 = cA + (size_t)(t + 1) * kstep;
;             const char* a2 = last ? nA : cA + (size_t)(t + 2) * kstep; const char* b2 = last ? nB : cB + (size_t)(t + 2) * kstep;
;             const char* a3 = a2 + kstep; const char* b3 = b2 + kstep;
;             PG8_LDB(B0, 0, 0); PG8_LDB(B1, 0, 1); PG8_SCHED; PG8_LDA(At, 0, 0); PG8_STAGE(PG8_SA(1, 1), a1 + hstepA, voffA);
;             PG8_WAIT_V(8); PG8_WAIT_L(0); PG8_BAR; PG8_MMA(0, 0, At, B0); PG8_MMA(0, 1, At, B1); PG8_BAR; PG8_SCHED;
;             PG8_LDA(At, 0, 1); PG8_STAGE(PG8_SB(0, 0), b2, voffB); PG8_STAGE(PG8_SB(0, 1), b2 + hstepB, voffB); PG8_STAGE(PG8_SA(0, 0), a2, voffA);
;             PG8_WAIT_V(8); PG8_WAIT_L(0); PG8_BAR; PG8_MMA(1, 0, At, B0); PG8_MMA(1, 1, At, B1); PG8_BAR; PG8_SCHED;
.LBB0_234:
	s_add_i32 s60, 0, 0x10000
	s_add_i32 s62, 0, 0x14000
	v_add_u32_e32 v150, s60, v163
	v_add_u32_e32 v170, s62, v163
	ds_read_b128 v[138:141], v150
	ds_read_b128 v[142:145], v150 offset:1024
	ds_read_b128 v[146:149], v150 offset:2048
	ds_read_b128 v[150:153], v150 offset:3072
	ds_read_b128 v[154:157], v170
	ds_read_b128 v[158:161], v170 offset:1024
	ds_read_b128 v[166:169], v170 offset:2048
	ds_read_b128 v[170:173], v170 offset:3072
	s_add_i32 m0, s41, 0xc000
	ds_read_b128 v[178:181], v165
	ds_read_b128 v[182:185], v165 offset:1024
	ds_read_b128 v[186:189], v165 offset:2048
	ds_read_b128 v[190:193], v165 offset:3072
	ds_read_b128 v[208:211], v165 offset:4096
	ds_read_b128 v[212:215], v165 offset:5120
	ds_read_b128 v[216:219], v165 offset:6144
	ds_read_b128 v[220:223], v165 offset:7168
	global_load_lds_dwordx4 v134, s[26:27]
	s_add_i32 m0, s41, 0xe000
	s_nop 0
	global_load_lds_dwordx4 v136, s[26:27]
	s_waitcnt vmcnt(8)
	s_waitcnt lgkmcnt(0)
	s_barrier
	s_setprio 1
	s_waitcnt lgkmcnt(0)
	v_mfma_f32_16x16x32_bf16 v[124:127], v[138:141], v[178:181], v[124:127]
	v_mfma_f32_16x16x32_bf16 v[120:123], v[146:149], v[178:181], v[120:123]
	v_mfma_f32_16x16x32_bf16 v[108:111], v[138:141], v[186:189], v[108:111]
	v_mfma_f32_16x16x32_bf16 v[104:107], v[146:149], v[186:189], v[104:107]
	v_mfma_f32_16x16x32_bf16 v[96:99], v[138:141], v[208:211], v[96:99]
	v_mfma_f32_16x16x32_bf16 v[92:95], v[146:149], v[208:211], v[92:95]
	v_mfma_f32_16x16x32_bf16 v[84:87], v[138:141], v[216:219], v[84:87]
	v_mfma_f32_16x16x32_bf16 v[76:79], v[146:149], v[216:219], v[76:79]
	v_mfma_f32_16x16x32_bf16 v[124:127], v[142:145], v[182:185], v[124:127]
	v_mfma_f32_16x16x32_bf16 v[120:123], v[150:153], v[182:185], v[120:123]
	v_mfma_f32_16x16x32_bf16 v[108:111], v[142:145], v[190:193], v[108:111]
	v_mfma_f32_16x16x32_bf16 v[104:107], v[150:153], v[190:193], v[104:107]
	v_mfma_f32_16x16x32_bf16 v[96:99], v[142:145], v[212:215], v[96:99]
	v_mfma_f32_16x16x32_bf16 v[92:95], v[150:153], v[212:215], v[92:95]
	v_mfma_f32_16x16x32_bf16 v[84:87], v[142:145], v[220:223], v[84:87]
	v_mfma_f32_16x16x32_bf16 v[76:79], v[150:153], v[220:223], v[76:79]
	s_setprio 0
	s_setprio 1
	v_mfma_f32_16x16x32_bf16 v[116:119], v[154:157], v[178:181], v[116:119]
	v_mfma_f32_16x16x32_bf16 v[112:115], v[166:169], v[178:181], v[112:115]
	v_mfma_f32_16x16x32_bf16 v[100:103], v[154:157], v[186:189], v[100:103]
	v_mfma_f32_16x16x32_bf16 v[88:91], v[166:169], v[186:189], v[88:91]
	v_mfma_f32_16x16x32_bf16 v[80:83], v[154:157], v[208:211], v[80:83]
	v_mfma_f32_16x16x32_bf16 v[72:75], v[166:169], v[208:211], v[72:75]
	v_mfma_f32_16x16x32_bf16 v[68:71], v[154:157], v[216:219], v[68:71]
	v_mfma_f32_16x16x32_bf16 v[64:67], v[166:169], v[216:219], v[64:67]
	v_mfma_f32_16x16x32_bf16 v[116:119], v[158:161], v[182:185], v[116:119]
	v_mfma_f32_16x16x32_bf16 v[112:115], v[170:173], v[182:185], v[112:115]
	v_mfma_f32_16x16x32_bf16 v[100:103], v[158:161], v[190:193], v[100:103]
	v_mfma_f32_16x16x32_bf16 v[88:91], v[170:173], v[190:193], v[88:91]
	v_mfma_f32_16x16x32_bf16 v[80:83], v[158:161], v[212:215], v[80:83]
	v_mfma_f32_16x16x32_bf16 v[72:75], v[170:173], v[212:215], v[72:75]
	v_mfma_f32_16x16x32_bf16 v[68:71], v[158:161], v[220:223], v[68:71]
	v_mfma_f32_16x16x32_bf16 v[64:67], v[170:173], v[220:223], v[64:67]
	s_setprio 0
	s_barrier
	s_add_u32 s28, s26, 0xfff80080
	s_addc_u32 s29, s27, -1
	s_cmp_eq_u32 s59, 4
	s_cselect_b32 s31, s13, s29
	s_cselect_b32 s30, s12, s28
	s_cselect_b32 s29, s0, s58
	s_cselect_b32 s28, s1, s53
	s_add_i32 s60, s60, s39
	v_lshl_add_u64 v[174:175], s[28:29], 0, v[176:177]
	s_mov_b32 m0, s60
	ds_read_b128 v[178:181], v165 offset:16384
	ds_read_b128 v[182:185], v165 offset:17408
	ds_read_b128 v[186:189], v165 offset:18432
	ds_read_b128 v[190:193], v165 offset:19456
	ds_read_b128 v[208:211], v165 offset:20480
	ds_read_b128 v[212:215], v165 offset:21504
	ds_read_b128 v[216:219], v165 offset:22528
	ds_read_b128 v[220:223], v165 offset:23552
	global_load_lds_dwordx4 v[174:175], off
	s_add_i32 m0, s60, 0x2000
	s_add_u32 s60, s28, 0x20000
	v_lshl_add_u64 v[194:195], s[28:29], 0, v[128:129]
	s_addc_u32 s61, s29, 0
	s_add_i32 s62, s62, s39
	global_load_lds_dwordx4 v[194:195], off
	v_lshl_add_u64 v[198:199], s[60:61], 0, v[176:177]
	s_mov_b32 m0, s62
	v_lshl_add_u64 v[200:201], s[30:31], 0, v[130:131]
	global_load_lds_dwordx4 v[198:199], off
	v_lshl_add_u64 v[198:199], s[60:61], 0, v[128:129]
	s_add_i32 m0, s62, 0x2000
	s_nop 0
	global_load_lds_dwordx4 v[198:199], off
	v_lshl_add_u64 v[198:199], s[30:31], 0, v[132:133]
	s_mov_b32 m0, s41
	s_nop 0
	global_load_lds_dwordx4 v[198:199], off
	s_mov_b32 m0, s42
	s_nop 0
	global_load_lds_dwordx4 v[200:201], off
	s_add_u32 s30, s30, 0x80000
	s_addc_u32 s31, s31, 0
	s_waitcnt vmcnt(8)
	s_waitcnt lgkmcnt(0)
	s_barrier
; #define PG8_STAGE(bufoff, gbase, voff) do { _Pragma("unroll") for (int _i = 0; _i < 2; ++_i) \
;         __builtin_amdgcn_global_load_lds((const unsigned*)((const char*)(gbase) + (voff)[_i]), (LAS unsigned*)(lds + (bufoff) + ldsw + _i * 8192), 16, 0, 0); } while (0)
; #define PG8_LDA(dst, b, h) do { _Pragma("unroll") for (int m = 0; m < 4; ++m) _Pragma("unroll") for (int k = 0; k < 2; ++k) dst[m][k] = *(const LAS bf16x8*)(lds + PG8_SA(b, h) + aoff + m * 2048 + k * 1024); } while (0)
; #define PG8_LDB(dst, b, h) do { _Pragma("unroll") for (int n = 0; n < 2; ++n) _Pragma("unroll") for (int k = 0; k < 2; ++k) dst[n][k] = *(const LAS bf16x8*)(lds + PG8_SB(b, h) + boff + n * 2048 + k * 1024); } while (0)
; #define PG8_WAIT_V(n) asm volatile("s_waitcnt vmcnt(" #n ")" ::: "memory")
; #define PG8_WAIT_L(n) asm volatile("s_waitcnt lgkmcnt(" #n ")" ::: "memory")
; #define PG8_BAR __builtin_amdgcn_s_barrier()
; #define PG8_SCHED __builtin_amdgcn_sched_barrier(0)
; template <bool F16, class Sched, class Epi>
; __device__ __forceinline__ void gemm_phase(LAS unsigned char* lds, const Gemm g, const Sched& S, const Epi& E, int wave_s) {
;     ...
;             PG8_WAIT_V(8); PG8_WAIT_L(0); PG8_BAR; PG8_MMA(1, 0, At, B0); PG8_MMA(1, 1, At, B1); PG8_BAR; PG8_SCHED;
;             PG8_LDB(B0, 1, 0); PG8_LDB(B1, 1, 1); PG8_SCHED; PG8_LDA(At, 1, 0); PG8_STAGE(PG8_SA(0, 1), a2 + hstepA, voffA);
;             PG8_WAIT_V(8); PG8_WAIT_L(0); PG8_BAR; PG8_MMA(0, 0, At, B0); PG8_MMA(0, 1, At, B1); PG8_BAR; PG8_SCHED;
	s_setprio 1
	s_waitcnt lgkmcnt(0)
	v_mfma_f32_16x16x32_bf16 v[60:63], v[138:141], v[178:181], v[60:63]
	v_mfma_f32_16x16x32_bf16 v[56:59], v[146:149], v[178:181], v[56:59]
	v_mfma_f32_16x16x32_bf16 v[52:55], v[138:141], v[186:189], v[52:55]
	v_mfma_f32_16x16x32_bf16 v[44:47], v[146:149], v[186:189], v[44:47]
	v_mfma_f32_16x16x32_bf16 v[36:39], v[138:141], v[208:211], v[36:39]
	v_mfma_f32_16x16x32_bf16 v[28:31], v[146:149], v[208:211], v[28:31]
	v_mfma_f32_16x16x32_bf16 v[20:23], v[138:141], v[216:219], v[20:23]
	v_mfma_f32_16x16x32_bf16 v[12:15], v[146:149], v[216:219], v[12:15]
	v_mfma_f32_16x16x32_bf16 v[60:63], v[142:145], v[182:185], v[60:63]
	v_mfma_f32_16x16x32_bf16 v[56:59], v[150:153], v[182:185], v[56:59]
	v_mfma_f32_16x16x32_bf16 v[52:55], v[142:145], v[190:193], v[52:55]
	v_mfma_f32_16x16x32_bf16 v[44:47], v[150:153], v[190:193], v[44:47]
	v_mfma_f32_16x16x32_bf16 v[36:39], v[142:145], v[212:215], v[36:39]
	v_mfma_f32_16x16x32_bf16 v[28:31], v[150:153], v[212:215], v[28:31]
	v_mfma_f32_16x16x32_bf16 v[20:23], v[142:145], v[220:223], v[20:23]
	v_mfma_f32_16x16x32_bf16 v[12:15], v[150:153], v[220:223], v[12:15]
	s_setprio 0
	s_setprio 1
	v_mfma_f32_16x16x32_bf16 v[48:51], v[154:157], v[178:181], v[48:51]
	v_mfma_f32_16x16x32_bf16 v[40:43], v[166:169], v[178:181], v[40:43]
	v_mfma_f32_16x16x32_bf16 v[32:35], v[154:157], v[186:189], v[32:35]
	v_mfma_f32_16x16x32_bf16 v[24:27], v[166:169], v[186:189], v[24:27]
	v_mfma_f32_16x16x32_bf16 v[16:19], v[154:157], v[208:211], v[16:19]
	v_mfma_f32_16x16x32_bf16 v[8:11], v[166:169], v[208:211], v[8:11]
	v_mfma_f32_16x16x32_bf16 v[4:7], v[154:157], v[216:219], v[4:7]
	v_mfma_f32_16x16x32_bf16 v[0:3], v[166:169], v[216:219], v[0:3]
	v_mfma_f32_16x16x32_bf16 v[48:51], v[158:161], v[182:185], v[48:51]
	v_mfma_f32_16x16x32_bf16 v[40:43], v[170:173], v[182:185], v[40:43]
	v_mfma_f32_16x16x32_bf16 v[32:35], v[158:161], v[190:193], v[32:35]
	v_mfma_f32_16x16x32_bf16 v[24:27], v[170:173], v[190:193], v[24:27]
	v_mfma_f32_16x16x32_bf16 v[16:19], v[158:161], v[212:215], v[16:19]
	v_mfma_f32_16x16x32_bf16 v[8:11], v[170:173], v[212:215], v[8:11]
	v_mfma_f32_16x16x32_bf16 v[4:7], v[158:161], v[220:223], v[4:7]
	v_mfma_f32_16x16x32_bf16 v[0:3], v[170:173], v[220:223], v[0:3]
	s_setprio 0
	s_barrier
	s_add_i32 s60, 0, 0x18000
	s_add_i32 s61, 0, 0x1c000
	v_add_u32_e32 v150, s60, v163
	v_add_u32_e32 v170, s61, v163
	ds_read_b128 v[138:141], v150
	ds_read_b128 v[142:145], v150 offset:1024
	ds_read_b128 v[146:149], v150 offset:2048
	ds_read_b128 v[150:153], v150 offset:3072
	ds_read_b128 v[154:157], v170
	ds_read_b128 v[158:161], v170 offset:1024
	ds_read_b128 v[166:169], v170 offset:2048
	ds_read_b128 v[170:173], v170 offset:3072
	s_mov_b32 m0, s43
	ds_read_b128 v[178:181], v165 offset:32768
	ds_read_b128 v[182:185], v165 offset:33792
	ds_read_b128 v[186:189], v165 offset:34816
	ds_read_b128 v[190:193], v165 offset:35840
	ds_read_b128 v[208:211], v165 offset:36864
	ds_read_b128 v[212:215], v165 offset:37888
	ds_read_b128 v[216:219], v165 offset:38912
	ds_read_b128 v[220:223], v165 offset:39936
	global_load_lds_dwordx4 v132, s[30:31]
	s_mov_b32 m0, s44
	s_nop 0
	global_load_lds_dwordx4 v130, s[30:31]
	s_waitcnt vmcnt(8)
	s_waitcnt lgkmcnt(0)
	s_barrier
	s_setprio 1
	s_waitcnt lgkmcnt(0)
	v_mfma_f32_16x16x32_bf16 v[124:127], v[138:141], v[178:181], v[124:127]
	v_mfma_f32_16x16x32_bf16 v[120:123], v[146:149], v[178:181], v[120:123]
	v_mfma_f32_16x16x32_bf16 v[108:111], v[138:141], v[186:189], v[108:111]
	v_mfma_f32_16x16x32_bf16 v[104:107], v[146:149], v[186:189], v[104:107]
	v_mfma_f32_16x16x32_bf16 v[96:99], v[138:141], v[208:211], v[96:99]
	v_mfma_f32_16x16x32_bf16 v[92:95], v[146:149], v[208:211], v[92:95]
	v_mfma_f32_16x16x32_bf16 v[84:87], v[138:141], v[216:219], v[84:87]
	v_mfma_f32_16x16x32_bf16 v[76:79], v[146:149], v[216:219], v[76:79]
	v_mfma_f32_16x16x32_bf16 v[124:127], v[142:145], v[182:185], v[124:127]
	v_mfma_f32_16x16x32_bf16 v[120:123], v[150:153], v[182:185], v[120:123]
	v_mfma_f32_16x16x32_bf16 v[108:111], v[142:145], v[190:193], v[108:111]
	v_mfma_f32_16x16x32_bf16 v[104:107], v[150:153], v[190:193], v[104:107]
	v_mfma_f32_16x16x32_bf16 v[96:99], v[142:145], v[212:215], v[96:99]
	v_mfma_f32_16x16x32_bf16 v[92:95], v[150:153], v[212:215], v[92:95]
	v_mfma_f32_16x16x32_bf16 v[84:87], v[142:145], v[220:223], v[84:87]
	v_mfma_f32_16x16x32_bf16 v[76:79], v[150:153], v[220:223], v[76:79]
	s_setprio 0
	s_setprio 1
	v_mfma_f32_16x16x32_bf16 v[116:119], v[154:157], v[178:181], v[116:119]
	v_mfma_f32_16x16x32_bf16 v[112:115], v[166:169], v[178:181], v[112:115]
	v_mfma_f32_16x16x32_bf16 v[100:103], v[154:157], v[186:189], v[100:103]
	v_mfma_f32_16x16x32_bf16 v[88:91], v[166:169], v[186:189], v[88:91]
	v_mfma_f32_16x16x32_bf16 v[80:83], v[154:157], v[208:211], v[80:83]
	v_mfma_f32_16x16x32_bf16 v[72:75], v[166:169], v[208:211], v[72:75]
	v_mfma_f32_16x16x32_bf16 v[68:71], v[154:157], v[216:219], v[68:71]
	v_mfma_f32_16x16x32_bf16 v[64:67], v[166:169], v[216:219], v[64:67]
	v_mfma_f32_16x16x32_bf16 v[116:119], v[158:161], v[182:185], v[116:119]
	v_mfma_f32_16x16x32_bf16 v[112:115], v[170:173], v[182:185], v[112:115]
	v_mfma_f32_16x16x32_bf16 v[100:103], v[158:161], v[190:193], v[100:103]
	v_mfma_f32_16x16x32_bf16 v[88:91], v[170:173], v[190:193], v[88:91]
	v_mfma_f32_16x16x32_bf16 v[80:83], v[158:161], v[212:215], v[80:83]
	v_mfma_f32_16x16x32_bf16 v[72:75], v[170:173], v[212:215], v[72:75]
	v_mfma_f32_16x16x32_bf16 v[68:71], v[158:161], v[220:223], v[68:71]
	v_mfma_f32_16x16x32_bf16 v[64:67], v[170:173], v[220:223], v[64:67]
	s_setprio 0
	s_barrier
; #define PG8_STAGE(bufoff, gbase, voff) do { _Pragma("unroll") for (int _i = 0; _i < 2; ++_i) \
;         __builtin_amdgcn_global_load_lds((const unsigned*)((const char*)(gbase) + (voff)[_i]), (LAS unsigned*)(lds + (bufoff) + ldsw + _i * 8192), 16, 0, 0); } while (0)
; #define PG8_LDA(dst, b, h) do { _Pragma("unroll") for (int m = 0; m < 4; ++m) _Pragma("unroll") for (int k = 0; k < 2; ++k) dst[m][k] = *(const LAS bf16x8*)(lds + PG8_SA(b, h) + aoff + m * 2048 + k * 1024); } while (0)
; #define PG8_WAIT_V(n) asm volatile("s_waitcnt vmcnt(" #n ")" ::: "memory")
; #define PG8_WAIT_L(n) asm volatile("s_waitcnt lgkmcnt(" #n ")" ::: "memory")
; #define PG8_BAR __builtin_amdgcn_s_barrier()
; #define PG8_SCHED __builtin_amdgcn_sched_barrier(0)
; template <bool F16, class Sched, class Epi>
; __device__ __forceinline__ void gemm_phase(LAS unsigned char* lds, const Gemm g, const Sched& S, const Epi& E, int wave_s) {
;     ...
;             PG8_LDA(At, 1, 1); PG8_STAGE(PG8_SB(1, 0), b3, voffB); PG8_STAGE(PG8_SB(1, 1), b3 + hstepB, voffB); PG8_STAGE(PG8_SA(1, 0), a3, voffA);
;             PG8_WAIT_V(8); PG8_WAIT_L(0); PG8_BAR; PG8_MMA(1, 0, At, B0); PG8_MMA(1, 1, At, B1); PG8_BAR; PG8_SCHED;
;         }
	s_add_i32 s30, s60, s39
	v_lshl_add_u64 v[174:175], v[174:175], 0, s[54:55]
	s_mov_b32 m0, s30
	ds_read_b128 v[178:181], v165 offset:49152
	ds_read_b128 v[182:185], v165 offset:50176
	ds_read_b128 v[186:189], v165 offset:51200
	ds_read_b128 v[190:193], v165 offset:52224
	ds_read_b128 v[208:211], v165 offset:53248
	ds_read_b128 v[212:215], v165 offset:54272
	ds_read_b128 v[216:219], v165 offset:55296
	ds_read_b128 v[220:223], v165 offset:56320
	global_load_lds_dwordx4 v[174:175], off
	s_add_i32 m0, s30, 0x2000
	s_add_u32 s28, s28, 0x20080
	v_lshl_add_u64 v[174:175], v[194:195], 0, s[54:55]
	s_addc_u32 s29, s29, 0
	s_add_i32 s30, s61, s39
	global_load_lds_dwordx4 v[174:175], off
	v_lshl_add_u64 v[174:175], s[28:29], 0, v[176:177]
	s_mov_b32 m0, s30
	s_nop 0
	global_load_lds_dwordx4 v[174:175], off
	v_lshl_add_u64 v[174:175], s[28:29], 0, v[128:129]
	s_add_i32 m0, s30, 0x2000
	s_nop 0
	global_load_lds_dwordx4 v[174:175], off
	v_lshl_add_u64 v[174:175], v[198:199], 0, s[54:55]
	s_mov_b32 m0, s19
	s_nop 0
	global_load_lds_dwordx4 v[174:175], off
	v_lshl_add_u64 v[174:175], v[200:201], 0, s[54:55]
	s_mov_b32 m0, s45
	s_nop 0
	global_load_lds_dwordx4 v[174:175], off
	s_waitcnt vmcnt(8)
	s_waitcnt lgkmcnt(0)
	s_barrier
	s_setprio 1
	s_waitcnt lgkmcnt(0)
	v_mfma_f32_16x16x32_bf16 v[60:63], v[138:141], v[178:181], v[60:63]
	v_mfma_f32_16x16x32_bf16 v[56:59], v[146:149], v[178:181], v[56:59]
	v_mfma_f32_16x16x32_bf16 v[52:55], v[138:141], v[186:189], v[52:55]
	v_mfma_f32_16x16x32_bf16 v[44:47], v[146:149], v[186:189], v[44:47]
	v_mfma_f32_16x16x32_bf16 v[36:39], v[138:141], v[208:211], v[36:39]
	v_mfma_f32_16x16x32_bf16 v[28:31], v[146:149], v[208:211], v[28:31]
	v_mfma_f32_16x16x32_bf16 v[20:23], v[138:141], v[216:219], v[20:23]
	v_mfma_f32_16x16x32_bf16 v[12:15], v[146:149], v[216:219], v[12:15]
	v_mfma_f32_16x16x32_bf16 v[60:63], v[142:145], v[182:185], v[60:63]
	v_mfma_f32_16x16x32_bf16 v[56:59], v[150:153], v[182:185], v[56:59]
	v_mfma_f32_16x16x32_bf16 v[52:55], v[142:145], v[190:193], v[52:55]
	v_mfma_f32_16x16x32_bf16 v[44:47], v[150:153], v[190:193], v[44:47]
	v_mfma_f32_16x16x32_bf16 v[36:39], v[142:145], v[212:215], v[36:39]
	v_mfma_f32_16x16x32_bf16 v[28:31], v[150:153], v[212:215], v[28:31]
	v_mfma_f32_16x16x32_bf16 v[20:23], v[142:145], v[220:223], v[20:23]
	v_mfma_f32_16x16x32_bf16 v[12:15], v[150:153], v[220:223], v[12:15]
	s_setprio 0
	s_setprio 1
	v_mfma_f32_16x16x32_bf16 v[48:51], v[154:157], v[178:181], v[48:51]
	v_mfma_f32_16x16x32_bf16 v[40:43], v[166:169], v[178:181], v[40:43]
	v_mfma_f32_16x16x32_bf16 v[32:35], v[154:157], v[186:189], v[32:35]
	v_mfma_f32_16x16x32_bf16 v[24:27], v[166:169], v[186:189], v[24:27]
	v_mfma_f32_16x16x32_bf16 v[16:19], v[154:157], v[208:211], v[16:19]
	v_mfma_f32_16x16x32_bf16 v[8:11], v[166:169], v[208:211], v[8:11]
	v_mfma_f32_16x16x32_bf16 v[4:7], v[154:157], v[216:219], v[4:7]
	v_mfma_f32_16x16x32_bf16 v[0:3], v[166:169], v[216:219], v[0:3]
	v_mfma_f32_16x16x32_bf16 v[48:51], v[158:161], v[182:185], v[48:51]
	v_mfma_f32_16x16x32_bf16 v[40:43], v[170:173], v[182:185], v[40:43]
	v_mfma_f32_16x16x32_bf16 v[32:35], v[158:161], v[190:193], v[32:35]
	v_mfma_f32_16x16x32_bf16 v[24:27], v[170:173], v[190:193], v[24:27]
	v_mfma_f32_16x16x32_bf16 v[16:19], v[158:161], v[212:215], v[16:19]
	v_mfma_f32_16x16x32_bf16 v[8:11], v[170:173], v[212:215], v[8:11]
	v_mfma_f32_16x16x32_bf16 v[4:7], v[158:161], v[220:223], v[4:7]
	v_mfma_f32_16x16x32_bf16 v[0:3], v[170:173], v[220:223], v[0:3]
	s_setprio 0
	s_barrier
	s_add_i32 s59, s59, 2
	s_add_u32 s26, s26, 0x100
	s_addc_u32 s27, s27, 0
	s_add_u32 s53, s53, 0x100
	s_addc_u32 s58, s58, 0
	s_cmp_gt_u32 s59, 5
	s_cbranch_scc0 .LBB0_234
	s_and_b64 vcc, exec, s[10:11]
	s_cbranch_vccz .LBB0_237
	s_barrier

; #define PG8_STAGE(bufoff, gbase, voff) do { _Pragma("unroll") for (int _i = 0; _i < 2; ++_i) \
;         __builtin_amdgcn_global_load_lds((const unsigned*)((const char*)(gbase) + (voff)[_i]), (LAS unsigned*)(lds + (bufoff) + ldsw + _i * 8192), 16, 0, 0); } while (0)
; #define PG8_LDA(dst, b, h) do { _Pragma("unroll") for (int m = 0; m < 4; ++m) _Pragma("unroll") for (int k = 0; k < 2; ++k) dst[m][k] = *(const LAS bf16x8*)(lds + PG8_SA(b, h) + aoff + m * 2048 + k * 1024); } while (0)
; #define PG8_LDB(dst, b, h) do { _Pragma("unroll") for (int n = 0; n < 2; ++n) _Pragma("unroll") for (int k = 0; k < 2; ++k) dst[n][k] = *(const LAS bf16x8*)(lds + PG8_SB(b, h) + boff + n * 2048 + k * 1024); } while (0)
; #define PG8_WAIT_V(n) asm volatile("s_waitcnt vmcnt(" #n ")" ::: "memory")
; #define PG8_WAIT_L(n) asm volatile("s_waitcnt lgkmcnt(" #n ")" ::: "memory")
; #define PG8_BAR __builtin_amdgcn_s_barrier()
; #define PG8_SCHED __builtin_amdgcn_sched_barrier(0)
; template <bool F16, class Sched, class Epi>
; __device__ __forceinline__ void gemm_phase(LAS unsigned char* lds, const Gemm g, const Sched& S, const Epi& E, int wave_s) {
;     ...
;             const char* a1 = cA + (size_t)(t + 1) * kstep;
;             const char* a2 = last ? nA : cA + (size_t)(t + 2) * kstep; const char* b2 = last ? nB : cB + (size_t)(t + 2) * kstep;
;             const char* a3 = a2 + kstep; const char* b3 = b2 + kstep;
;             PG8_LDB(B0, 0, 0); PG8_LDB(B1, 0, 1); PG8_SCHED; PG8_LDA(At, 0, 0); PG8_STAGE(PG8_SA(1, 1), a1 + hstepA, voffA);
;             PG8_WAIT_V(8); PG8_WAIT_L(0); PG8_BAR; PG8_MMA(0, 0, At, B0); PG8_MMA(0, 1, At, B1); PG8_BAR; PG8_SCHED;
;             PG8_LDA(At, 0, 1); PG8_STAGE(PG8_SB(0, 0), b2, voffB); PG8_STAGE(PG8_SB(0, 1), b2 + hstepB, voffB); PG8_STAGE(PG8_SA(0, 0), a2, voffA);
;             PG8_WAIT_V(8); PG8_WAIT_L(0); PG8_BAR; PG8_MMA(1, 0, At, B0); PG8_MMA(1, 1, At, B1); PG8_BAR; PG8_SCHED;
.LBB0_304:
	s_add_i32 s71, 0, 0x10000
	s_add_i32 s74, 0, 0x14000
	v_add_u32_e32 v150, s71, v162
	v_add_u32_e32 v158, s74, v162
	ds_read_b128 v[138:141], v150
	ds_read_b128 v[142:145], v150 offset:1024
	ds_read_b128 v[146:149], v150 offset:2048
	ds_read_b128 v[150:153], v150 offset:3072
	ds_read_b128 v[154:157], v158
	ds_read_b128 v[166:169], v158 offset:1024
	ds_read_b128 v[170:173], v158 offset:2048
	ds_read_b128 v[178:181], v158 offset:3072
	s_add_i32 m0, s49, 0xc000
	ds_read_b128 v[182:185], v164
	ds_read_b128 v[186:189], v164 offset:1024
	ds_read_b128 v[190:193], v164 offset:2048
	ds_read_b128 v[208:211], v164 offset:3072
	ds_read_b128 v[212:215], v164 offset:4096
	ds_read_b128 v[216:219], v164 offset:5120
	ds_read_b128 v[220:223], v164 offset:6144
	ds_read_b128 v[224:227], v164 offset:7168
	global_load_lds_dwordx4 v134, s[2:3]
	s_add_i32 m0, s49, 0xe000
	s_nop 0
	global_load_lds_dwordx4 v136, s[2:3]
	s_waitcnt vmcnt(8)
	s_waitcnt lgkmcnt(0)
	s_barrier
	s_setprio 1
	s_waitcnt lgkmcnt(0)
	v_mfma_f32_16x16x32_bf16 v[124:127], v[138:141], v[182:185], v[124:127]
	v_mfma_f32_16x16x32_bf16 v[120:123], v[146:149], v[182:185], v[120:123]
	v_mfma_f32_16x16x32_bf16 v[108:111], v[138:141], v[190:193], v[108:111]
	v_mfma_f32_16x16x32_bf16 v[104:107], v[146:149], v[190:193], v[104:107]
	v_mfma_f32_16x16x32_bf16 v[92:95], v[138:141], v[212:215], v[92:95]
	v_mfma_f32_16x16x32_bf16 v[88:91], v[146:149], v[212:215], v[88:91]
	v_mfma_f32_16x16x32_bf16 v[76:79], v[138:141], v[220:223], v[76:79]
	v_mfma_f32_16x16x32_bf16 v[72:75], v[146:149], v[220:223], v[72:75]
	v_mfma_f32_16x16x32_bf16 v[124:127], v[142:145], v[186:189], v[124:127]
	v_mfma_f32_16x16x32_bf16 v[120:123], v[150:153], v[186:189], v[120:123]
	v_mfma_f32_16x16x32_bf16 v[108:111], v[142:145], v[208:211], v[108:111]
	v_mfma_f32_16x16x32_bf16 v[104:107], v[150:153], v[208:211], v[104:107]
	v_mfma_f32_16x16x32_bf16 v[92:95], v[142:145], v[216:219], v[92:95]
	v_mfma_f32_16x16x32_bf16 v[88:91], v[150:153], v[216:219], v[88:91]
	v_mfma_f32_16x16x32_bf16 v[76:79], v[142:145], v[224:227], v[76:79]
	v_mfma_f32_16x16x32_bf16 v[72:75], v[150:153], v[224:227], v[72:75]
	s_setprio 0
	s_setprio 1
	v_mfma_f32_16x16x32_bf16 v[116:119], v[154:157], v[182:185], v[116:119]
	v_mfma_f32_16x16x32_bf16 v[112:115], v[170:173], v[182:185], v[112:115]
	v_mfma_f32_16x16x32_bf16 v[100:103], v[154:157], v[190:193], v[100:103]
	v_mfma_f32_16x16x32_bf16 v[96:99], v[170:173], v[190:193], v[96:99]
	v_mfma_f32_16x16x32_bf16 v[84:87], v[154:157], v[212:215], v[84:87]
	v_mfma_f32_16x16x32_bf16 v[80:83], v[170:173], v[212:215], v[80:83]
	v_mfma_f32_16x16x32_bf16 v[68:71], v[154:157], v[220:223], v[68:71]
	v_mfma_f32_16x16x32_bf16 v[64:67], v[170:173], v[220:223], v[64:67]
	v_mfma_f32_16x16x32_bf16 v[116:119], v[166:169], v[186:189], v[116:119]
	v_mfma_f32_16x16x32_bf16 v[112:115], v[178:181], v[186:189], v[112:115]
	v_mfma_f32_16x16x32_bf16 v[100:103], v[166:169], v[208:211], v[100:103]
	v_mfma_f32_16x16x32_bf16 v[96:99], v[178:181], v[208:211], v[96:99]
	v_mfma_f32_16x16x32_bf16 v[84:87], v[166:169], v[216:219], v[84:87]
	v_mfma_f32_16x16x32_bf16 v[80:83], v[178:181], v[216:219], v[80:83]
	v_mfma_f32_16x16x32_bf16 v[68:71], v[166:169], v[224:227], v[68:71]
	v_mfma_f32_16x16x32_bf16 v[64:67], v[178:181], v[224:227], v[64:67]
	s_setprio 0
	s_barrier
	s_add_u32 s4, s2, 0xfff80080
	s_addc_u32 s5, s3, -1
	s_cmp_eq_u32 s70, 28
	s_cselect_b32 s39, s62, s5
	s_cselect_b32 s38, s63, s4
	s_cselect_b32 s5, s64, s69
	s_cselect_b32 s4, s65, s68
	s_add_i32 s71, s71, s46
	v_lshl_add_u64 v[158:159], s[4:5], 0, v[176:177]
	s_mov_b32 m0, s71
	ds_read_b128 v[182:185], v164 offset:16384
	ds_read_b128 v[186:189], v164 offset:17408
	ds_read_b128 v[190:193], v164 offset:18432
	ds_read_b128 v[208:211], v164 offset:19456
	ds_read_b128 v[212:215], v164 offset:20480
	ds_read_b128 v[216:219], v164 offset:21504
	ds_read_b128 v[220:223], v164 offset:22528
	ds_read_b128 v[224:227], v164 offset:23552
	global_load_lds_dwordx4 v[158:159], off
	s_add_i32 m0, s71, 0x2000
	s_add_u32 s72, s4, 0x80000
	v_lshl_add_u64 v[174:175], s[4:5], 0, v[128:129]
	s_addc_u32 s73, s5, 0
	s_add_i32 s71, s74, s46
	global_load_lds_dwordx4 v[174:175], off
	v_lshl_add_u64 v[194:195], s[72:73], 0, v[176:177]
	s_mov_b32 m0, s71
	v_lshl_add_u64 v[198:199], s[38:39], 0, v[130:131]
	global_load_lds_dwordx4 v[194:195], off
	v_lshl_add_u64 v[194:195], s[72:73], 0, v[128:129]
	s_add_i32 m0, s71, 0x2000
	s_nop 0
	global_load_lds_dwordx4 v[194:195], off
	v_lshl_add_u64 v[194:195], s[38:39], 0, v[132:133]
	s_mov_b32 m0, s49
	s_nop 0
	global_load_lds_dwordx4 v[194:195], off
	s_mov_b32 m0, s52
	s_nop 0
	global_load_lds_dwordx4 v[198:199], off
	s_add_u32 s38, s38, 0x80000
	s_addc_u32 s39, s39, 0
	s_waitcnt vmcnt(8)
	s_waitcnt lgkmcnt(0)
	s_barrier
; #define PG8_STAGE(bufoff, gbase, voff) do { _Pragma("unroll") for (int _i = 0; _i < 2; ++_i) \
;         __builtin_amdgcn_global_load_lds((const unsigned*)((const char*)(gbase) + (voff)[_i]), (LAS unsigned*)(lds + (bufoff) + ldsw + _i * 8192), 16, 0, 0); } while (0)
; #define PG8_LDA(dst, b, h) do { _Pragma("unroll") for (int m = 0; m < 4; ++m) _Pragma("unroll") for (int k = 0; k < 2; ++k) dst[m][k] = *(const LAS bf16x8*)(lds + PG8_SA(b, h) + aoff + m * 2048 + k * 1024); } while (0)
; #define PG8_LDB(dst, b, h) do { _Pragma("unroll") for (int n = 0; n < 2; ++n) _Pragma("unroll") for (int k = 0; k < 2; ++k) dst[n][k] = *(const LAS bf16x8*)(lds + PG8_SB(b, h) + boff + n * 2048 + k * 1024); } while (0)
; #define PG8_WAIT_V(n) asm volatile("s_waitcnt vmcnt(" #n ")" ::: "memory")
; #define PG8_WAIT_L(n) asm volatile("s_waitcnt lgkmcnt(" #n ")" ::: "memory")
; #define PG8_BAR __builtin_amdgcn_s_barrier()
; #define PG8_SCHED __builtin_amdgcn_sched_barrier(0)
; template <bool F16, class Sched, class Epi>
; __device__ __forceinline__ void gemm_phase(LAS unsigned char* lds, const Gemm g, const Sched& S, const Epi& E, int wave_s) {
;     ...
;             PG8_WAIT_V(8); PG8_WAIT_L(0); PG8_BAR; PG8_MMA(1, 0, At, B0); PG8_MMA(1, 1, At, B1); PG8_BAR; PG8_SCHED;
;             PG8_LDB(B0, 1, 0); PG8_LDB(B1, 1, 1); PG8_SCHED; PG8_LDA(At, 1, 0); PG8_STAGE(PG8_SA(0, 1), a2 + hstepA, voffA);
;             PG8_WAIT_V(8); PG8_WAIT_L(0); PG8_BAR; PG8_MMA(0, 0, At, B0); PG8_MMA(0, 1, At, B1); PG8_BAR; PG8_SCHED;
	s_setprio 1
	s_waitcnt lgkmcnt(0)
	v_mfma_f32_16x16x32_bf16 v[60:63], v[138:141], v[182:185], v[60:63]
	v_mfma_f32_16x16x32_bf16 v[56:59], v[146:149], v[182:185], v[56:59]
	v_mfma_f32_16x16x32_bf16 v[44:47], v[138:141], v[190:193], v[44:47]
	v_mfma_f32_16x16x32_bf16 v[40:43], v[146:149], v[190:193], v[40:43]
	v_mfma_f32_16x16x32_bf16 v[28:31], v[138:141], v[212:215], v[28:31]
	v_mfma_f32_16x16x32_bf16 v[24:27], v[146:149], v[212:215], v[24:27]
	v_mfma_f32_16x16x32_bf16 v[12:15], v[138:141], v[220:223], v[12:15]
	v_mfma_f32_16x16x32_bf16 v[8:11], v[146:149], v[220:223], v[8:11]
	v_mfma_f32_16x16x32_bf16 v[60:63], v[142:145], v[186:189], v[60:63]
	v_mfma_f32_16x16x32_bf16 v[56:59], v[150:153], v[186:189], v[56:59]
	v_mfma_f32_16x16x32_bf16 v[44:47], v[142:145], v[208:211], v[44:47]
	v_mfma_f32_16x16x32_bf16 v[40:43], v[150:153], v[208:211], v[40:43]
	v_mfma_f32_16x16x32_bf16 v[28:31], v[142:145], v[216:219], v[28:31]
	v_mfma_f32_16x16x32_bf16 v[24:27], v[150:153], v[216:219], v[24:27]
	v_mfma_f32_16x16x32_bf16 v[12:15], v[142:145], v[224:227], v[12:15]
	v_mfma_f32_16x16x32_bf16 v[8:11], v[150:153], v[224:227], v[8:11]
	s_setprio 0
	s_setprio 1
	v_mfma_f32_16x16x32_bf16 v[52:55], v[154:157], v[182:185], v[52:55]
	v_mfma_f32_16x16x32_bf16 v[48:51], v[170:173], v[182:185], v[48:51]
	v_mfma_f32_16x16x32_bf16 v[36:39], v[154:157], v[190:193], v[36:39]
	v_mfma_f32_16x16x32_bf16 v[32:35], v[170:173], v[190:193], v[32:35]
	v_mfma_f32_16x16x32_bf16 v[20:23], v[154:157], v[212:215], v[20:23]
	v_mfma_f32_16x16x32_bf16 v[16:19], v[170:173], v[212:215], v[16:19]
	v_mfma_f32_16x16x32_bf16 v[4:7], v[154:157], v[220:223], v[4:7]
	v_mfma_f32_16x16x32_bf16 v[0:3], v[170:173], v[220:223], v[0:3]
	v_mfma_f32_16x16x32_bf16 v[52:55], v[166:169], v[186:189], v[52:55]
	v_mfma_f32_16x16x32_bf16 v[48:51], v[178:181], v[186:189], v[48:51]
	v_mfma_f32_16x16x32_bf16 v[36:39], v[166:169], v[208:211], v[36:39]
	v_mfma_f32_16x16x32_bf16 v[32:35], v[178:181], v[208:211], v[32:35]
	v_mfma_f32_16x16x32_bf16 v[20:23], v[166:169], v[216:219], v[20:23]
	v_mfma_f32_16x16x32_bf16 v[16:19], v[178:181], v[216:219], v[16:19]
	v_mfma_f32_16x16x32_bf16 v[4:7], v[166:169], v[224:227], v[4:7]
	v_mfma_f32_16x16x32_bf16 v[0:3], v[178:181], v[224:227], v[0:3]
	s_setprio 0
	s_barrier
	s_add_i32 s71, 0, 0x18000
	s_add_i32 s72, 0, 0x1c000
	v_add_u32_e32 v150, s71, v162
	v_add_u32_e32 v160, s72, v162
	ds_read_b128 v[138:141], v150
	ds_read_b128 v[142:145], v150 offset:1024
	ds_read_b128 v[146:149], v150 offset:2048
	ds_read_b128 v[150:153], v150 offset:3072
	ds_read_b128 v[154:157], v160
	ds_read_b128 v[166:169], v160 offset:1024
	ds_read_b128 v[170:173], v160 offset:2048
	ds_read_b128 v[178:181], v160 offset:3072
	s_mov_b32 m0, s53
	ds_read_b128 v[182:185], v164 offset:32768
	ds_read_b128 v[186:189], v164 offset:33792
	ds_read_b128 v[190:193], v164 offset:34816
	ds_read_b128 v[208:211], v164 offset:35840
	ds_read_b128 v[212:215], v164 offset:36864
	ds_read_b128 v[216:219], v164 offset:37888
	ds_read_b128 v[220:223], v164 offset:38912
	ds_read_b128 v[224:227], v164 offset:39936
	global_load_lds_dwordx4 v132, s[38:39]
	s_mov_b32 m0, s58
	s_nop 0
	global_load_lds_dwordx4 v130, s[38:39]
	s_waitcnt vmcnt(8)
	s_waitcnt lgkmcnt(0)
	s_barrier
	s_setprio 1
	s_waitcnt lgkmcnt(0)
	v_mfma_f32_16x16x32_bf16 v[124:127], v[138:141], v[182:185], v[124:127]
	v_mfma_f32_16x16x32_bf16 v[120:123], v[146:149], v[182:185], v[120:123]
	v_mfma_f32_16x16x32_bf16 v[108:111], v[138:141], v[190:193], v[108:111]
	v_mfma_f32_16x16x32_bf16 v[104:107], v[146:149], v[190:193], v[104:107]
	v_mfma_f32_16x16x32_bf16 v[92:95], v[138:141], v[212:215], v[92:95]
	v_mfma_f32_16x16x32_bf16 v[88:91], v[146:149], v[212:215], v[88:91]
	v_mfma_f32_16x16x32_bf16 v[76:79], v[138:141], v[220:223], v[76:79]
	v_mfma_f32_16x16x32_bf16 v[72:75], v[146:149], v[220:223], v[72:75]
	v_mfma_f32_16x16x32_bf16 v[124:127], v[142:145], v[186:189], v[124:127]
	v_mfma_f32_16x16x32_bf16 v[120:123], v[150:153], v[186:189], v[120:123]
	v_mfma_f32_16x16x32_bf16 v[108:111], v[142:145], v[208:211], v[108:111]
	v_mfma_f32_16x16x32_bf16 v[104:107], v[150:153], v[208:211], v[104:107]
	v_mfma_f32_16x16x32_bf16 v[92:95], v[142:145], v[216:219], v[92:95]
	v_mfma_f32_16x16x32_bf16 v[88:91], v[150:153], v[216:219], v[88:91]
	v_mfma_f32_16x16x32_bf16 v[76:79], v[142:145], v[224:227], v[76:79]
	v_mfma_f32_16x16x32_bf16 v[72:75], v[150:153], v[224:227], v[72:75]
	s_setprio 0
	s_setprio 1
	v_mfma_f32_16x16x32_bf16 v[116:119], v[154:157], v[182:185], v[116:119]
	v_mfma_f32_16x16x32_bf16 v[112:115], v[170:173], v[182:185], v[112:115]
	v_mfma_f32_16x16x32_bf16 v[100:103], v[154:157], v[190:193], v[100:103]
	v_mfma_f32_16x16x32_bf16 v[96:99], v[170:173], v[190:193], v[96:99]
	v_mfma_f32_16x16x32_bf16 v[84:87], v[154:157], v[212:215], v[84:87]
	v_mfma_f32_16x16x32_bf16 v[80:83], v[170:173], v[212:215], v[80:83]
	v_mfma_f32_16x16x32_bf16 v[68:71], v[154:157], v[220:223], v[68:71]
	v_mfma_f32_16x16x32_bf16 v[64:67], v[170:173], v[220:223], v[64:67]
	v_mfma_f32_16x16x32_bf16 v[116:119], v[166:169], v[186:189], v[116:119]
	v_mfma_f32_16x16x32_bf16 v[112:115], v[178:181], v[186:189], v[112:115]
	v_mfma_f32_16x16x32_bf16 v[100:103], v[166:169], v[208:211], v[100:103]
	v_mfma_f32_16x16x32_bf16 v[96:99], v[178:181], v[208:211], v[96:99]
	v_mfma_f32_16x16x32_bf16 v[84:87], v[166:169], v[216:219], v[84:87]
	v_mfma_f32_16x16x32_bf16 v[80:83], v[178:181], v[216:219], v[80:83]
	v_mfma_f32_16x16x32_bf16 v[68:71], v[166:169], v[224:227], v[68:71]
	v_mfma_f32_16x16x32_bf16 v[64:67], v[178:181], v[224:227], v[64:67]
	s_setprio 0
	s_barrier
; #define PG8_STAGE(bufoff, gbase, voff) do { _Pragma("unroll") for (int _i = 0; _i < 2; ++_i) \
;         __builtin_amdgcn_global_load_lds((const unsigned*)((const char*)(gbase) + (voff)[_i]), (LAS unsigned*)(lds + (bufoff) + ldsw + _i * 8192), 16, 0, 0); } while (0)
; #define PG8_LDA(dst, b, h) do { _Pragma("unroll") for (int m = 0; m < 4; ++m) _Pragma("unroll") for (int k = 0; k < 2; ++k) dst[m][k] = *(const LAS bf16x8*)(lds + PG8_SA(b, h) + aoff + m * 2048 + k * 1024); } while (0)
; #define PG8_WAIT_V(n) asm volatile("s_waitcnt vmcnt(" #n ")" ::: "memory")
; #define PG8_WAIT_L(n) asm volatile("s_waitcnt lgkmcnt(" #n ")" ::: "memory")
; #define PG8_BAR __builtin_amdgcn_s_barrier()
; #define PG8_SCHED __builtin_amdgcn_sched_barrier(0)
; template <bool F16, class Sched, class Epi>
; __device__ __forceinline__ void gemm_phase(LAS unsigned char* lds, const Gemm g, const Sched& S, const Epi& E, int wave_s) {
;     ...
;             PG8_LDA(At, 1, 1); PG8_STAGE(PG8_SB(1, 0), b3, voffB); PG8_STAGE(PG8_SB(1, 1), b3 + hstepB, voffB); PG8_STAGE(PG8_SA(1, 0), a3, voffA);
;             PG8_WAIT_V(8); PG8_WAIT_L(0); PG8_BAR; PG8_MMA(1, 0, At, B0); PG8_MMA(1, 1, At, B1); PG8_BAR; PG8_SCHED;
;         }
	s_add_i32 s38, s71, s46
	v_lshl_add_u64 v[158:159], v[158:159], 0, s[54:55]
	s_mov_b32 m0, s38
	ds_read_b128 v[182:185], v164 offset:49152
	ds_read_b128 v[186:189], v164 offset:50176
	ds_read_b128 v[190:193], v164 offset:51200
	ds_read_b128 v[208:211], v164 offset:52224
	ds_read_b128 v[212:215], v164 offset:53248
	ds_read_b128 v[216:219], v164 offset:54272
	ds_read_b128 v[220:223], v164 offset:55296
	ds_read_b128 v[224:227], v164 offset:56320
	global_load_lds_dwordx4 v[158:159], off
	s_add_i32 m0, s38, 0x2000
	s_add_u32 s4, s4, 0x80080
	v_lshl_add_u64 v[158:159], v[174:175], 0, s[54:55]
	s_addc_u32 s5, s5, 0
	s_add_i32 s38, s72, s46
	global_load_lds_dwordx4 v[158:159], off
	v_lshl_add_u64 v[158:159], s[4:5], 0, v[176:177]
	s_mov_b32 m0, s38
	s_nop 0
	global_load_lds_dwordx4 v[158:159], off
	v_lshl_add_u64 v[158:159], s[4:5], 0, v[128:129]
	s_add_i32 m0, s38, 0x2000
	s_nop 0
	global_load_lds_dwordx4 v[158:159], off
	v_lshl_add_u64 v[158:159], v[194:195], 0, s[54:55]
	s_mov_b32 m0, s59
	s_nop 0
	global_load_lds_dwordx4 v[158:159], off
	v_lshl_add_u64 v[158:159], v[198:199], 0, s[54:55]
	s_mov_b32 m0, s60
	s_nop 0
	global_load_lds_dwordx4 v[158:159], off
	s_waitcnt vmcnt(8)
	s_waitcnt lgkmcnt(0)
	s_barrier
	s_setprio 1
	s_waitcnt lgkmcnt(0)
	v_mfma_f32_16x16x32_bf16 v[60:63], v[138:141], v[182:185], v[60:63]
	v_mfma_f32_16x16x32_bf16 v[56:59], v[146:149], v[182:185], v[56:59]
	v_mfma_f32_16x16x32_bf16 v[44:47], v[138:141], v[190:193], v[44:47]
	v_mfma_f32_16x16x32_bf16 v[40:43], v[146:149], v[190:193], v[40:43]
	v_mfma_f32_16x16x32_bf16 v[28:31], v[138:141], v[212:215], v[28:31]
	v_mfma_f32_16x16x32_bf16 v[24:27], v[146:149], v[212:215], v[24:27]
	v_mfma_f32_16x16x32_bf16 v[12:15], v[138:141], v[220:223], v[12:15]
	v_mfma_f32_16x16x32_bf16 v[8:11], v[146:149], v[220:223], v[8:11]
	v_mfma_f32_16x16x32_bf16 v[60:63], v[142:145], v[186:189], v[60:63]
	v_mfma_f32_16x16x32_bf16 v[56:59], v[150:153], v[186:189], v[56:59]
	v_mfma_f32_16x16x32_bf16 v[44:47], v[142:145], v[208:211], v[44:47]
	v_mfma_f32_16x16x32_bf16 v[40:43], v[150:153], v[208:211], v[40:43]
	v_mfma_f32_16x16x32_bf16 v[28:31], v[142:145], v[216:219], v[28:31]
	v_mfma_f32_16x16x32_bf16 v[24:27], v[150:153], v[216:219], v[24:27]
	v_mfma_f32_16x16x32_bf16 v[12:15], v[142:145], v[224:227], v[12:15]
	v_mfma_f32_16x16x32_bf16 v[8:11], v[150:153], v[224:227], v[8:11]
	s_setprio 0
	s_setprio 1
	v_mfma_f32_16x16x32_bf16 v[52:55], v[154:157], v[182:185], v[52:55]
	v_mfma_f32_16x16x32_bf16 v[48:51], v[170:173], v[182:185], v[48:51]
	v_mfma_f32_16x16x32_bf16 v[36:39], v[154:157], v[190:193], v[36:39]
	v_mfma_f32_16x16x32_bf16 v[32:35], v[170:173], v[190:193], v[32:35]
	v_mfma_f32_16x16x32_bf16 v[20:23], v[154:157], v[212:215], v[20:23]
	v_mfma_f32_16x16x32_bf16 v[16:19], v[170:173], v[212:215], v[16:19]
	v_mfma_f32_16x16x32_bf16 v[4:7], v[154:157], v[220:223], v[4:7]
	v_mfma_f32_16x16x32_bf16 v[0:3], v[170:173], v[220:223], v[0:3]
	v_mfma_f32_16x16x32_bf16 v[52:55], v[166:169], v[186:189], v[52:55]
	v_mfma_f32_16x16x32_bf16 v[48:51], v[178:181], v[186:189], v[48:51]
	v_mfma_f32_16x16x32_bf16 v[36:39], v[166:169], v[208:211], v[36:39]
	v_mfma_f32_16x16x32_bf16 v[32:35], v[178:181], v[208:211], v[32:35]
	v_mfma_f32_16x16x32_bf16 v[20:23], v[166:169], v[216:219], v[20:23]
	v_mfma_f32_16x16x32_bf16 v[16:19], v[178:181], v[216:219], v[16:19]
	v_mfma_f32_16x16x32_bf16 v[4:7], v[166:169], v[224:227], v[4:7]
	v_mfma_f32_16x16x32_bf16 v[0:3], v[178:181], v[224:227], v[0:3]
	s_setprio 0
	s_barrier
	s_add_i32 s70, s70, 2
	s_add_u32 s2, s2, 0x100
	s_addc_u32 s3, s3, 0
	s_add_u32 s68, s68, 0x100
	s_addc_u32 s69, s69, 0
	s_cmp_gt_u32 s70, 29
	s_cbranch_scc0 .LBB0_304
	s_and_b64 vcc, exec, s[28:29]
	s_cbranch_vccz .LBB0_307
	s_barrier

; #define PG8_STAGE(bufoff, gbase, voff) do { _Pragma("unroll") for (int _i = 0; _i < 2; ++_i) \
;         __builtin_amdgcn_global_load_lds((const unsigned*)((const char*)(gbase) + (voff)[_i]), (LAS unsigned*)(lds + (bufoff) + ldsw + _i * 8192), 16, 0, 0); } while (0)
; #define PG8_LDA(dst, b, h) do { _Pragma("unroll") for (int m = 0; m < 4; ++m) _Pragma("unroll") for (int k = 0; k < 2; ++k) dst[m][k] = *(const LAS bf16x8*)(lds + PG8_SA(b, h) + aoff + m * 2048 + k * 1024); } while (0)
; #define PG8_LDB(dst, b, h) do { _Pragma("unroll") for (int n = 0; n < 2; ++n) _Pragma("unroll") for (int k = 0; k < 2; ++k) dst[n][k] = *(const LAS bf16x8*)(lds + PG8_SB(b, h) + boff + n * 2048 + k * 1024); } while (0)
; #define PG8_WAIT_V(n) asm volatile("s_waitcnt vmcnt(" #n ")" ::: "memory")
; #define PG8_WAIT_L(n) asm volatile("s_waitcnt lgkmcnt(" #n ")" ::: "memory")
; #define PG8_BAR __builtin_amdgcn_s_barrier()
; #define PG8_SCHED __builtin_amdgcn_sched_barrier(0)
; template <bool F16, class Sched, class Epi>
; __device__ __forceinline__ void gemm_phase(LAS unsigned char* lds, const Gemm g, const Sched& S, const Epi& E, int wave_s) {
;     ...
;             const char* a1 = cA + (size_t)(t + 1) * kstep;
;             const char* a2 = last ? nA : cA + (size_t)(t + 2) * kstep; const char* b2 = last ? nB : cB + (size_t)(t + 2) * kstep;
;             const char* a3 = a2 + kstep; const char* b3 = b2 + kstep;
;             PG8_LDB(B0, 0, 0); PG8_LDB(B1, 0, 1); PG8_SCHED; PG8_LDA(At, 0, 0); PG8_STAGE(PG8_SA(1, 1), a1 + hstepA, voffA);
;             PG8_WAIT_V(8); PG8_WAIT_L(0); PG8_BAR; PG8_MMA(0, 0, At, B0); PG8_MMA(0, 1, At, B1); PG8_BAR; PG8_SCHED;
;             PG8_LDA(At, 0, 1); PG8_STAGE(PG8_SB(0, 0), b2, voffB); PG8_STAGE(PG8_SB(0, 1), b2 + hstepB, voffB); PG8_STAGE(PG8_SA(0, 0), a2, voffA);
;             PG8_WAIT_V(8); PG8_WAIT_L(0); PG8_BAR; PG8_MMA(1, 0, At, B0); PG8_MMA(1, 1, At, B1); PG8_BAR; PG8_SCHED;
.LBB0_358:
	s_add_i32 s65, 0, 0x10000
	s_add_i32 s70, 0, 0x14000
	v_add_u32_e32 v150, s65, v163
	v_add_u32_e32 v158, s70, v163
	ds_read_b128 v[138:141], v150
	ds_read_b128 v[142:145], v150 offset:1024
	ds_read_b128 v[146:149], v150 offset:2048
	ds_read_b128 v[150:153], v150 offset:3072
	ds_read_b128 v[154:157], v158
	ds_read_b128 v[168:171], v158 offset:1024
	ds_read_b128 v[172:175], v158 offset:2048
	ds_read_b128 v[178:181], v158 offset:3072
	s_add_i32 m0, s44, 0xc000
	ds_read_b128 v[182:185], v167
	ds_read_b128 v[186:189], v167 offset:1024
	ds_read_b128 v[190:193], v167 offset:2048
	ds_read_b128 v[208:211], v167 offset:3072
	ds_read_b128 v[212:215], v167 offset:4096
	ds_read_b128 v[216:219], v167 offset:5120
	ds_read_b128 v[220:223], v167 offset:6144
	ds_read_b128 v[224:227], v167 offset:7168
	global_load_lds_dwordx4 v134, s[2:3]
	s_add_i32 m0, s44, 0xe000
	s_nop 0
	global_load_lds_dwordx4 v136, s[2:3]
	s_waitcnt vmcnt(8)
	s_waitcnt lgkmcnt(0)
	s_barrier
	s_setprio 1
	s_waitcnt lgkmcnt(0)
	v_mfma_f32_16x16x32_bf16 v[124:127], v[138:141], v[182:185], v[124:127]
	v_mfma_f32_16x16x32_bf16 v[120:123], v[146:149], v[182:185], v[120:123]
	v_mfma_f32_16x16x32_bf16 v[108:111], v[138:141], v[190:193], v[108:111]
	v_mfma_f32_16x16x32_bf16 v[104:107], v[146:149], v[190:193], v[104:107]
	v_mfma_f32_16x16x32_bf16 v[92:95], v[138:141], v[212:215], v[92:95]
	v_mfma_f32_16x16x32_bf16 v[88:91], v[146:149], v[212:215], v[88:91]
	v_mfma_f32_16x16x32_bf16 v[76:79], v[138:141], v[220:223], v[76:79]
	v_mfma_f32_16x16x32_bf16 v[72:75], v[146:149], v[220:223], v[72:75]
	v_mfma_f32_16x16x32_bf16 v[124:127], v[142:145], v[186:189], v[124:127]
	v_mfma_f32_16x16x32_bf16 v[120:123], v[150:153], v[186:189], v[120:123]
	v_mfma_f32_16x16x32_bf16 v[108:111], v[142:145], v[208:211], v[108:111]
	v_mfma_f32_16x16x32_bf16 v[104:107], v[150:153], v[208:211], v[104:107]
	v_mfma_f32_16x16x32_bf16 v[92:95], v[142:145], v[216:219], v[92:95]
	v_mfma_f32_16x16x32_bf16 v[88:91], v[150:153], v[216:219], v[88:91]
	v_mfma_f32_16x16x32_bf16 v[76:79], v[142:145], v[224:227], v[76:79]
	v_mfma_f32_16x16x32_bf16 v[72:75], v[150:153], v[224:227], v[72:75]
	s_setprio 0
	s_setprio 1
	v_mfma_f32_16x16x32_bf16 v[116:119], v[154:157], v[182:185], v[116:119]
	v_mfma_f32_16x16x32_bf16 v[112:115], v[172:175], v[182:185], v[112:115]
	v_mfma_f32_16x16x32_bf16 v[100:103], v[154:157], v[190:193], v[100:103]
	v_mfma_f32_16x16x32_bf16 v[96:99], v[172:175], v[190:193], v[96:99]
	v_mfma_f32_16x16x32_bf16 v[84:87], v[154:157], v[212:215], v[84:87]
	v_mfma_f32_16x16x32_bf16 v[80:83], v[172:175], v[212:215], v[80:83]
	v_mfma_f32_16x16x32_bf16 v[68:71], v[154:157], v[220:223], v[68:71]
	v_mfma_f32_16x16x32_bf16 v[64:67], v[172:175], v[220:223], v[64:67]
	v_mfma_f32_16x16x32_bf16 v[116:119], v[168:171], v[186:189], v[116:119]
	v_mfma_f32_16x16x32_bf16 v[112:115], v[178:181], v[186:189], v[112:115]
	v_mfma_f32_16x16x32_bf16 v[100:103], v[168:171], v[208:211], v[100:103]
	v_mfma_f32_16x16x32_bf16 v[96:99], v[178:181], v[208:211], v[96:99]
	v_mfma_f32_16x16x32_bf16 v[84:87], v[168:171], v[216:219], v[84:87]
	v_mfma_f32_16x16x32_bf16 v[80:83], v[178:181], v[216:219], v[80:83]
	v_mfma_f32_16x16x32_bf16 v[68:71], v[168:171], v[224:227], v[68:71]
	v_mfma_f32_16x16x32_bf16 v[64:67], v[178:181], v[224:227], v[64:67]
	s_setprio 0
	s_barrier
	s_add_u32 s30, s2, 0xfff80080
	s_addc_u32 s31, s3, -1
	s_cmp_eq_u32 s64, 28
	s_cselect_b32 s35, s58, s31
	s_cselect_b32 s34, s59, s30
	s_cselect_b32 s31, s60, s63
	s_cselect_b32 s30, s61, s62
	s_add_i32 s65, s65, s42
	v_lshl_add_u64 v[158:159], s[30:31], 0, v[176:177]
	s_mov_b32 m0, s65
	ds_read_b128 v[182:185], v167 offset:16384
	ds_read_b128 v[186:189], v167 offset:17408
	ds_read_b128 v[190:193], v167 offset:18432
	ds_read_b128 v[208:211], v167 offset:19456
	ds_read_b128 v[212:215], v167 offset:20480
	ds_read_b128 v[216:219], v167 offset:21504
	ds_read_b128 v[220:223], v167 offset:22528
	ds_read_b128 v[224:227], v167 offset:23552
	global_load_lds_dwordx4 v[158:159], off
	s_add_i32 m0, s65, 0x2000
	s_add_u32 s68, s30, 0x80000
	v_lshl_add_u64 v[194:195], s[30:31], 0, v[128:129]
	s_addc_u32 s69, s31, 0
	s_add_i32 s65, s70, s42
	global_load_lds_dwordx4 v[194:195], off
	v_lshl_add_u64 v[198:199], s[68:69], 0, v[176:177]
	s_mov_b32 m0, s65
	v_lshl_add_u64 v[200:201], s[34:35], 0, v[130:131]
	global_load_lds_dwordx4 v[198:199], off
	v_lshl_add_u64 v[198:199], s[68:69], 0, v[128:129]
	s_add_i32 m0, s65, 0x2000
	s_nop 0
	global_load_lds_dwordx4 v[198:199], off
	v_lshl_add_u64 v[198:199], s[34:35], 0, v[132:133]
	s_mov_b32 m0, s44
	s_nop 0
	global_load_lds_dwordx4 v[198:199], off
	s_mov_b32 m0, s46
	s_nop 0
	global_load_lds_dwordx4 v[200:201], off
	s_add_u32 s34, s34, 0x80000
	s_addc_u32 s35, s35, 0
	s_waitcnt vmcnt(8)
	s_waitcnt lgkmcnt(0)
	s_barrier
; #define PG8_STAGE(bufoff, gbase, voff) do { _Pragma("unroll") for (int _i = 0; _i < 2; ++_i) \
;         __builtin_amdgcn_global_load_lds((const unsigned*)((const char*)(gbase) + (voff)[_i]), (LAS unsigned*)(lds + (bufoff) + ldsw + _i * 8192), 16, 0, 0); } while (0)
; #define PG8_LDA(dst, b, h) do { _Pragma("unroll") for (int m = 0; m < 4; ++m) _Pragma("unroll") for (int k = 0; k < 2; ++k) dst[m][k] = *(const LAS bf16x8*)(lds + PG8_SA(b, h) + aoff + m * 2048 + k * 1024); } while (0)
; #define PG8_LDB(dst, b, h) do { _Pragma("unroll") for (int n = 0; n < 2; ++n) _Pragma("unroll") for (int k = 0; k < 2; ++k) dst[n][k] = *(const LAS bf16x8*)(lds + PG8_SB(b, h) + boff + n * 2048 + k * 1024); } while (0)
; #define PG8_WAIT_V(n) asm volatile("s_waitcnt vmcnt(" #n ")" ::: "memory")
; #define PG8_WAIT_L(n) asm volatile("s_waitcnt lgkmcnt(" #n ")" ::: "memory")
; #define PG8_BAR __builtin_amdgcn_s_barrier()
; #define PG8_SCHED __builtin_amdgcn_sched_barrier(0)
; template <bool F16, class Sched, class Epi>
; __device__ __forceinline__ void gemm_phase(LAS unsigned char* lds, const Gemm g, const Sched& S, const Epi& E, int wave_s) {
;     ...
;             PG8_WAIT_V(8); PG8_WAIT_L(0); PG8_BAR; PG8_MMA(1, 0, At, B0); PG8_MMA(1, 1, At, B1); PG8_BAR; PG8_SCHED;
;             PG8_LDB(B0, 1, 0); PG8_LDB(B1, 1, 1); PG8_SCHED; PG8_LDA(At, 1, 0); PG8_STAGE(PG8_SA(0, 1), a2 + hstepA, voffA);
;             PG8_WAIT_V(8); PG8_WAIT_L(0); PG8_BAR; PG8_MMA(0, 0, At, B0); PG8_MMA(0, 1, At, B1); PG8_BAR; PG8_SCHED;
	s_setprio 1
	s_waitcnt lgkmcnt(0)
	v_mfma_f32_16x16x32_bf16 v[60:63], v[138:141], v[182:185], v[60:63]
	v_mfma_f32_16x16x32_bf16 v[56:59], v[146:149], v[182:185], v[56:59]
	v_mfma_f32_16x16x32_bf16 v[48:51], v[138:141], v[190:193], v[48:51]
	v_mfma_f32_16x16x32_bf16 v[40:43], v[146:149], v[190:193], v[40:43]
	v_mfma_f32_16x16x32_bf16 v[32:35], v[138:141], v[212:215], v[32:35]
	v_mfma_f32_16x16x32_bf16 v[24:27], v[146:149], v[212:215], v[24:27]
	v_mfma_f32_16x16x32_bf16 v[16:19], v[138:141], v[220:223], v[16:19]
	v_mfma_f32_16x16x32_bf16 v[8:11], v[146:149], v[220:223], v[8:11]
	v_mfma_f32_16x16x32_bf16 v[60:63], v[142:145], v[186:189], v[60:63]
	v_mfma_f32_16x16x32_bf16 v[56:59], v[150:153], v[186:189], v[56:59]
	v_mfma_f32_16x16x32_bf16 v[48:51], v[142:145], v[208:211], v[48:51]
	v_mfma_f32_16x16x32_bf16 v[40:43], v[150:153], v[208:211], v[40:43]
	v_mfma_f32_16x16x32_bf16 v[32:35], v[142:145], v[216:219], v[32:35]
	v_mfma_f32_16x16x32_bf16 v[24:27], v[150:153], v[216:219], v[24:27]
	v_mfma_f32_16x16x32_bf16 v[16:19], v[142:145], v[224:227], v[16:19]
	v_mfma_f32_16x16x32_bf16 v[8:11], v[150:153], v[224:227], v[8:11]
	s_setprio 0
	s_setprio 1
	v_mfma_f32_16x16x32_bf16 v[52:55], v[154:157], v[182:185], v[52:55]
	v_mfma_f32_16x16x32_bf16 v[44:47], v[172:175], v[182:185], v[44:47]
	v_mfma_f32_16x16x32_bf16 v[36:39], v[154:157], v[190:193], v[36:39]
	v_mfma_f32_16x16x32_bf16 v[28:31], v[172:175], v[190:193], v[28:31]
	v_mfma_f32_16x16x32_bf16 v[20:23], v[154:157], v[212:215], v[20:23]
	v_mfma_f32_16x16x32_bf16 v[12:15], v[172:175], v[212:215], v[12:15]
	v_mfma_f32_16x16x32_bf16 v[4:7], v[154:157], v[220:223], v[4:7]
	v_mfma_f32_16x16x32_bf16 v[0:3], v[172:175], v[220:223], v[0:3]
	v_mfma_f32_16x16x32_bf16 v[52:55], v[168:171], v[186:189], v[52:55]
	v_mfma_f32_16x16x32_bf16 v[44:47], v[178:181], v[186:189], v[44:47]
	v_mfma_f32_16x16x32_bf16 v[36:39], v[168:171], v[208:211], v[36:39]
	v_mfma_f32_16x16x32_bf16 v[28:31], v[178:181], v[208:211], v[28:31]
	v_mfma_f32_16x16x32_bf16 v[20:23], v[168:171], v[216:219], v[20:23]
	v_mfma_f32_16x16x32_bf16 v[12:15], v[178:181], v[216:219], v[12:15]
	v_mfma_f32_16x16x32_bf16 v[4:7], v[168:171], v[224:227], v[4:7]
	v_mfma_f32_16x16x32_bf16 v[0:3], v[178:181], v[224:227], v[0:3]
	s_setprio 0
	s_barrier
	s_add_i32 s65, 0, 0x18000
	s_add_i32 s68, 0, 0x1c000
	v_add_u32_e32 v150, s65, v163
	v_add_u32_e32 v160, s68, v163
	ds_read_b128 v[138:141], v150
	ds_read_b128 v[142:145], v150 offset:1024
	ds_read_b128 v[146:149], v150 offset:2048
	ds_read_b128 v[150:153], v150 offset:3072
	ds_read_b128 v[154:157], v160
	ds_read_b128 v[168:171], v160 offset:1024
	ds_read_b128 v[172:175], v160 offset:2048
	ds_read_b128 v[178:181], v160 offset:3072
	s_mov_b32 m0, s47
	ds_read_b128 v[182:185], v167 offset:32768
	ds_read_b128 v[186:189], v167 offset:33792
	ds_read_b128 v[190:193], v167 offset:34816
	ds_read_b128 v[208:211], v167 offset:35840
	ds_read_b128 v[212:215], v167 offset:36864
	ds_read_b128 v[216:219], v167 offset:37888
	ds_read_b128 v[220:223], v167 offset:38912
	ds_read_b128 v[224:227], v167 offset:39936
	global_load_lds_dwordx4 v132, s[34:35]
	s_mov_b32 m0, s48
	s_nop 0
	global_load_lds_dwordx4 v130, s[34:35]
	s_waitcnt vmcnt(8)
	s_waitcnt lgkmcnt(0)
	s_barrier
	s_setprio 1
	s_waitcnt lgkmcnt(0)
	v_mfma_f32_16x16x32_bf16 v[124:127], v[138:141], v[182:185], v[124:127]
	v_mfma_f32_16x16x32_bf16 v[120:123], v[146:149], v[182:185], v[120:123]
	v_mfma_f32_16x16x32_bf16 v[108:111], v[138:141], v[190:193], v[108:111]
	v_mfma_f32_16x16x32_bf16 v[104:107], v[146:149], v[190:193], v[104:107]
	v_mfma_f32_16x16x32_bf16 v[92:95], v[138:141], v[212:215], v[92:95]
	v_mfma_f32_16x16x32_bf16 v[88:91], v[146:149], v[212:215], v[88:91]
	v_mfma_f32_16x16x32_bf16 v[76:79], v[138:141], v[220:223], v[76:79]
	v_mfma_f32_16x16x32_bf16 v[72:75], v[146:149], v[220:223], v[72:75]
	v_mfma_f32_16x16x32_bf16 v[124:127], v[142:145], v[186:189], v[124:127]
	v_mfma_f32_16x16x32_bf16 v[120:123], v[150:153], v[186:189], v[120:123]
	v_mfma_f32_16x16x32_bf16 v[108:111], v[142:145], v[208:211], v[108:111]
	v_mfma_f32_16x16x32_bf16 v[104:107], v[150:153], v[208:211], v[104:107]
	v_mfma_f32_16x16x32_bf16 v[92:95], v[142:145], v[216:219], v[92:95]
	v_mfma_f32_16x16x32_bf16 v[88:91], v[150:153], v[216:219], v[88:91]
	v_mfma_f32_16x16x32_bf16 v[76:79], v[142:145], v[224:227], v[76:79]
	v_mfma_f32_16x16x32_bf16 v[72:75], v[150:153], v[224:227], v[72:75]
	s_setprio 0
	s_setprio 1
	v_mfma_f32_16x16x32_bf16 v[116:119], v[154:157], v[182:185], v[116:119]
	v_mfma_f32_16x16x32_bf16 v[112:115], v[172:175], v[182:185], v[112:115]
	v_mfma_f32_16x16x32_bf16 v[100:103], v[154:157], v[190:193], v[100:103]
	v_mfma_f32_16x16x32_bf16 v[96:99], v[172:175], v[190:193], v[96:99]
	v_mfma_f32_16x16x32_bf16 v[84:87], v[154:157], v[212:215], v[84:87]
	v_mfma_f32_16x16x32_bf16 v[80:83], v[172:175], v[212:215], v[80:83]
	v_mfma_f32_16x16x32_bf16 v[68:71], v[154:157], v[220:223], v[68:71]
	v_mfma_f32_16x16x32_bf16 v[64:67], v[172:175], v[220:223], v[64:67]
	v_mfma_f32_16x16x32_bf16 v[116:119], v[168:171], v[186:189], v[116:119]
	v_mfma_f32_16x16x32_bf16 v[112:115], v[178:181], v[186:189], v[112:115]
	v_mfma_f32_16x16x32_bf16 v[100:103], v[168:171], v[208:211], v[100:103]
	v_mfma_f32_16x16x32_bf16 v[96:99], v[178:181], v[208:211], v[96:99]
	v_mfma_f32_16x16x32_bf16 v[84:87], v[168:171], v[216:219], v[84:87]
	v_mfma_f32_16x16x32_bf16 v[80:83], v[178:181], v[216:219], v[80:83]
	v_mfma_f32_16x16x32_bf16 v[68:71], v[168:171], v[224:227], v[68:71]
	v_mfma_f32_16x16x32_bf16 v[64:67], v[178:181], v[224:227], v[64:67]
	s_setprio 0
	s_barrier
; #define PG8_STAGE(bufoff, gbase, voff) do { _Pragma("unroll") for (int _i = 0; _i < 2; ++_i) \
;         __builtin_amdgcn_global_load_lds((const unsigned*)((const char*)(gbase) + (voff)[_i]), (LAS unsigned*)(lds + (bufoff) + ldsw + _i * 8192), 16, 0, 0); } while (0)
; #define PG8_LDA(dst, b, h) do { _Pragma("unroll") for (int m = 0; m < 4; ++m) _Pragma("unroll") for (int k = 0; k < 2; ++k) dst[m][k] = *(const LAS bf16x8*)(lds + PG8_SA(b, h) + aoff + m * 2048 + k * 1024); } while (0)
; #define PG8_WAIT_V(n) asm volatile("s_waitcnt vmcnt(" #n ")" ::: "memory")
; #define PG8_WAIT_L(n) asm volatile("s_waitcnt lgkmcnt(" #n ")" ::: "memory")
; #define PG8_BAR __builtin_amdgcn_s_barrier()
; #define PG8_SCHED __builtin_amdgcn_sched_barrier(0)
; template <bool F16, class Sched, class Epi>
; __device__ __forceinline__ void gemm_phase(LAS unsigned char* lds, const Gemm g, const Sched& S, const Epi& E, int wave_s) {
;     ...
;             PG8_LDA(At, 1, 1); PG8_STAGE(PG8_SB(1, 0), b3, voffB); PG8_STAGE(PG8_SB(1, 1), b3 + hstepB, voffB); PG8_STAGE(PG8_SA(1, 0), a3, voffA);
;             PG8_WAIT_V(8); PG8_WAIT_L(0); PG8_BAR; PG8_MMA(1, 0, At, B0); PG8_MMA(1, 1, At, B1); PG8_BAR; PG8_SCHED;
;         }
	s_add_i32 s34, s65, s42
	v_lshl_add_u64 v[158:159], v[158:159], 0, s[54:55]
	s_mov_b32 m0, s34
	ds_read_b128 v[182:185], v167 offset:49152
	ds_read_b128 v[186:189], v167 offset:50176
	ds_read_b128 v[190:193], v167 offset:51200
	ds_read_b128 v[208:211], v167 offset:52224
	ds_read_b128 v[212:215], v167 offset:53248
	ds_read_b128 v[216:219], v167 offset:54272
	ds_read_b128 v[220:223], v167 offset:55296
	ds_read_b128 v[224:227], v167 offset:56320
	global_load_lds_dwordx4 v[158:159], off
	s_add_i32 m0, s34, 0x2000
	s_add_u32 s30, s30, 0x80080
	v_lshl_add_u64 v[158:159], v[194:195], 0, s[54:55]
	s_addc_u32 s31, s31, 0
	s_add_i32 s34, s68, s42
	global_load_lds_dwordx4 v[158:159], off
	v_lshl_add_u64 v[158:159], s[30:31], 0, v[176:177]
	s_mov_b32 m0, s34
	s_nop 0
	global_load_lds_dwordx4 v[158:159], off
	v_lshl_add_u64 v[158:159], s[30:31], 0, v[128:129]
	s_add_i32 m0, s34, 0x2000
	s_nop 0
	global_load_lds_dwordx4 v[158:159], off
	v_lshl_add_u64 v[158:159], v[198:199], 0, s[54:55]
	s_mov_b32 m0, s49
	s_nop 0
	global_load_lds_dwordx4 v[158:159], off
	v_lshl_add_u64 v[158:159], v[200:201], 0, s[54:55]
	s_mov_b32 m0, s52
	s_nop 0
	global_load_lds_dwordx4 v[158:159], off
	s_waitcnt vmcnt(8)
	s_waitcnt lgkmcnt(0)
	s_barrier
	s_setprio 1
	s_waitcnt lgkmcnt(0)
	v_mfma_f32_16x16x32_bf16 v[60:63], v[138:141], v[182:185], v[60:63]
	v_mfma_f32_16x16x32_bf16 v[56:59], v[146:149], v[182:185], v[56:59]
	v_mfma_f32_16x16x32_bf16 v[48:51], v[138:141], v[190:193], v[48:51]
	v_mfma_f32_16x16x32_bf16 v[40:43], v[146:149], v[190:193], v[40:43]
	v_mfma_f32_16x16x32_bf16 v[32:35], v[138:141], v[212:215], v[32:35]
	v_mfma_f32_16x16x32_bf16 v[24:27], v[146:149], v[212:215], v[24:27]
	v_mfma_f32_16x16x32_bf16 v[16:19], v[138:141], v[220:223], v[16:19]
	v_mfma_f32_16x16x32_bf16 v[8:11], v[146:149], v[220:223], v[8:11]
	v_mfma_f32_16x16x32_bf16 v[60:63], v[142:145], v[186:189], v[60:63]
	v_mfma_f32_16x16x32_bf16 v[56:59], v[150:153], v[186:189], v[56:59]
	v_mfma_f32_16x16x32_bf16 v[48:51], v[142:145], v[208:211], v[48:51]
	v_mfma_f32_16x16x32_bf16 v[40:43], v[150:153], v[208:211], v[40:43]
	v_mfma_f32_16x16x32_bf16 v[32:35], v[142:145], v[216:219], v[32:35]
	v_mfma_f32_16x16x32_bf16 v[24:27], v[150:153], v[216:219], v[24:27]
	v_mfma_f32_16x16x32_bf16 v[16:19], v[142:145], v[224:227], v[16:19]
	v_mfma_f32_16x16x32_bf16 v[8:11], v[150:153], v[224:227], v[8:11]
	s_setprio 0
	s_setprio 1
	v_mfma_f32_16x16x32_bf16 v[52:55], v[154:157], v[182:185], v[52:55]
	v_mfma_f32_16x16x32_bf16 v[44:47], v[172:175], v[182:185], v[44:47]
	v_mfma_f32_16x16x32_bf16 v[36:39], v[154:157], v[190:193], v[36:39]
	v_mfma_f32_16x16x32_bf16 v[28:31], v[172:175], v[190:193], v[28:31]
	v_mfma_f32_16x16x32_bf16 v[20:23], v[154:157], v[212:215], v[20:23]
	v_mfma_f32_16x16x32_bf16 v[12:15], v[172:175], v[212:215], v[12:15]
	v_mfma_f32_16x16x32_bf16 v[4:7], v[154:157], v[220:223], v[4:7]
	v_mfma_f32_16x16x32_bf16 v[0:3], v[172:175], v[220:223], v[0:3]
	v_mfma_f32_16x16x32_bf16 v[52:55], v[168:171], v[186:189], v[52:55]
	v_mfma_f32_16x16x32_bf16 v[44:47], v[178:181], v[186:189], v[44:47]
	v_mfma_f32_16x16x32_bf16 v[36:39], v[168:171], v[208:211], v[36:39]
	v_mfma_f32_16x16x32_bf16 v[28:31], v[178:181], v[208:211], v[28:31]
	v_mfma_f32_16x16x32_bf16 v[20:23], v[168:171], v[216:219], v[20:23]
	v_mfma_f32_16x16x32_bf16 v[12:15], v[178:181], v[216:219], v[12:15]
	v_mfma_f32_16x16x32_bf16 v[4:7], v[168:171], v[224:227], v[4:7]
	v_mfma_f32_16x16x32_bf16 v[0:3], v[178:181], v[224:227], v[0:3]
	s_setprio 0
	s_barrier
	s_add_i32 s64, s64, 2
	s_add_u32 s2, s2, 0x100
	s_addc_u32 s3, s3, 0
	s_add_u32 s62, s62, 0x100
	s_addc_u32 s63, s63, 0
	s_cmp_gt_u32 s64, 29
	s_cbranch_scc0 .LBB0_358
	s_and_b64 vcc, exec, s[26:27]
	s_cbranch_vccz .LBB0_361
	s_barrier

; #define PG8_STAGE(bufoff, gbase, voff) do { _Pragma("unroll") for (int _i = 0; _i < 2; ++_i) \
;         __builtin_amdgcn_global_load_lds((const unsigned*)((const char*)(gbase) + (voff)[_i]), (LAS unsigned*)(lds + (bufoff) + ldsw + _i * 8192), 16, 0, 0); } while (0)
; #define PG8_LDA(dst, b, h) do { _Pragma("unroll") for (int m = 0; m < 4; ++m) _Pragma("unroll") for (int k = 0; k < 2; ++k) dst[m][k] = *(const LAS bf16x8*)(lds + PG8_SA(b, h) + aoff + m * 2048 + k * 1024); } while (0)
; #define PG8_LDB(dst, b, h) do { _Pragma("unroll") for (int n = 0; n < 2; ++n) _Pragma("unroll") for (int k = 0; k < 2; ++k) dst[n][k] = *(const LAS bf16x8*)(lds + PG8_SB(b, h) + boff + n * 2048 + k * 1024); } while (0)
; #define PG8_WAIT_V(n) asm volatile("s_waitcnt vmcnt(" #n ")" ::: "memory")
; #define PG8_WAIT_L(n) asm volatile("s_waitcnt lgkmcnt(" #n ")" ::: "memory")
; #define PG8_BAR __builtin_amdgcn_s_barrier()
; #define PG8_SCHED __builtin_amdgcn_sched_barrier(0)
; template <bool F16, class Sched, class Epi>
; __device__ __forceinline__ void gemm_phase(LAS unsigned char* lds, const Gemm g, const Sched& S, const Epi& E, int wave_s) {
;     ...
;             const char* a1 = cA + (size_t)(t + 1) * kstep;
;             const char* a2 = last ? nA : cA + (size_t)(t + 2) * kstep; const char* b2 = last ? nB : cB + (size_t)(t + 2) * kstep;
;             const char* a3 = a2 + kstep; const char* b3 = b2 + kstep;
;             PG8_LDB(B0, 0, 0); PG8_LDB(B1, 0, 1); PG8_SCHED; PG8_LDA(At, 0, 0); PG8_STAGE(PG8_SA(1, 1), a1 + hstepA, voffA);
;             PG8_WAIT_V(8); PG8_WAIT_L(0); PG8_BAR; PG8_MMA(0, 0, At, B0); PG8_MMA(0, 1, At, B1); PG8_BAR; PG8_SCHED;
;             PG8_LDA(At, 0, 1); PG8_STAGE(PG8_SB(0, 0), b2, voffB); PG8_STAGE(PG8_SB(0, 1), b2 + hstepB, voffB); PG8_STAGE(PG8_SA(0, 0), a2, voffA);
;             PG8_WAIT_V(8); PG8_WAIT_L(0); PG8_BAR; PG8_MMA(1, 0, At, B0); PG8_MMA(1, 1, At, B1); PG8_BAR; PG8_SCHED;
.LBB0_598:
	s_add_i32 s61, 0, 0x10000
	s_add_i32 s64, 0, 0x14000
	v_add_u32_e32 v150, s61, v163
	v_add_u32_e32 v170, s64, v163
	ds_read_b128 v[138:141], v150
	ds_read_b128 v[142:145], v150 offset:1024
	ds_read_b128 v[146:149], v150 offset:2048
	ds_read_b128 v[150:153], v150 offset:3072
	ds_read_b128 v[154:157], v170
	ds_read_b128 v[158:161], v170 offset:1024
	ds_read_b128 v[166:169], v170 offset:2048
	ds_read_b128 v[170:173], v170 offset:3072
	s_add_i32 m0, s43, 0xc000
	ds_read_b128 v[178:181], v165
	ds_read_b128 v[182:185], v165 offset:1024
	ds_read_b128 v[186:189], v165 offset:2048
	ds_read_b128 v[190:193], v165 offset:3072
	ds_read_b128 v[208:211], v165 offset:4096
	ds_read_b128 v[212:215], v165 offset:5120
	ds_read_b128 v[216:219], v165 offset:6144
	ds_read_b128 v[220:223], v165 offset:7168
	global_load_lds_dwordx4 v134, s[26:27]
	s_add_i32 m0, s43, 0xe000
	s_nop 0
	global_load_lds_dwordx4 v136, s[26:27]
	s_waitcnt vmcnt(8)
	s_waitcnt lgkmcnt(0)
	s_barrier
	s_setprio 1
	s_waitcnt lgkmcnt(0)
	v_mfma_f32_16x16x32_bf16 v[124:127], v[138:141], v[178:181], v[124:127]
	v_mfma_f32_16x16x32_bf16 v[120:123], v[146:149], v[178:181], v[120:123]
	v_mfma_f32_16x16x32_bf16 v[108:111], v[138:141], v[186:189], v[108:111]
	v_mfma_f32_16x16x32_bf16 v[104:107], v[146:149], v[186:189], v[104:107]
	v_mfma_f32_16x16x32_bf16 v[96:99], v[138:141], v[208:211], v[96:99]
	v_mfma_f32_16x16x32_bf16 v[92:95], v[146:149], v[208:211], v[92:95]
	v_mfma_f32_16x16x32_bf16 v[84:87], v[138:141], v[216:219], v[84:87]
	v_mfma_f32_16x16x32_bf16 v[76:79], v[146:149], v[216:219], v[76:79]
	v_mfma_f32_16x16x32_bf16 v[124:127], v[142:145], v[182:185], v[124:127]
	v_mfma_f32_16x16x32_bf16 v[120:123], v[150:153], v[182:185], v[120:123]
	v_mfma_f32_16x16x32_bf16 v[108:111], v[142:145], v[190:193], v[108:111]
	v_mfma_f32_16x16x32_bf16 v[104:107], v[150:153], v[190:193], v[104:107]
	v_mfma_f32_16x16x32_bf16 v[96:99], v[142:145], v[212:215], v[96:99]
	v_mfma_f32_16x16x32_bf16 v[92:95], v[150:153], v[212:215], v[92:95]
	v_mfma_f32_16x16x32_bf16 v[84:87], v[142:145], v[220:223], v[84:87]
	v_mfma_f32_16x16x32_bf16 v[76:79], v[150:153], v[220:223], v[76:79]
	s_setprio 0
	s_setprio 1
	v_mfma_f32_16x16x32_bf16 v[116:119], v[154:157], v[178:181], v[116:119]
	v_mfma_f32_16x16x32_bf16 v[112:115], v[166:169], v[178:181], v[112:115]
	v_mfma_f32_16x16x32_bf16 v[100:103], v[154:157], v[186:189], v[100:103]
	v_mfma_f32_16x16x32_bf16 v[88:91], v[166:169], v[186:189], v[88:91]
	v_mfma_f32_16x16x32_bf16 v[80:83], v[154:157], v[208:211], v[80:83]
	v_mfma_f32_16x16x32_bf16 v[72:75], v[166:169], v[208:211], v[72:75]
	v_mfma_f32_16x16x32_bf16 v[68:71], v[154:157], v[216:219], v[68:71]
	v_mfma_f32_16x16x32_bf16 v[64:67], v[166:169], v[216:219], v[64:67]
	v_mfma_f32_16x16x32_bf16 v[116:119], v[158:161], v[182:185], v[116:119]
	v_mfma_f32_16x16x32_bf16 v[112:115], v[170:173], v[182:185], v[112:115]
	v_mfma_f32_16x16x32_bf16 v[100:103], v[158:161], v[190:193], v[100:103]
	v_mfma_f32_16x16x32_bf16 v[88:91], v[170:173], v[190:193], v[88:91]
	v_mfma_f32_16x16x32_bf16 v[80:83], v[158:161], v[212:215], v[80:83]
	v_mfma_f32_16x16x32_bf16 v[72:75], v[170:173], v[212:215], v[72:75]
	v_mfma_f32_16x16x32_bf16 v[68:71], v[158:161], v[220:223], v[68:71]
	v_mfma_f32_16x16x32_bf16 v[64:67], v[170:173], v[220:223], v[64:67]
	s_setprio 0
	s_barrier
	s_add_u32 s28, s26, 0xfff80080
	s_addc_u32 s29, s27, -1
	s_cmp_eq_u32 s60, 28
	s_cselect_b32 s31, s49, s29
	s_cselect_b32 s30, s50, s28
	s_cselect_b32 s29, s52, s59
	s_cselect_b32 s28, s53, s58
	s_add_i32 s61, s61, s39
	v_lshl_add_u64 v[174:175], s[28:29], 0, v[176:177]
	s_mov_b32 m0, s61
	ds_read_b128 v[178:181], v165 offset:16384
	ds_read_b128 v[182:185], v165 offset:17408
	ds_read_b128 v[186:189], v165 offset:18432
	ds_read_b128 v[190:193], v165 offset:19456
	ds_read_b128 v[208:211], v165 offset:20480
	ds_read_b128 v[212:215], v165 offset:21504
	ds_read_b128 v[216:219], v165 offset:22528
	ds_read_b128 v[220:223], v165 offset:23552
	global_load_lds_dwordx4 v[174:175], off
	s_add_i32 m0, s61, 0x2000
	s_add_u32 s62, s28, 0x80000
	v_lshl_add_u64 v[194:195], s[28:29], 0, v[128:129]
	s_addc_u32 s63, s29, 0
	s_add_i32 s61, s64, s39
	global_load_lds_dwordx4 v[194:195], off
	v_lshl_add_u64 v[198:199], s[62:63], 0, v[176:177]
	s_mov_b32 m0, s61
	v_lshl_add_u64 v[200:201], s[30:31], 0, v[130:131]
	global_load_lds_dwordx4 v[198:199], off
	v_lshl_add_u64 v[198:199], s[62:63], 0, v[128:129]
	s_add_i32 m0, s61, 0x2000
	s_nop 0
	global_load_lds_dwordx4 v[198:199], off
	v_lshl_add_u64 v[198:199], s[30:31], 0, v[132:133]
	s_mov_b32 m0, s43
	s_nop 0
	global_load_lds_dwordx4 v[198:199], off
	s_mov_b32 m0, s44
	s_nop 0
	global_load_lds_dwordx4 v[200:201], off
	s_add_u32 s30, s30, 0x80000
	s_addc_u32 s31, s31, 0
	s_waitcnt vmcnt(8)
	s_waitcnt lgkmcnt(0)
	s_barrier
; #define PG8_STAGE(bufoff, gbase, voff) do { _Pragma("unroll") for (int _i = 0; _i < 2; ++_i) \
;         __builtin_amdgcn_global_load_lds((const unsigned*)((const char*)(gbase) + (voff)[_i]), (LAS unsigned*)(lds + (bufoff) + ldsw + _i * 8192), 16, 0, 0); } while (0)
; #define PG8_LDA(dst, b, h) do { _Pragma("unroll") for (int m = 0; m < 4; ++m) _Pragma("unroll") for (int k = 0; k < 2; ++k) dst[m][k] = *(const LAS bf16x8*)(lds + PG8_SA(b, h) + aoff + m * 2048 + k * 1024); } while (0)
; #define PG8_LDB(dst, b, h) do { _Pragma("unroll") for (int n = 0; n < 2; ++n) _Pragma("unroll") for (int k = 0; k < 2; ++k) dst[n][k] = *(const LAS bf16x8*)(lds + PG8_SB(b, h) + boff + n * 2048 + k * 1024); } while (0)
; #define PG8_WAIT_V(n) asm volatile("s_waitcnt vmcnt(" #n ")" ::: "memory")
; #define PG8_WAIT_L(n) asm volatile("s_waitcnt lgkmcnt(" #n ")" ::: "memory")
; #define PG8_BAR __builtin_amdgcn_s_barrier()
; #define PG8_SCHED __builtin_amdgcn_sched_barrier(0)
; template <bool F16, class Sched, class Epi>
; __device__ __forceinline__ void gemm_phase(LAS unsigned char* lds, const Gemm g, const Sched& S, const Epi& E, int wave_s) {
;     ...
;             PG8_WAIT_V(8); PG8_WAIT_L(0); PG8_BAR; PG8_MMA(1, 0, At, B0); PG8_MMA(1, 1, At, B1); PG8_BAR; PG8_SCHED;
;             PG8_LDB(B0, 1, 0); PG8_LDB(B1, 1, 1); PG8_SCHED; PG8_LDA(At, 1, 0); PG8_STAGE(PG8_SA(0, 1), a2 + hstepA, voffA);
;             PG8_WAIT_V(8); PG8_WAIT_L(0); PG8_BAR; PG8_MMA(0, 0, At, B0); PG8_MMA(0, 1, At, B1); PG8_BAR; PG8_SCHED;
	s_setprio 1
	s_waitcnt lgkmcnt(0)
	v_mfma_f32_16x16x32_bf16 v[60:63], v[138:141], v[178:181], v[60:63]
	v_mfma_f32_16x16x32_bf16 v[56:59], v[146:149], v[178:181], v[56:59]
	v_mfma_f32_16x16x32_bf16 v[52:55], v[138:141], v[186:189], v[52:55]
	v_mfma_f32_16x16x32_bf16 v[44:47], v[146:149], v[186:189], v[44:47]
	v_mfma_f32_16x16x32_bf16 v[36:39], v[138:141], v[208:211], v[36:39]
	v_mfma_f32_16x16x32_bf16 v[28:31], v[146:149], v[208:211], v[28:31]
	v_mfma_f32_16x16x32_bf16 v[20:23], v[138:141], v[216:219], v[20:23]
	v_mfma_f32_16x16x32_bf16 v[12:15], v[146:149], v[216:219], v[12:15]
	v_mfma_f32_16x16x32_bf16 v[60:63], v[142:145], v[182:185], v[60:63]
	v_mfma_f32_16x16x32_bf16 v[56:59], v[150:153], v[182:185], v[56:59]
	v_mfma_f32_16x16x32_bf16 v[52:55], v[142:145], v[190:193], v[52:55]
	v_mfma_f32_16x16x32_bf16 v[44:47], v[150:153], v[190:193], v[44:47]
	v_mfma_f32_16x16x32_bf16 v[36:39], v[142:145], v[212:215], v[36:39]
	v_mfma_f32_16x16x32_bf16 v[28:31], v[150:153], v[212:215], v[28:31]
	v_mfma_f32_16x16x32_bf16 v[20:23], v[142:145], v[220:223], v[20:23]
	v_mfma_f32_16x16x32_bf16 v[12:15], v[150:153], v[220:223], v[12:15]
	s_setprio 0
	s_setprio 1
	v_mfma_f32_16x16x32_bf16 v[48:51], v[154:157], v[178:181], v[48:51]
	v_mfma_f32_16x16x32_bf16 v[40:43], v[166:169], v[178:181], v[40:43]
	v_mfma_f32_16x16x32_bf16 v[32:35], v[154:157], v[186:189], v[32:35]
	v_mfma_f32_16x16x32_bf16 v[24:27], v[166:169], v[186:189], v[24:27]
	v_mfma_f32_16x16x32_bf16 v[16:19], v[154:157], v[208:211], v[16:19]
	v_mfma_f32_16x16x32_bf16 v[8:11], v[166:169], v[208:211], v[8:11]
	v_mfma_f32_16x16x32_bf16 v[4:7], v[154:157], v[216:219], v[4:7]
	v_mfma_f32_16x16x32_bf16 v[0:3], v[166:169], v[216:219], v[0:3]
	v_mfma_f32_16x16x32_bf16 v[48:51], v[158:161], v[182:185], v[48:51]
	v_mfma_f32_16x16x32_bf16 v[40:43], v[170:173], v[182:185], v[40:43]
	v_mfma_f32_16x16x32_bf16 v[32:35], v[158:161], v[190:193], v[32:35]
	v_mfma_f32_16x16x32_bf16 v[24:27], v[170:173], v[190:193], v[24:27]
	v_mfma_f32_16x16x32_bf16 v[16:19], v[158:161], v[212:215], v[16:19]
	v_mfma_f32_16x16x32_bf16 v[8:11], v[170:173], v[212:215], v[8:11]
	v_mfma_f32_16x16x32_bf16 v[4:7], v[158:161], v[220:223], v[4:7]
	v_mfma_f32_16x16x32_bf16 v[0:3], v[170:173], v[220:223], v[0:3]
	s_setprio 0
	s_barrier
	s_add_i32 s61, 0, 0x18000
	s_add_i32 s62, 0, 0x1c000
	v_add_u32_e32 v150, s61, v163
	v_add_u32_e32 v170, s62, v163
	ds_read_b128 v[138:141], v150
	ds_read_b128 v[142:145], v150 offset:1024
	ds_read_b128 v[146:149], v150 offset:2048
	ds_read_b128 v[150:153], v150 offset:3072
	ds_read_b128 v[154:157], v170
	ds_read_b128 v[158:161], v170 offset:1024
	ds_read_b128 v[166:169], v170 offset:2048
	ds_read_b128 v[170:173], v170 offset:3072
	s_mov_b32 m0, s45
	ds_read_b128 v[178:181], v165 offset:32768
	ds_read_b128 v[182:185], v165 offset:33792
	ds_read_b128 v[186:189], v165 offset:34816
	ds_read_b128 v[190:193], v165 offset:35840
	ds_read_b128 v[208:211], v165 offset:36864
	ds_read_b128 v[212:215], v165 offset:37888
	ds_read_b128 v[216:219], v165 offset:38912
	ds_read_b128 v[220:223], v165 offset:39936
	global_load_lds_dwordx4 v132, s[30:31]
	s_mov_b32 m0, s46
	s_nop 0
	global_load_lds_dwordx4 v130, s[30:31]
	s_waitcnt vmcnt(8)
	s_waitcnt lgkmcnt(0)
	s_barrier
	s_setprio 1
	s_waitcnt lgkmcnt(0)
	v_mfma_f32_16x16x32_bf16 v[124:127], v[138:141], v[178:181], v[124:127]
	v_mfma_f32_16x16x32_bf16 v[120:123], v[146:149], v[178:181], v[120:123]
	v_mfma_f32_16x16x32_bf16 v[108:111], v[138:141], v[186:189], v[108:111]
	v_mfma_f32_16x16x32_bf16 v[104:107], v[146:149], v[186:189], v[104:107]
	v_mfma_f32_16x16x32_bf16 v[96:99], v[138:141], v[208:211], v[96:99]
	v_mfma_f32_16x16x32_bf16 v[92:95], v[146:149], v[208:211], v[92:95]
	v_mfma_f32_16x16x32_bf16 v[84:87], v[138:141], v[216:219], v[84:87]
	v_mfma_f32_16x16x32_bf16 v[76:79], v[146:149], v[216:219], v[76:79]
	v_mfma_f32_16x16x32_bf16 v[124:127], v[142:145], v[182:185], v[124:127]
	v_mfma_f32_16x16x32_bf16 v[120:123], v[150:153], v[182:185], v[120:123]
	v_mfma_f32_16x16x32_bf16 v[108:111], v[142:145], v[190:193], v[108:111]
	v_mfma_f32_16x16x32_bf16 v[104:107], v[150:153], v[190:193], v[104:107]
	v_mfma_f32_16x16x32_bf16 v[96:99], v[142:145], v[212:215], v[96:99]
	v_mfma_f32_16x16x32_bf16 v[92:95], v[150:153], v[212:215], v[92:95]
	v_mfma_f32_16x16x32_bf16 v[84:87], v[142:145], v[220:223], v[84:87]
	v_mfma_f32_16x16x32_bf16 v[76:79], v[150:153], v[220:223], v[76:79]
	s_setprio 0
	s_setprio 1
	v_mfma_f32_16x16x32_bf16 v[116:119], v[154:157], v[178:181], v[116:119]
	v_mfma_f32_16x16x32_bf16 v[112:115], v[166:169], v[178:181], v[112:115]
	v_mfma_f32_16x16x32_bf16 v[100:103], v[154:157], v[186:189], v[100:103]
	v_mfma_f32_16x16x32_bf16 v[88:91], v[166:169], v[186:189], v[88:91]
	v_mfma_f32_16x16x32_bf16 v[80:83], v[154:157], v[208:211], v[80:83]
	v_mfma_f32_16x16x32_bf16 v[72:75], v[166:169], v[208:211], v[72:75]
	v_mfma_f32_16x16x32_bf16 v[68:71], v[154:157], v[216:219], v[68:71]
	v_mfma_f32_16x16x32_bf16 v[64:67], v[166:169], v[216:219], v[64:67]
	v_mfma_f32_16x16x32_bf16 v[116:119], v[158:161], v[182:185], v[116:119]
	v_mfma_f32_16x16x32_bf16 v[112:115], v[170:173], v[182:185], v[112:115]
	v_mfma_f32_16x16x32_bf16 v[100:103], v[158:161], v[190:193], v[100:103]
	v_mfma_f32_16x16x32_bf16 v[88:91], v[170:173], v[190:193], v[88:91]
	v_mfma_f32_16x16x32_bf16 v[80:83], v[158:161], v[212:215], v[80:83]
	v_mfma_f32_16x16x32_bf16 v[72:75], v[170:173], v[212:215], v[72:75]
	v_mfma_f32_16x16x32_bf16 v[68:71], v[158:161], v[220:223], v[68:71]
	v_mfma_f32_16x16x32_bf16 v[64:67], v[170:173], v[220:223], v[64:67]
	s_setprio 0
	s_barrier
; #define PG8_STAGE(bufoff, gbase, voff) do { _Pragma("unroll") for (int _i = 0; _i < 2; ++_i) \
;         __builtin_amdgcn_global_load_lds((const unsigned*)((const char*)(gbase) + (voff)[_i]), (LAS unsigned*)(lds + (bufoff) + ldsw + _i * 8192), 16, 0, 0); } while (0)
; #define PG8_LDA(dst, b, h) do { _Pragma("unroll") for (int m = 0; m < 4; ++m) _Pragma("unroll") for (int k = 0; k < 2; ++k) dst[m][k] = *(const LAS bf16x8*)(lds + PG8_SA(b, h) + aoff + m * 2048 + k * 1024); } while (0)
; #define PG8_WAIT_V(n) asm volatile("s_waitcnt vmcnt(" #n ")" ::: "memory")
; #define PG8_WAIT_L(n) asm volatile("s_waitcnt lgkmcnt(" #n ")" ::: "memory")
; #define PG8_BAR __builtin_amdgcn_s_barrier()
; #define PG8_SCHED __builtin_amdgcn_sched_barrier(0)
; template <bool F16, class Sched, class Epi>
; __device__ __forceinline__ void gemm_phase(LAS unsigned char* lds, const Gemm g, const Sched& S, const Epi& E, int wave_s) {
;     ...
;             PG8_LDA(At, 1, 1); PG8_STAGE(PG8_SB(1, 0), b3, voffB); PG8_STAGE(PG8_SB(1, 1), b3 + hstepB, voffB); PG8_STAGE(PG8_SA(1, 0), a3, voffA);
;             PG8_WAIT_V(8); PG8_WAIT_L(0); PG8_BAR; PG8_MMA(1, 0, At, B0); PG8_MMA(1, 1, At, B1); PG8_BAR; PG8_SCHED;
;         }
	s_add_i32 s30, s61, s39
	v_lshl_add_u64 v[174:175], v[174:175], 0, s[54:55]
	s_mov_b32 m0, s30
	ds_read_b128 v[178:181], v165 offset:49152
	ds_read_b128 v[182:185], v165 offset:50176
	ds_read_b128 v[186:189], v165 offset:51200
	ds_read_b128 v[190:193], v165 offset:52224
	ds_read_b128 v[208:211], v165 offset:53248
	ds_read_b128 v[212:215], v165 offset:54272
	ds_read_b128 v[216:219], v165 offset:55296
	ds_read_b128 v[220:223], v165 offset:56320
	global_load_lds_dwordx4 v[174:175], off
	s_add_i32 m0, s30, 0x2000
	s_add_u32 s28, s28, 0x80080
	v_lshl_add_u64 v[174:175], v[194:195], 0, s[54:55]
	s_addc_u32 s29, s29, 0
	s_add_i32 s30, s62, s39
	global_load_lds_dwordx4 v[174:175], off
	v_lshl_add_u64 v[174:175], s[28:29], 0, v[176:177]
	s_mov_b32 m0, s30
	s_nop 0
	global_load_lds_dwordx4 v[174:175], off
	v_lshl_add_u64 v[174:175], s[28:29], 0, v[128:129]
	s_add_i32 m0, s30, 0x2000
	s_nop 0
	global_load_lds_dwordx4 v[174:175], off
	v_lshl_add_u64 v[174:175], v[198:199], 0, s[54:55]
	s_mov_b32 m0, s19
	s_nop 0
	global_load_lds_dwordx4 v[174:175], off
	v_lshl_add_u64 v[174:175], v[200:201], 0, s[54:55]
	s_mov_b32 m0, s47
	s_nop 0
	global_load_lds_dwordx4 v[174:175], off
	s_waitcnt vmcnt(8)
	s_waitcnt lgkmcnt(0)
	s_barrier
	s_setprio 1
	s_waitcnt lgkmcnt(0)
	v_mfma_f32_16x16x32_bf16 v[60:63], v[138:141], v[178:181], v[60:63]
	v_mfma_f32_16x16x32_bf16 v[56:59], v[146:149], v[178:181], v[56:59]
	v_mfma_f32_16x16x32_bf16 v[52:55], v[138:141], v[186:189], v[52:55]
	v_mfma_f32_16x16x32_bf16 v[44:47], v[146:149], v[186:189], v[44:47]
	v_mfma_f32_16x16x32_bf16 v[36:39], v[138:141], v[208:211], v[36:39]
	v_mfma_f32_16x16x32_bf16 v[28:31], v[146:149], v[208:211], v[28:31]
	v_mfma_f32_16x16x32_bf16 v[20:23], v[138:141], v[216:219], v[20:23]
	v_mfma_f32_16x16x32_bf16 v[12:15], v[146:149], v[216:219], v[12:15]
	v_mfma_f32_16x16x32_bf16 v[60:63], v[142:145], v[182:185], v[60:63]
	v_mfma_f32_16x16x32_bf16 v[56:59], v[150:153], v[182:185], v[56:59]
	v_mfma_f32_16x16x32_bf16 v[52:55], v[142:145], v[190:193], v[52:55]
	v_mfma_f32_16x16x32_bf16 v[44:47], v[150:153], v[190:193], v[44:47]
	v_mfma_f32_16x16x32_bf16 v[36:39], v[142:145], v[212:215], v[36:39]
	v_mfma_f32_16x16x32_bf16 v[28:31], v[150:153], v[212:215], v[28:31]
	v_mfma_f32_16x16x32_bf16 v[20:23], v[142:145], v[220:223], v[20:23]
	v_mfma_f32_16x16x32_bf16 v[12:15], v[150:153], v[220:223], v[12:15]
	s_setprio 0
	s_setprio 1
	v_mfma_f32_16x16x32_bf16 v[48:51], v[154:157], v[178:181], v[48:51]
	v_mfma_f32_16x16x32_bf16 v[40:43], v[166:169], v[178:181], v[40:43]
	v_mfma_f32_16x16x32_bf16 v[32:35], v[154:157], v[186:189], v[32:35]
	v_mfma_f32_16x16x32_bf16 v[24:27], v[166:169], v[186:189], v[24:27]
	v_mfma_f32_16x16x32_bf16 v[16:19], v[154:157], v[208:211], v[16:19]
	v_mfma_f32_16x16x32_bf16 v[8:11], v[166:169], v[208:211], v[8:11]
	v_mfma_f32_16x16x32_bf16 v[4:7], v[154:157], v[216:219], v[4:7]
	v_mfma_f32_16x16x32_bf16 v[0:3], v[166:169], v[216:219], v[0:3]
	v_mfma_f32_16x16x32_bf16 v[48:51], v[158:161], v[182:185], v[48:51]
	v_mfma_f32_16x16x32_bf16 v[40:43], v[170:173], v[182:185], v[40:43]
	v_mfma_f32_16x16x32_bf16 v[32:35], v[158:161], v[190:193], v[32:35]
	v_mfma_f32_16x16x32_bf16 v[24:27], v[170:173], v[190:193], v[24:27]
	v_mfma_f32_16x16x32_bf16 v[16:19], v[158:161], v[212:215], v[16:19]
	v_mfma_f32_16x16x32_bf16 v[8:11], v[170:173], v[212:215], v[8:11]
	v_mfma_f32_16x16x32_bf16 v[4:7], v[158:161], v[220:223], v[4:7]
	v_mfma_f32_16x16x32_bf16 v[0:3], v[170:173], v[220:223], v[0:3]
	s_setprio 0
	s_barrier
	s_add_i32 s60, s60, 2
	s_add_u32 s26, s26, 0x100
	s_addc_u32 s27, s27, 0
	s_add_u32 s58, s58, 0x100
	s_addc_u32 s59, s59, 0
	s_cmp_gt_u32 s60, 29
	s_cbranch_scc0 .LBB0_598
	s_and_b64 vcc, exec, s[14:15]
	s_cbranch_vccz .LBB0_601
	s_barrier

; #define PG8_STAGE(bufoff, gbase, voff) do { _Pragma("unroll") for (int _i = 0; _i < 2; ++_i) \
;         __builtin_amdgcn_global_load_lds((const unsigned*)((const char*)(gbase) + (voff)[_i]), (LAS unsigned*)(lds + (bufoff) + ldsw + _i * 8192), 16, 0, 0); } while (0)
; #define PG8_LDA(dst, b, h) do { _Pragma("unroll") for (int m = 0; m < 4; ++m) _Pragma("unroll") for (int k = 0; k < 2; ++k) dst[m][k] = *(const LAS bf16x8*)(lds + PG8_SA(b, h) + aoff + m * 2048 + k * 1024); } while (0)
; #define PG8_LDB(dst, b, h) do { _Pragma("unroll") for (int n = 0; n < 2; ++n) _Pragma("unroll") for (int k = 0; k < 2; ++k) dst[n][k] = *(const LAS bf16x8*)(lds + PG8_SB(b, h) + boff + n * 2048 + k * 1024); } while (0)
; #define PG8_WAIT_V(n) asm volatile("s_waitcnt vmcnt(" #n ")" ::: "memory")
; #define PG8_WAIT_L(n) asm volatile("s_waitcnt lgkmcnt(" #n ")" ::: "memory")
; #define PG8_BAR __builtin_amdgcn_s_barrier()
; #define PG8_SCHED __builtin_amdgcn_sched_barrier(0)
; template <bool F16, class Sched, class Epi>
; __device__ __forceinline__ void gemm_phase(LAS unsigned char* lds, const Gemm g, const Sched& S, const Epi& E, int wave_s) {
;     ...
;             const char* a1 = cA + (size_t)(t + 1) * kstep;
;             const char* a2 = last ? nA : cA + (size_t)(t + 2) * kstep; const char* b2 = last ? nB : cB + (size_t)(t + 2) * kstep;
;             const char* a3 = a2 + kstep; const char* b3 = b2 + kstep;
;             PG8_LDB(B0, 0, 0); PG8_LDB(B1, 0, 1); PG8_SCHED; PG8_LDA(At, 0, 0); PG8_STAGE(PG8_SA(1, 1), a1 + hstepA, voffA);
;             PG8_WAIT_V(8); PG8_WAIT_L(0); PG8_BAR; PG8_MMA(0, 0, At, B0); PG8_MMA(0, 1, At, B1); PG8_BAR; PG8_SCHED;
;             PG8_LDA(At, 0, 1); PG8_STAGE(PG8_SB(0, 0), b2, voffB); PG8_STAGE(PG8_SB(0, 1), b2 + hstepB, voffB); PG8_STAGE(PG8_SA(0, 0), a2, voffA);
;             PG8_WAIT_V(8); PG8_WAIT_L(0); PG8_BAR; PG8_MMA(1, 0, At, B0); PG8_MMA(1, 1, At, B1); PG8_BAR; PG8_SCHED;
.LBB0_681:
	s_add_i32 s61, 0, 0x10000
	v_add_u32_e32 v146, s61, v149
	s_add_i32 s64, 0, 0x14000
	ds_read_b128 v[138:141], v146
	ds_read_b128 v[142:145], v146 offset:1024
	ds_read_b128 v[154:157], v146 offset:2048
	ds_read_b128 v[158:161], v146 offset:3072
	v_add_u32_e32 v146, s64, v149
	ds_read_b128 v[162:165], v146
	ds_read_b128 v[166:169], v146 offset:1024
	ds_read_b128 v[170:173], v146 offset:2048
	ds_read_b128 v[178:181], v146 offset:3072
	s_add_i32 m0, s39, 0xc000
	ds_read_b128 v[182:185], v152
	ds_read_b128 v[186:189], v152 offset:1024
	ds_read_b128 v[190:193], v152 offset:2048
	ds_read_b128 v[208:211], v152 offset:3072
	ds_read_b128 v[212:215], v152 offset:4096
	ds_read_b128 v[216:219], v152 offset:5120
	ds_read_b128 v[220:223], v152 offset:6144
	ds_read_b128 v[224:227], v152 offset:7168
	global_load_lds_dwordx4 v134, s[24:25]
	s_add_i32 m0, s39, 0xe000
	s_nop 0
	global_load_lds_dwordx4 v136, s[24:25]
	s_waitcnt vmcnt(8)
	s_waitcnt lgkmcnt(0)
	s_barrier
	s_setprio 1
	s_waitcnt lgkmcnt(0)
	v_mfma_f32_16x16x32_bf16 v[124:127], v[138:141], v[182:185], v[124:127]
	v_mfma_f32_16x16x32_bf16 v[116:119], v[154:157], v[182:185], v[116:119]
	v_mfma_f32_16x16x32_bf16 v[108:111], v[138:141], v[190:193], v[108:111]
	v_mfma_f32_16x16x32_bf16 v[100:103], v[154:157], v[190:193], v[100:103]
	v_mfma_f32_16x16x32_bf16 v[92:95], v[138:141], v[212:215], v[92:95]
	v_mfma_f32_16x16x32_bf16 v[84:87], v[154:157], v[212:215], v[84:87]
	v_mfma_f32_16x16x32_bf16 v[76:79], v[138:141], v[220:223], v[76:79]
	v_mfma_f32_16x16x32_bf16 v[68:71], v[154:157], v[220:223], v[68:71]
	v_mfma_f32_16x16x32_bf16 v[124:127], v[142:145], v[186:189], v[124:127]
	v_mfma_f32_16x16x32_bf16 v[116:119], v[158:161], v[186:189], v[116:119]
	v_mfma_f32_16x16x32_bf16 v[108:111], v[142:145], v[208:211], v[108:111]
	v_mfma_f32_16x16x32_bf16 v[100:103], v[158:161], v[208:211], v[100:103]
	v_mfma_f32_16x16x32_bf16 v[92:95], v[142:145], v[216:219], v[92:95]
	v_mfma_f32_16x16x32_bf16 v[84:87], v[158:161], v[216:219], v[84:87]
	v_mfma_f32_16x16x32_bf16 v[76:79], v[142:145], v[224:227], v[76:79]
	v_mfma_f32_16x16x32_bf16 v[68:71], v[158:161], v[224:227], v[68:71]
	s_setprio 0
	s_setprio 1
	v_mfma_f32_16x16x32_bf16 v[120:123], v[162:165], v[182:185], v[120:123]
	v_mfma_f32_16x16x32_bf16 v[112:115], v[170:173], v[182:185], v[112:115]
	v_mfma_f32_16x16x32_bf16 v[104:107], v[162:165], v[190:193], v[104:107]
	v_mfma_f32_16x16x32_bf16 v[96:99], v[170:173], v[190:193], v[96:99]
	v_mfma_f32_16x16x32_bf16 v[88:91], v[162:165], v[212:215], v[88:91]
	v_mfma_f32_16x16x32_bf16 v[80:83], v[170:173], v[212:215], v[80:83]
	v_mfma_f32_16x16x32_bf16 v[72:75], v[162:165], v[220:223], v[72:75]
	v_mfma_f32_16x16x32_bf16 v[64:67], v[170:173], v[220:223], v[64:67]
	v_mfma_f32_16x16x32_bf16 v[120:123], v[166:169], v[186:189], v[120:123]
	v_mfma_f32_16x16x32_bf16 v[112:115], v[178:181], v[186:189], v[112:115]
	v_mfma_f32_16x16x32_bf16 v[104:107], v[166:169], v[208:211], v[104:107]
	v_mfma_f32_16x16x32_bf16 v[96:99], v[178:181], v[208:211], v[96:99]
	v_mfma_f32_16x16x32_bf16 v[88:91], v[166:169], v[216:219], v[88:91]
	v_mfma_f32_16x16x32_bf16 v[80:83], v[178:181], v[216:219], v[80:83]
	v_mfma_f32_16x16x32_bf16 v[72:75], v[166:169], v[224:227], v[72:75]
	v_mfma_f32_16x16x32_bf16 v[64:67], v[178:181], v[224:227], v[64:67]
	s_setprio 0
	s_barrier
	s_add_u32 s26, s24, 0xfff80080
	s_addc_u32 s27, s25, -1
	s_cmp_eq_u32 s60, 28
	s_cselect_b32 s29, s49, s27
	s_cselect_b32 s28, s50, s26
	s_cselect_b32 s27, s52, s59
	s_cselect_b32 s26, s53, s58
	s_add_i32 s61, s61, s38
	v_lshl_add_u64 v[146:147], s[26:27], 0, v[176:177]
	s_mov_b32 m0, s61
	ds_read_b128 v[182:185], v152 offset:16384
	ds_read_b128 v[186:189], v152 offset:17408
	ds_read_b128 v[190:193], v152 offset:18432
	ds_read_b128 v[208:211], v152 offset:19456
	ds_read_b128 v[212:215], v152 offset:20480
	ds_read_b128 v[216:219], v152 offset:21504
	ds_read_b128 v[220:223], v152 offset:22528
	ds_read_b128 v[224:227], v152 offset:23552
	global_load_lds_dwordx4 v[146:147], off
	s_add_i32 m0, s61, 0x2000
	s_add_u32 s62, s26, 0x80000
	v_lshl_add_u64 v[174:175], s[26:27], 0, v[128:129]
	s_addc_u32 s63, s27, 0
	s_add_i32 s61, s64, s38
	global_load_lds_dwordx4 v[174:175], off
	v_lshl_add_u64 v[194:195], s[62:63], 0, v[176:177]
	s_mov_b32 m0, s61
	v_lshl_add_u64 v[198:199], s[28:29], 0, v[130:131]
	global_load_lds_dwordx4 v[194:195], off
	v_lshl_add_u64 v[194:195], s[62:63], 0, v[128:129]
	s_add_i32 m0, s61, 0x2000
	s_nop 0
	global_load_lds_dwordx4 v[194:195], off
	v_lshl_add_u64 v[194:195], s[28:29], 0, v[132:133]
	s_mov_b32 m0, s39
	s_nop 0
	global_load_lds_dwordx4 v[194:195], off
	s_mov_b32 m0, s43
	s_nop 0
	global_load_lds_dwordx4 v[198:199], off
	s_add_u32 s28, s28, 0x80000
	s_addc_u32 s29, s29, 0
	s_waitcnt vmcnt(8)
	s_waitcnt lgkmcnt(0)
	s_barrier
; #define PG8_STAGE(bufoff, gbase, voff) do { _Pragma("unroll") for (int _i = 0; _i < 2; ++_i) \
;         __builtin_amdgcn_global_load_lds((const unsigned*)((const char*)(gbase) + (voff)[_i]), (LAS unsigned*)(lds + (bufoff) + ldsw + _i * 8192), 16, 0, 0); } while (0)
; #define PG8_LDA(dst, b, h) do { _Pragma("unroll") for (int m = 0; m < 4; ++m) _Pragma("unroll") for (int k = 0; k < 2; ++k) dst[m][k] = *(const LAS bf16x8*)(lds + PG8_SA(b, h) + aoff + m * 2048 + k * 1024); } while (0)
; #define PG8_LDB(dst, b, h) do { _Pragma("unroll") for (int n = 0; n < 2; ++n) _Pragma("unroll") for (int k = 0; k < 2; ++k) dst[n][k] = *(const LAS bf16x8*)(lds + PG8_SB(b, h) + boff + n * 2048 + k * 1024); } while (0)
; #define PG8_WAIT_V(n) asm volatile("s_waitcnt vmcnt(" #n ")" ::: "memory")
; #define PG8_WAIT_L(n) asm volatile("s_waitcnt lgkmcnt(" #n ")" ::: "memory")
; #define PG8_BAR __builtin_amdgcn_s_barrier()
; #define PG8_SCHED __builtin_amdgcn_sched_barrier(0)
; template <bool F16, class Sched, class Epi>
; __device__ __forceinline__ void gemm_phase(LAS unsigned char* lds, const Gemm g, const Sched& S, const Epi& E, int wave_s) {
;     ...
;             PG8_WAIT_V(8); PG8_WAIT_L(0); PG8_BAR; PG8_MMA(1, 0, At, B0); PG8_MMA(1, 1, At, B1); PG8_BAR; PG8_SCHED;
;             PG8_LDB(B0, 1, 0); PG8_LDB(B1, 1, 1); PG8_SCHED; PG8_LDA(At, 1, 0); PG8_STAGE(PG8_SA(0, 1), a2 + hstepA, voffA);
;             PG8_WAIT_V(8); PG8_WAIT_L(0); PG8_BAR; PG8_MMA(0, 0, At, B0); PG8_MMA(0, 1, At, B1); PG8_BAR; PG8_SCHED;
	s_setprio 1
	s_waitcnt lgkmcnt(0)
	v_mfma_f32_16x16x32_bf16 v[60:63], v[138:141], v[182:185], v[60:63]
	v_mfma_f32_16x16x32_bf16 v[52:55], v[154:157], v[182:185], v[52:55]
	v_mfma_f32_16x16x32_bf16 v[44:47], v[138:141], v[190:193], v[44:47]
	v_mfma_f32_16x16x32_bf16 v[36:39], v[154:157], v[190:193], v[36:39]
	v_mfma_f32_16x16x32_bf16 v[28:31], v[138:141], v[212:215], v[28:31]
	v_mfma_f32_16x16x32_bf16 v[20:23], v[154:157], v[212:215], v[20:23]
	v_mfma_f32_16x16x32_bf16 v[12:15], v[138:141], v[220:223], v[12:15]
	v_mfma_f32_16x16x32_bf16 v[4:7], v[154:157], v[220:223], v[4:7]
	v_mfma_f32_16x16x32_bf16 v[60:63], v[142:145], v[186:189], v[60:63]
	v_mfma_f32_16x16x32_bf16 v[52:55], v[158:161], v[186:189], v[52:55]
	v_mfma_f32_16x16x32_bf16 v[44:47], v[142:145], v[208:211], v[44:47]
	v_mfma_f32_16x16x32_bf16 v[36:39], v[158:161], v[208:211], v[36:39]
	v_mfma_f32_16x16x32_bf16 v[28:31], v[142:145], v[216:219], v[28:31]
	v_mfma_f32_16x16x32_bf16 v[20:23], v[158:161], v[216:219], v[20:23]
	v_mfma_f32_16x16x32_bf16 v[12:15], v[142:145], v[224:227], v[12:15]
	v_mfma_f32_16x16x32_bf16 v[4:7], v[158:161], v[224:227], v[4:7]
	s_setprio 0
	s_setprio 1
	v_mfma_f32_16x16x32_bf16 v[56:59], v[162:165], v[182:185], v[56:59]
	v_mfma_f32_16x16x32_bf16 v[48:51], v[170:173], v[182:185], v[48:51]
	v_mfma_f32_16x16x32_bf16 v[40:43], v[162:165], v[190:193], v[40:43]
	v_mfma_f32_16x16x32_bf16 v[32:35], v[170:173], v[190:193], v[32:35]
	v_mfma_f32_16x16x32_bf16 v[24:27], v[162:165], v[212:215], v[24:27]
	v_mfma_f32_16x16x32_bf16 v[16:19], v[170:173], v[212:215], v[16:19]
	v_mfma_f32_16x16x32_bf16 v[8:11], v[162:165], v[220:223], v[8:11]
	v_mfma_f32_16x16x32_bf16 v[0:3], v[170:173], v[220:223], v[0:3]
	v_mfma_f32_16x16x32_bf16 v[56:59], v[166:169], v[186:189], v[56:59]
	v_mfma_f32_16x16x32_bf16 v[48:51], v[178:181], v[186:189], v[48:51]
	v_mfma_f32_16x16x32_bf16 v[40:43], v[166:169], v[208:211], v[40:43]
	v_mfma_f32_16x16x32_bf16 v[32:35], v[178:181], v[208:211], v[32:35]
	v_mfma_f32_16x16x32_bf16 v[24:27], v[166:169], v[216:219], v[24:27]
	v_mfma_f32_16x16x32_bf16 v[16:19], v[178:181], v[216:219], v[16:19]
	v_mfma_f32_16x16x32_bf16 v[8:11], v[166:169], v[224:227], v[8:11]
	v_mfma_f32_16x16x32_bf16 v[0:3], v[178:181], v[224:227], v[0:3]
	s_setprio 0
	s_barrier
	s_add_i32 s61, 0, 0x18000
	v_add_u32_e32 v153, s61, v149
	s_add_i32 s62, 0, 0x1c000
	ds_read_b128 v[138:141], v153
	ds_read_b128 v[142:145], v153 offset:1024
	ds_read_b128 v[154:157], v153 offset:2048
	ds_read_b128 v[158:161], v153 offset:3072
	v_add_u32_e32 v153, s62, v149
	ds_read_b128 v[162:165], v153
	ds_read_b128 v[166:169], v153 offset:1024
	ds_read_b128 v[170:173], v153 offset:2048
	ds_read_b128 v[178:181], v153 offset:3072
	s_mov_b32 m0, s44
	ds_read_b128 v[182:185], v152 offset:32768
	ds_read_b128 v[186:189], v152 offset:33792
	ds_read_b128 v[190:193], v152 offset:34816
	ds_read_b128 v[208:211], v152 offset:35840
	ds_read_b128 v[212:215], v152 offset:36864
	ds_read_b128 v[216:219], v152 offset:37888
	ds_read_b128 v[220:223], v152 offset:38912
	ds_read_b128 v[224:227], v152 offset:39936
	global_load_lds_dwordx4 v132, s[28:29]
	s_mov_b32 m0, s45
	s_nop 0
	global_load_lds_dwordx4 v130, s[28:29]
	s_waitcnt vmcnt(8)
	s_waitcnt lgkmcnt(0)
	s_barrier
	s_setprio 1
	s_waitcnt lgkmcnt(0)
	v_mfma_f32_16x16x32_bf16 v[124:127], v[138:141], v[182:185], v[124:127]
	v_mfma_f32_16x16x32_bf16 v[116:119], v[154:157], v[182:185], v[116:119]
	v_mfma_f32_16x16x32_bf16 v[108:111], v[138:141], v[190:193], v[108:111]
	v_mfma_f32_16x16x32_bf16 v[100:103], v[154:157], v[190:193], v[100:103]
	v_mfma_f32_16x16x32_bf16 v[92:95], v[138:141], v[212:215], v[92:95]
	v_mfma_f32_16x16x32_bf16 v[84:87], v[154:157], v[212:215], v[84:87]
	v_mfma_f32_16x16x32_bf16 v[76:79], v[138:141], v[220:223], v[76:79]
	v_mfma_f32_16x16x32_bf16 v[68:71], v[154:157], v[220:223], v[68:71]
	v_mfma_f32_16x16x32_bf16 v[124:127], v[142:145], v[186:189], v[124:127]
	v_mfma_f32_16x16x32_bf16 v[116:119], v[158:161], v[186:189], v[116:119]
	v_mfma_f32_16x16x32_bf16 v[108:111], v[142:145], v[208:211], v[108:111]
	v_mfma_f32_16x16x32_bf16 v[100:103], v[158:161], v[208:211], v[100:103]
	v_mfma_f32_16x16x32_bf16 v[92:95], v[142:145], v[216:219], v[92:95]
	v_mfma_f32_16x16x32_bf16 v[84:87], v[158:161], v[216:219], v[84:87]
	v_mfma_f32_16x16x32_bf16 v[76:79], v[142:145], v[224:227], v[76:79]
	v_mfma_f32_16x16x32_bf16 v[68:71], v[158:161], v[224:227], v[68:71]
	s_setprio 0
	s_setprio 1
	v_mfma_f32_16x16x32_bf16 v[120:123], v[162:165], v[182:185], v[120:123]
	v_mfma_f32_16x16x32_bf16 v[112:115], v[170:173], v[182:185], v[112:115]
	v_mfma_f32_16x16x32_bf16 v[104:107], v[162:165], v[190:193], v[104:107]
	v_mfma_f32_16x16x32_bf16 v[96:99], v[170:173], v[190:193], v[96:99]
	v_mfma_f32_16x16x32_bf16 v[88:91], v[162:165], v[212:215], v[88:91]
	v_mfma_f32_16x16x32_bf16 v[80:83], v[170:173], v[212:215], v[80:83]
	v_mfma_f32_16x16x32_bf16 v[72:75], v[162:165], v[220:223], v[72:75]
	v_mfma_f32_16x16x32_bf16 v[64:67], v[170:173], v[220:223], v[64:67]
	v_mfma_f32_16x16x32_bf16 v[120:123], v[166:169], v[186:189], v[120:123]
	v_mfma_f32_16x16x32_bf16 v[112:115], v[178:181], v[186:189], v[112:115]
	v_mfma_f32_16x16x32_bf16 v[104:107], v[166:169], v[208:211], v[104:107]
	v_mfma_f32_16x16x32_bf16 v[96:99], v[178:181], v[208:211], v[96:99]
	v_mfma_f32_16x16x32_bf16 v[88:91], v[166:169], v[216:219], v[88:91]
	v_mfma_f32_16x16x32_bf16 v[80:83], v[178:181], v[216:219], v[80:83]
	v_mfma_f32_16x16x32_bf16 v[72:75], v[166:169], v[224:227], v[72:75]
	v_mfma_f32_16x16x32_bf16 v[64:67], v[178:181], v[224:227], v[64:67]
	s_setprio 0
	s_barrier
; #define PG8_STAGE(bufoff, gbase, voff) do { _Pragma("unroll") for (int _i = 0; _i < 2; ++_i) \
;         __builtin_amdgcn_global_load_lds((const unsigned*)((const char*)(gbase) + (voff)[_i]), (LAS unsigned*)(lds + (bufoff) + ldsw + _i * 8192), 16, 0, 0); } while (0)
; #define PG8_LDA(dst, b, h) do { _Pragma("unroll") for (int m = 0; m < 4; ++m) _Pragma("unroll") for (int k = 0; k < 2; ++k) dst[m][k] = *(const LAS bf16x8*)(lds + PG8_SA(b, h) + aoff + m * 2048 + k * 1024); } while (0)
; #define PG8_WAIT_V(n) asm volatile("s_waitcnt vmcnt(" #n ")" ::: "memory")
; #define PG8_WAIT_L(n) asm volatile("s_waitcnt lgkmcnt(" #n ")" ::: "memory")
; #define PG8_BAR __builtin_amdgcn_s_barrier()
; #define PG8_SCHED __builtin_amdgcn_sched_barrier(0)
; template <bool F16, class Sched, class Epi>
; __device__ __forceinline__ void gemm_phase(LAS unsigned char* lds, const Gemm g, const Sched& S, const Epi& E, int wave_s) {
;     ...
;             PG8_LDA(At, 1, 1); PG8_STAGE(PG8_SB(1, 0), b3, voffB); PG8_STAGE(PG8_SB(1, 1), b3 + hstepB, voffB); PG8_STAGE(PG8_SA(1, 0), a3, voffA);
;             PG8_WAIT_V(8); PG8_WAIT_L(0); PG8_BAR; PG8_MMA(1, 0, At, B0); PG8_MMA(1, 1, At, B1); PG8_BAR; PG8_SCHED;
;         }
	s_add_i32 s28, s61, s38
	v_lshl_add_u64 v[146:147], v[146:147], 0, s[54:55]
	s_mov_b32 m0, s28
	ds_read_b128 v[182:185], v152 offset:49152
	ds_read_b128 v[186:189], v152 offset:50176
	ds_read_b128 v[190:193], v152 offset:51200
	ds_read_b128 v[208:211], v152 offset:52224
	ds_read_b128 v[212:215], v152 offset:53248
	ds_read_b128 v[216:219], v152 offset:54272
	ds_read_b128 v[220:223], v152 offset:55296
	ds_read_b128 v[224:227], v152 offset:56320
	global_load_lds_dwordx4 v[146:147], off
	s_add_i32 m0, s28, 0x2000
	s_add_u32 s26, s26, 0x80080
	v_lshl_add_u64 v[146:147], v[174:175], 0, s[54:55]
	s_addc_u32 s27, s27, 0
	s_add_i32 s28, s62, s38
	global_load_lds_dwordx4 v[146:147], off
	v_lshl_add_u64 v[146:147], s[26:27], 0, v[176:177]
	s_mov_b32 m0, s28
	s_nop 0
	global_load_lds_dwordx4 v[146:147], off
	v_lshl_add_u64 v[146:147], s[26:27], 0, v[128:129]
	s_add_i32 m0, s28, 0x2000
	s_nop 0
	global_load_lds_dwordx4 v[146:147], off
	v_lshl_add_u64 v[146:147], v[194:195], 0, s[54:55]
	s_mov_b32 m0, s46
	s_nop 0
	global_load_lds_dwordx4 v[146:147], off
	v_lshl_add_u64 v[146:147], v[198:199], 0, s[54:55]
	s_mov_b32 m0, s47
	s_nop 0
	global_load_lds_dwordx4 v[146:147], off
	s_waitcnt vmcnt(8)
	s_waitcnt lgkmcnt(0)
	s_barrier
	s_setprio 1
	s_waitcnt lgkmcnt(0)
	v_mfma_f32_16x16x32_bf16 v[60:63], v[138:141], v[182:185], v[60:63]
	v_mfma_f32_16x16x32_bf16 v[52:55], v[154:157], v[182:185], v[52:55]
	v_mfma_f32_16x16x32_bf16 v[44:47], v[138:141], v[190:193], v[44:47]
	v_mfma_f32_16x16x32_bf16 v[36:39], v[154:157], v[190:193], v[36:39]
	v_mfma_f32_16x16x32_bf16 v[28:31], v[138:141], v[212:215], v[28:31]
	v_mfma_f32_16x16x32_bf16 v[20:23], v[154:157], v[212:215], v[20:23]
	v_mfma_f32_16x16x32_bf16 v[12:15], v[138:141], v[220:223], v[12:15]
	v_mfma_f32_16x16x32_bf16 v[4:7], v[154:157], v[220:223], v[4:7]
	v_mfma_f32_16x16x32_bf16 v[60:63], v[142:145], v[186:189], v[60:63]
	v_mfma_f32_16x16x32_bf16 v[52:55], v[158:161], v[186:189], v[52:55]
	v_mfma_f32_16x16x32_bf16 v[44:47], v[142:145], v[208:211], v[44:47]
	v_mfma_f32_16x16x32_bf16 v[36:39], v[158:161], v[208:211], v[36:39]
	v_mfma_f32_16x16x32_bf16 v[28:31], v[142:145], v[216:219], v[28:31]
	v_mfma_f32_16x16x32_bf16 v[20:23], v[158:161], v[216:219], v[20:23]
	v_mfma_f32_16x16x32_bf16 v[12:15], v[142:145], v[224:227], v[12:15]
	v_mfma_f32_16x16x32_bf16 v[4:7], v[158:161], v[224:227], v[4:7]
	s_setprio 0
	s_setprio 1
	v_mfma_f32_16x16x32_bf16 v[56:59], v[162:165], v[182:185], v[56:59]
	v_mfma_f32_16x16x32_bf16 v[48:51], v[170:173], v[182:185], v[48:51]
	v_mfma_f32_16x16x32_bf16 v[40:43], v[162:165], v[190:193], v[40:43]
	v_mfma_f32_16x16x32_bf16 v[32:35], v[170:173], v[190:193], v[32:35]
	v_mfma_f32_16x16x32_bf16 v[24:27], v[162:165], v[212:215], v[24:27]
	v_mfma_f32_16x16x32_bf16 v[16:19], v[170:173], v[212:215], v[16:19]
	v_mfma_f32_16x16x32_bf16 v[8:11], v[162:165], v[220:223], v[8:11]
	v_mfma_f32_16x16x32_bf16 v[0:3], v[170:173], v[220:223], v[0:3]
	v_mfma_f32_16x16x32_bf16 v[56:59], v[166:169], v[186:189], v[56:59]
	v_mfma_f32_16x16x32_bf16 v[48:51], v[178:181], v[186:189], v[48:51]
	v_mfma_f32_16x16x32_bf16 v[40:43], v[166:169], v[208:211], v[40:43]
	v_mfma_f32_16x16x32_bf16 v[32:35], v[178:181], v[208:211], v[32:35]
	v_mfma_f32_16x16x32_bf16 v[24:27], v[166:169], v[216:219], v[24:27]
	v_mfma_f32_16x16x32_bf16 v[16:19], v[178:181], v[216:219], v[16:19]
	v_mfma_f32_16x16x32_bf16 v[8:11], v[166:169], v[224:227], v[8:11]
	v_mfma_f32_16x16x32_bf16 v[0:3], v[178:181], v[224:227], v[0:3]
	s_setprio 0
	s_barrier
	s_add_i32 s60, s60, 2
	s_add_u32 s24, s24, 0x100
	s_addc_u32 s25, s25, 0
	s_add_u32 s58, s58, 0x100
	s_addc_u32 s59, s59, 0
	s_cmp_gt_u32 s60, 29
	s_cbranch_scc0 .LBB0_681
	s_and_b64 vcc, exec, s[12:13]
	s_cbranch_vccz .LBB0_684
	s_barrier

; #define PG8_STAGE(bufoff, gbase, voff) do { _Pragma("unroll") for (int _i = 0; _i < 2; ++_i) \
;         __builtin_amdgcn_global_load_lds((const unsigned*)((const char*)(gbase) + (voff)[_i]), (LAS unsigned*)(lds + (bufoff) + ldsw + _i * 8192), 16, 0, 0); } while (0)
; #define PG8_LDA(dst, b, h) do { _Pragma("unroll") for (int m = 0; m < 4; ++m) _Pragma("unroll") for (int k = 0; k < 2; ++k) dst[m][k] = *(const LAS bf16x8*)(lds + PG8_SA(b, h) + aoff + m * 2048 + k * 1024); } while (0)
; #define PG8_LDB(dst, b, h) do { _Pragma("unroll") for (int n = 0; n < 2; ++n) _Pragma("unroll") for (int k = 0; k < 2; ++k) dst[n][k] = *(const LAS bf16x8*)(lds + PG8_SB(b, h) + boff + n * 2048 + k * 1024); } while (0)
; #define PG8_WAIT_V(n) asm volatile("s_waitcnt vmcnt(" #n ")" ::: "memory")
; #define PG8_WAIT_L(n) asm volatile("s_waitcnt lgkmcnt(" #n ")" ::: "memory")
; #define PG8_BAR __builtin_amdgcn_s_barrier()
; #define PG8_SCHED __builtin_amdgcn_sched_barrier(0)
; template <bool F16, class Sched, class Epi>
; __device__ __forceinline__ void gemm_phase(LAS unsigned char* lds, const Gemm g, const Sched& S, const Epi& E, int wave_s) {
;     ...
;             const char* a1 = cA + (size_t)(t + 1) * kstep;
;             const char* a2 = last ? nA : cA + (size_t)(t + 2) * kstep; const char* b2 = last ? nB : cB + (size_t)(t + 2) * kstep;
;             const char* a3 = a2 + kstep; const char* b3 = b2 + kstep;
;             PG8_LDB(B0, 0, 0); PG8_LDB(B1, 0, 1); PG8_SCHED; PG8_LDA(At, 0, 0); PG8_STAGE(PG8_SA(1, 1), a1 + hstepA, voffA);
;             PG8_WAIT_V(8); PG8_WAIT_L(0); PG8_BAR; PG8_MMA(0, 0, At, B0); PG8_MMA(0, 1, At, B1); PG8_BAR; PG8_SCHED;
;             PG8_LDA(At, 0, 1); PG8_STAGE(PG8_SB(0, 0), b2, voffB); PG8_STAGE(PG8_SB(0, 1), b2 + hstepB, voffB); PG8_STAGE(PG8_SA(0, 0), a2, voffA);
;             PG8_WAIT_V(8); PG8_WAIT_L(0); PG8_BAR; PG8_MMA(1, 0, At, B0); PG8_MMA(1, 1, At, B1); PG8_BAR; PG8_SCHED;
.LBB0_795:
	s_add_i32 s64, 0, 0x10000
	s_add_i32 s65, 0, 0x14000
	v_add_u32_e32 v150, s64, v163
	v_add_u32_e32 v170, s65, v163
	ds_read_b128 v[138:141], v150
	ds_read_b128 v[142:145], v150 offset:1024
	ds_read_b128 v[146:149], v150 offset:2048
	ds_read_b128 v[150:153], v150 offset:3072
	ds_read_b128 v[154:157], v170
	ds_read_b128 v[158:161], v170 offset:1024
	ds_read_b128 v[166:169], v170 offset:2048
	ds_read_b128 v[170:173], v170 offset:3072
	v_lshl_add_u64 v[174:175], s[28:29], 0, v[134:135]
	s_add_i32 m0, s46, 0xc000
	ds_read_b128 v[178:181], v165
	ds_read_b128 v[182:185], v165 offset:1024
	ds_read_b128 v[186:189], v165 offset:2048
	ds_read_b128 v[190:193], v165 offset:3072
	ds_read_b128 v[198:201], v165 offset:4096
	ds_read_b128 v[208:211], v165 offset:5120
	ds_read_b128 v[212:215], v165 offset:6144
	ds_read_b128 v[216:219], v165 offset:7168
	global_load_lds_dwordx4 v[174:175], off
	v_lshl_add_u64 v[174:175], s[28:29], 0, v[136:137]
	s_add_i32 m0, s46, 0xe000
	s_nop 0
	global_load_lds_dwordx4 v[174:175], off
	s_waitcnt vmcnt(8)
	s_waitcnt lgkmcnt(0)
	s_barrier
	s_setprio 1
	s_waitcnt lgkmcnt(0)
	v_mfma_f32_16x16x32_bf16 v[124:127], v[138:141], v[178:181], v[124:127]
	v_mfma_f32_16x16x32_bf16 v[120:123], v[146:149], v[178:181], v[120:123]
	v_mfma_f32_16x16x32_bf16 v[108:111], v[138:141], v[186:189], v[108:111]
	v_mfma_f32_16x16x32_bf16 v[104:107], v[146:149], v[186:189], v[104:107]
	v_mfma_f32_16x16x32_bf16 v[96:99], v[138:141], v[198:201], v[96:99]
	v_mfma_f32_16x16x32_bf16 v[92:95], v[146:149], v[198:201], v[92:95]
	v_mfma_f32_16x16x32_bf16 v[84:87], v[138:141], v[212:215], v[84:87]
	v_mfma_f32_16x16x32_bf16 v[76:79], v[146:149], v[212:215], v[76:79]
	v_mfma_f32_16x16x32_bf16 v[124:127], v[142:145], v[182:185], v[124:127]
	v_mfma_f32_16x16x32_bf16 v[120:123], v[150:153], v[182:185], v[120:123]
	v_mfma_f32_16x16x32_bf16 v[108:111], v[142:145], v[190:193], v[108:111]
	v_mfma_f32_16x16x32_bf16 v[104:107], v[150:153], v[190:193], v[104:107]
	v_mfma_f32_16x16x32_bf16 v[96:99], v[142:145], v[208:211], v[96:99]
	v_mfma_f32_16x16x32_bf16 v[92:95], v[150:153], v[208:211], v[92:95]
	v_mfma_f32_16x16x32_bf16 v[84:87], v[142:145], v[216:219], v[84:87]
	v_mfma_f32_16x16x32_bf16 v[76:79], v[150:153], v[216:219], v[76:79]
	s_setprio 0
	s_setprio 1
	v_mfma_f32_16x16x32_bf16 v[116:119], v[154:157], v[178:181], v[116:119]
	v_mfma_f32_16x16x32_bf16 v[112:115], v[166:169], v[178:181], v[112:115]
	v_mfma_f32_16x16x32_bf16 v[100:103], v[154:157], v[186:189], v[100:103]
	v_mfma_f32_16x16x32_bf16 v[88:91], v[166:169], v[186:189], v[88:91]
	v_mfma_f32_16x16x32_bf16 v[80:83], v[154:157], v[198:201], v[80:83]
	v_mfma_f32_16x16x32_bf16 v[72:75], v[166:169], v[198:201], v[72:75]
	v_mfma_f32_16x16x32_bf16 v[68:71], v[154:157], v[212:215], v[68:71]
	v_mfma_f32_16x16x32_bf16 v[64:67], v[166:169], v[212:215], v[64:67]
	v_mfma_f32_16x16x32_bf16 v[116:119], v[158:161], v[182:185], v[116:119]
	v_mfma_f32_16x16x32_bf16 v[112:115], v[170:173], v[182:185], v[112:115]
	v_mfma_f32_16x16x32_bf16 v[100:103], v[158:161], v[190:193], v[100:103]
	v_mfma_f32_16x16x32_bf16 v[88:91], v[170:173], v[190:193], v[88:91]
	v_mfma_f32_16x16x32_bf16 v[80:83], v[158:161], v[208:211], v[80:83]
	v_mfma_f32_16x16x32_bf16 v[72:75], v[170:173], v[208:211], v[72:75]
	v_mfma_f32_16x16x32_bf16 v[68:71], v[158:161], v[216:219], v[68:71]
	v_mfma_f32_16x16x32_bf16 v[64:67], v[170:173], v[216:219], v[64:67]
	s_setprio 0
	s_barrier
	s_add_u32 s30, s28, 0x100
	s_addc_u32 s31, s29, 0
	s_cmpk_eq_i32 s63, 0x54
	s_cselect_b32 s37, s15, s31
	s_cselect_b32 s36, s14, s30
	s_cselect_b32 s35, s27, s1
	s_cselect_b32 s34, s26, s0
	s_add_i32 s28, s64, s45
	v_lshl_add_u64 v[174:175], s[34:35], 0, v[176:177]
	s_mov_b32 m0, s28
	ds_read_b128 v[178:181], v165 offset:16384
	ds_read_b128 v[182:185], v165 offset:17408
	ds_read_b128 v[186:189], v165 offset:18432
	ds_read_b128 v[190:193], v165 offset:19456
	ds_read_b128 v[198:201], v165 offset:20480
	ds_read_b128 v[208:211], v165 offset:21504
	ds_read_b128 v[212:215], v165 offset:22528
	ds_read_b128 v[216:219], v165 offset:23552
	global_load_lds_dwordx4 v[174:175], off
	s_add_i32 m0, s28, 0x2000
	s_add_u32 s28, s34, 0x160000
	v_lshl_add_u64 v[194:195], s[34:35], 0, v[128:129]
	s_addc_u32 s29, s35, 0
	s_add_i32 s64, s65, s45
	global_load_lds_dwordx4 v[194:195], off
	v_lshl_add_u64 v[202:203], s[28:29], 0, v[176:177]
	s_mov_b32 m0, s64
	v_lshl_add_u64 v[220:221], s[36:37], 0, v[130:131]
	global_load_lds_dwordx4 v[202:203], off
	v_lshl_add_u64 v[202:203], s[28:29], 0, v[128:129]
	s_add_i32 m0, s64, 0x2000
	s_nop 0
	global_load_lds_dwordx4 v[202:203], off
	v_lshl_add_u64 v[202:203], s[36:37], 0, v[132:133]
	s_mov_b32 m0, s46
	s_nop 0
	global_load_lds_dwordx4 v[202:203], off
	s_mov_b32 m0, s47
	s_nop 0
	global_load_lds_dwordx4 v[220:221], off
	s_add_u32 s28, s36, 0x160000
	s_addc_u32 s29, s37, 0
	s_waitcnt vmcnt(8)
	s_waitcnt lgkmcnt(0)
	s_barrier
; #define PG8_STAGE(bufoff, gbase, voff) do { _Pragma("unroll") for (int _i = 0; _i < 2; ++_i) \
;         __builtin_amdgcn_global_load_lds((const unsigned*)((const char*)(gbase) + (voff)[_i]), (LAS unsigned*)(lds + (bufoff) + ldsw + _i * 8192), 16, 0, 0); } while (0)
; #define PG8_LDA(dst, b, h) do { _Pragma("unroll") for (int m = 0; m < 4; ++m) _Pragma("unroll") for (int k = 0; k < 2; ++k) dst[m][k] = *(const LAS bf16x8*)(lds + PG8_SA(b, h) + aoff + m * 2048 + k * 1024); } while (0)
; #define PG8_LDB(dst, b, h) do { _Pragma("unroll") for (int n = 0; n < 2; ++n) _Pragma("unroll") for (int k = 0; k < 2; ++k) dst[n][k] = *(const LAS bf16x8*)(lds + PG8_SB(b, h) + boff + n * 2048 + k * 1024); } while (0)
; #define PG8_WAIT_V(n) asm volatile("s_waitcnt vmcnt(" #n ")" ::: "memory")
; #define PG8_WAIT_L(n) asm volatile("s_waitcnt lgkmcnt(" #n ")" ::: "memory")
; #define PG8_BAR __builtin_amdgcn_s_barrier()
; #define PG8_SCHED __builtin_amdgcn_sched_barrier(0)
; template <bool F16, class Sched, class Epi>
; __device__ __forceinline__ void gemm_phase(LAS unsigned char* lds, const Gemm g, const Sched& S, const Epi& E, int wave_s) {
;     ...
;             PG8_WAIT_V(8); PG8_WAIT_L(0); PG8_BAR; PG8_MMA(1, 0, At, B0); PG8_MMA(1, 1, At, B1); PG8_BAR; PG8_SCHED;
;             PG8_LDB(B0, 1, 0); PG8_LDB(B1, 1, 1); PG8_SCHED; PG8_LDA(At, 1, 0); PG8_STAGE(PG8_SA(0, 1), a2 + hstepA, voffA);
;             PG8_WAIT_V(8); PG8_WAIT_L(0); PG8_BAR; PG8_MMA(0, 0, At, B0); PG8_MMA(0, 1, At, B1); PG8_BAR; PG8_SCHED;
	s_setprio 1
	s_waitcnt lgkmcnt(0)
	v_mfma_f32_16x16x32_bf16 v[60:63], v[138:141], v[178:181], v[60:63]
	v_mfma_f32_16x16x32_bf16 v[56:59], v[146:149], v[178:181], v[56:59]
	v_mfma_f32_16x16x32_bf16 v[52:55], v[138:141], v[186:189], v[52:55]
	v_mfma_f32_16x16x32_bf16 v[44:47], v[146:149], v[186:189], v[44:47]
	v_mfma_f32_16x16x32_bf16 v[36:39], v[138:141], v[198:201], v[36:39]
	v_mfma_f32_16x16x32_bf16 v[28:31], v[146:149], v[198:201], v[28:31]
	v_mfma_f32_16x16x32_bf16 v[20:23], v[138:141], v[212:215], v[20:23]
	v_mfma_f32_16x16x32_bf16 v[12:15], v[146:149], v[212:215], v[12:15]
	v_mfma_f32_16x16x32_bf16 v[60:63], v[142:145], v[182:185], v[60:63]
	v_mfma_f32_16x16x32_bf16 v[56:59], v[150:153], v[182:185], v[56:59]
	v_mfma_f32_16x16x32_bf16 v[52:55], v[142:145], v[190:193], v[52:55]
	v_mfma_f32_16x16x32_bf16 v[44:47], v[150:153], v[190:193], v[44:47]
	v_mfma_f32_16x16x32_bf16 v[36:39], v[142:145], v[208:211], v[36:39]
	v_mfma_f32_16x16x32_bf16 v[28:31], v[150:153], v[208:211], v[28:31]
	v_mfma_f32_16x16x32_bf16 v[20:23], v[142:145], v[216:219], v[20:23]
	v_mfma_f32_16x16x32_bf16 v[12:15], v[150:153], v[216:219], v[12:15]
	s_setprio 0
	s_setprio 1
	v_mfma_f32_16x16x32_bf16 v[48:51], v[154:157], v[178:181], v[48:51]
	v_mfma_f32_16x16x32_bf16 v[40:43], v[166:169], v[178:181], v[40:43]
	v_mfma_f32_16x16x32_bf16 v[32:35], v[154:157], v[186:189], v[32:35]
	v_mfma_f32_16x16x32_bf16 v[24:27], v[166:169], v[186:189], v[24:27]
	v_mfma_f32_16x16x32_bf16 v[16:19], v[154:157], v[198:201], v[16:19]
	v_mfma_f32_16x16x32_bf16 v[8:11], v[166:169], v[198:201], v[8:11]
	v_mfma_f32_16x16x32_bf16 v[4:7], v[154:157], v[212:215], v[4:7]
	v_mfma_f32_16x16x32_bf16 v[0:3], v[166:169], v[212:215], v[0:3]
	v_mfma_f32_16x16x32_bf16 v[48:51], v[158:161], v[182:185], v[48:51]
	v_mfma_f32_16x16x32_bf16 v[40:43], v[170:173], v[182:185], v[40:43]
	v_mfma_f32_16x16x32_bf16 v[32:35], v[158:161], v[190:193], v[32:35]
	v_mfma_f32_16x16x32_bf16 v[24:27], v[170:173], v[190:193], v[24:27]
	v_mfma_f32_16x16x32_bf16 v[16:19], v[158:161], v[208:211], v[16:19]
	v_mfma_f32_16x16x32_bf16 v[8:11], v[170:173], v[208:211], v[8:11]
	v_mfma_f32_16x16x32_bf16 v[4:7], v[158:161], v[216:219], v[4:7]
	v_mfma_f32_16x16x32_bf16 v[0:3], v[170:173], v[216:219], v[0:3]
	s_setprio 0
	s_barrier
	s_add_i32 s64, 0, 0x18000
	s_add_i32 s65, 0, 0x1c000
	v_add_u32_e32 v150, s64, v163
	v_add_u32_e32 v170, s65, v163
	ds_read_b128 v[138:141], v150
	ds_read_b128 v[142:145], v150 offset:1024
	ds_read_b128 v[146:149], v150 offset:2048
	ds_read_b128 v[150:153], v150 offset:3072
	ds_read_b128 v[154:157], v170
	ds_read_b128 v[158:161], v170 offset:1024
	ds_read_b128 v[166:169], v170 offset:2048
	ds_read_b128 v[170:173], v170 offset:3072
	s_mov_b32 m0, s48
	ds_read_b128 v[178:181], v165 offset:32768
	ds_read_b128 v[182:185], v165 offset:33792
	ds_read_b128 v[186:189], v165 offset:34816
	ds_read_b128 v[190:193], v165 offset:35840
	ds_read_b128 v[198:201], v165 offset:36864
	ds_read_b128 v[208:211], v165 offset:37888
	ds_read_b128 v[212:215], v165 offset:38912
	ds_read_b128 v[216:219], v165 offset:39936
	global_load_lds_dwordx4 v132, s[28:29]
	s_mov_b32 m0, s49
	s_nop 0
	global_load_lds_dwordx4 v130, s[28:29]
	s_waitcnt vmcnt(8)
	s_waitcnt lgkmcnt(0)
	s_barrier
	s_setprio 1
	s_waitcnt lgkmcnt(0)
	v_mfma_f32_16x16x32_bf16 v[124:127], v[138:141], v[178:181], v[124:127]
	v_mfma_f32_16x16x32_bf16 v[120:123], v[146:149], v[178:181], v[120:123]
	v_mfma_f32_16x16x32_bf16 v[108:111], v[138:141], v[186:189], v[108:111]
	v_mfma_f32_16x16x32_bf16 v[104:107], v[146:149], v[186:189], v[104:107]
	v_mfma_f32_16x16x32_bf16 v[96:99], v[138:141], v[198:201], v[96:99]
	v_mfma_f32_16x16x32_bf16 v[92:95], v[146:149], v[198:201], v[92:95]
	v_mfma_f32_16x16x32_bf16 v[84:87], v[138:141], v[212:215], v[84:87]
	v_mfma_f32_16x16x32_bf16 v[76:79], v[146:149], v[212:215], v[76:79]
	v_mfma_f32_16x16x32_bf16 v[124:127], v[142:145], v[182:185], v[124:127]
	v_mfma_f32_16x16x32_bf16 v[120:123], v[150:153], v[182:185], v[120:123]
	v_mfma_f32_16x16x32_bf16 v[108:111], v[142:145], v[190:193], v[108:111]
	v_mfma_f32_16x16x32_bf16 v[104:107], v[150:153], v[190:193], v[104:107]
	v_mfma_f32_16x16x32_bf16 v[96:99], v[142:145], v[208:211], v[96:99]
	v_mfma_f32_16x16x32_bf16 v[92:95], v[150:153], v[208:211], v[92:95]
	v_mfma_f32_16x16x32_bf16 v[84:87], v[142:145], v[216:219], v[84:87]
	v_mfma_f32_16x16x32_bf16 v[76:79], v[150:153], v[216:219], v[76:79]
	s_setprio 0
	s_setprio 1
	v_mfma_f32_16x16x32_bf16 v[116:119], v[154:157], v[178:181], v[116:119]
	v_mfma_f32_16x16x32_bf16 v[112:115], v[166:169], v[178:181], v[112:115]
	v_mfma_f32_16x16x32_bf16 v[100:103], v[154:157], v[186:189], v[100:103]
	v_mfma_f32_16x16x32_bf16 v[88:91], v[166:169], v[186:189], v[88:91]
	v_mfma_f32_16x16x32_bf16 v[80:83], v[154:157], v[198:201], v[80:83]
	v_mfma_f32_16x16x32_bf16 v[72:75], v[166:169], v[198:201], v[72:75]
	v_mfma_f32_16x16x32_bf16 v[68:71], v[154:157], v[212:215], v[68:71]
	v_mfma_f32_16x16x32_bf16 v[64:67], v[166:169], v[212:215], v[64:67]
	v_mfma_f32_16x16x32_bf16 v[116:119], v[158:161], v[182:185], v[116:119]
	v_mfma_f32_16x16x32_bf16 v[112:115], v[170:173], v[182:185], v[112:115]
	v_mfma_f32_16x16x32_bf16 v[100:103], v[158:161], v[190:193], v[100:103]
	v_mfma_f32_16x16x32_bf16 v[88:91], v[170:173], v[190:193], v[88:91]
	v_mfma_f32_16x16x32_bf16 v[80:83], v[158:161], v[208:211], v[80:83]
	v_mfma_f32_16x16x32_bf16 v[72:75], v[170:173], v[208:211], v[72:75]
	v_mfma_f32_16x16x32_bf16 v[68:71], v[158:161], v[216:219], v[68:71]
	v_mfma_f32_16x16x32_bf16 v[64:67], v[170:173], v[216:219], v[64:67]
	s_setprio 0
	s_barrier
; #define PG8_STAGE(bufoff, gbase, voff) do { _Pragma("unroll") for (int _i = 0; _i < 2; ++_i) \
;         __builtin_amdgcn_global_load_lds((const unsigned*)((const char*)(gbase) + (voff)[_i]), (LAS unsigned*)(lds + (bufoff) + ldsw + _i * 8192), 16, 0, 0); } while (0)
; #define PG8_LDA(dst, b, h) do { _Pragma("unroll") for (int m = 0; m < 4; ++m) _Pragma("unroll") for (int k = 0; k < 2; ++k) dst[m][k] = *(const LAS bf16x8*)(lds + PG8_SA(b, h) + aoff + m * 2048 + k * 1024); } while (0)
; #define PG8_WAIT_V(n) asm volatile("s_waitcnt vmcnt(" #n ")" ::: "memory")
; #define PG8_WAIT_L(n) asm volatile("s_waitcnt lgkmcnt(" #n ")" ::: "memory")
; #define PG8_BAR __builtin_amdgcn_s_barrier()
; #define PG8_SCHED __builtin_amdgcn_sched_barrier(0)
; template <bool F16, class Sched, class Epi>
; __device__ __forceinline__ void gemm_phase(LAS unsigned char* lds, const Gemm g, const Sched& S, const Epi& E, int wave_s) {
;     ...
;             PG8_LDA(At, 1, 1); PG8_STAGE(PG8_SB(1, 0), b3, voffB); PG8_STAGE(PG8_SB(1, 1), b3 + hstepB, voffB); PG8_STAGE(PG8_SA(1, 0), a3, voffA);
;             PG8_WAIT_V(8); PG8_WAIT_L(0); PG8_BAR; PG8_MMA(1, 0, At, B0); PG8_MMA(1, 1, At, B1); PG8_BAR; PG8_SCHED;
;         }
	s_add_i32 s28, s64, s45
	v_lshl_add_u64 v[174:175], v[174:175], 0, s[54:55]
	s_mov_b32 m0, s28
	ds_read_b128 v[178:181], v165 offset:49152
	ds_read_b128 v[182:185], v165 offset:50176
	ds_read_b128 v[186:189], v165 offset:51200
	ds_read_b128 v[190:193], v165 offset:52224
	ds_read_b128 v[198:201], v165 offset:53248
	ds_read_b128 v[208:211], v165 offset:54272
	ds_read_b128 v[212:215], v165 offset:55296
	ds_read_b128 v[216:219], v165 offset:56320
	global_load_lds_dwordx4 v[174:175], off
	s_add_i32 m0, s28, 0x2000
	s_add_u32 s28, s34, 0x160080
	v_lshl_add_u64 v[174:175], v[194:195], 0, s[54:55]
	s_addc_u32 s29, s35, 0
	s_add_i32 s34, s65, s45
	global_load_lds_dwordx4 v[174:175], off
	v_lshl_add_u64 v[174:175], s[28:29], 0, v[176:177]
	s_mov_b32 m0, s34
	s_nop 0
	global_load_lds_dwordx4 v[174:175], off
	v_lshl_add_u64 v[174:175], s[28:29], 0, v[128:129]
	s_add_i32 m0, s34, 0x2000
	s_nop 0
	global_load_lds_dwordx4 v[174:175], off
	v_lshl_add_u64 v[174:175], v[202:203], 0, s[54:55]
	s_mov_b32 m0, s52
	s_nop 0
	global_load_lds_dwordx4 v[174:175], off
	v_lshl_add_u64 v[174:175], v[220:221], 0, s[54:55]
	s_mov_b32 m0, s53
	s_nop 0
	global_load_lds_dwordx4 v[174:175], off
	s_waitcnt vmcnt(8)
	s_waitcnt lgkmcnt(0)
	s_barrier
	s_setprio 1
	s_waitcnt lgkmcnt(0)
	v_mfma_f32_16x16x32_bf16 v[60:63], v[138:141], v[178:181], v[60:63]
	v_mfma_f32_16x16x32_bf16 v[56:59], v[146:149], v[178:181], v[56:59]
	v_mfma_f32_16x16x32_bf16 v[52:55], v[138:141], v[186:189], v[52:55]
	v_mfma_f32_16x16x32_bf16 v[44:47], v[146:149], v[186:189], v[44:47]
	v_mfma_f32_16x16x32_bf16 v[36:39], v[138:141], v[198:201], v[36:39]
	v_mfma_f32_16x16x32_bf16 v[28:31], v[146:149], v[198:201], v[28:31]
	v_mfma_f32_16x16x32_bf16 v[20:23], v[138:141], v[212:215], v[20:23]
	v_mfma_f32_16x16x32_bf16 v[12:15], v[146:149], v[212:215], v[12:15]
	v_mfma_f32_16x16x32_bf16 v[60:63], v[142:145], v[182:185], v[60:63]
	v_mfma_f32_16x16x32_bf16 v[56:59], v[150:153], v[182:185], v[56:59]
	v_mfma_f32_16x16x32_bf16 v[52:55], v[142:145], v[190:193], v[52:55]
	v_mfma_f32_16x16x32_bf16 v[44:47], v[150:153], v[190:193], v[44:47]
	v_mfma_f32_16x16x32_bf16 v[36:39], v[142:145], v[208:211], v[36:39]
	v_mfma_f32_16x16x32_bf16 v[28:31], v[150:153], v[208:211], v[28:31]
	v_mfma_f32_16x16x32_bf16 v[20:23], v[142:145], v[216:219], v[20:23]
	v_mfma_f32_16x16x32_bf16 v[12:15], v[150:153], v[216:219], v[12:15]
	s_setprio 0
	s_setprio 1
	v_mfma_f32_16x16x32_bf16 v[48:51], v[154:157], v[178:181], v[48:51]
	v_mfma_f32_16x16x32_bf16 v[40:43], v[166:169], v[178:181], v[40:43]
	v_mfma_f32_16x16x32_bf16 v[32:35], v[154:157], v[186:189], v[32:35]
	v_mfma_f32_16x16x32_bf16 v[24:27], v[166:169], v[186:189], v[24:27]
	v_mfma_f32_16x16x32_bf16 v[16:19], v[154:157], v[198:201], v[16:19]
	v_mfma_f32_16x16x32_bf16 v[8:11], v[166:169], v[198:201], v[8:11]
	v_mfma_f32_16x16x32_bf16 v[4:7], v[154:157], v[212:215], v[4:7]
	v_mfma_f32_16x16x32_bf16 v[0:3], v[166:169], v[212:215], v[0:3]
	v_mfma_f32_16x16x32_bf16 v[48:51], v[158:161], v[182:185], v[48:51]
	v_mfma_f32_16x16x32_bf16 v[40:43], v[170:173], v[182:185], v[40:43]
	v_mfma_f32_16x16x32_bf16 v[32:35], v[158:161], v[190:193], v[32:35]
	v_mfma_f32_16x16x32_bf16 v[24:27], v[170:173], v[190:193], v[24:27]
	v_mfma_f32_16x16x32_bf16 v[16:19], v[158:161], v[208:211], v[16:19]
	v_mfma_f32_16x16x32_bf16 v[8:11], v[170:173], v[208:211], v[8:11]
	v_mfma_f32_16x16x32_bf16 v[4:7], v[158:161], v[216:219], v[4:7]
	v_mfma_f32_16x16x32_bf16 v[0:3], v[170:173], v[216:219], v[0:3]
	s_setprio 0
	s_barrier
	s_add_i32 s63, s63, 2
	s_add_u32 s0, s0, 0x100
	s_addc_u32 s1, s1, 0
	s_cmpk_gt_u32 s63, 0x55
	s_mov_b64 s[28:29], s[30:31]
	s_cbranch_scc0 .LBB0_795
	s_and_b64 vcc, exec, s[12:13]
	s_cbranch_vccz .LBB0_798
	s_barrier

; #define PG8_STAGE(bufoff, gbase, voff) do { _Pragma("unroll") for (int _i = 0; _i < 2; ++_i) \
;         __builtin_amdgcn_global_load_lds((const unsigned*)((const char*)(gbase) + (voff)[_i]), (LAS unsigned*)(lds + (bufoff) + ldsw + _i * 8192), 16, 0, 0); } while (0)
; #define PG8_LDA(dst, b, h) do { _Pragma("unroll") for (int m = 0; m < 4; ++m) _Pragma("unroll") for (int k = 0; k < 2; ++k) dst[m][k] = *(const LAS bf16x8*)(lds + PG8_SA(b, h) + aoff + m * 2048 + k * 1024); } while (0)
; #define PG8_LDB(dst, b, h) do { _Pragma("unroll") for (int n = 0; n < 2; ++n) _Pragma("unroll") for (int k = 0; k < 2; ++k) dst[n][k] = *(const LAS bf16x8*)(lds + PG8_SB(b, h) + boff + n * 2048 + k * 1024); } while (0)
; #define PG8_WAIT_V(n) asm volatile("s_waitcnt vmcnt(" #n ")" ::: "memory")
; #define PG8_WAIT_L(n) asm volatile("s_waitcnt lgkmcnt(" #n ")" ::: "memory")
; #define PG8_BAR __builtin_amdgcn_s_barrier()
; #define PG8_SCHED __builtin_amdgcn_sched_barrier(0)
; template <bool F16, class Sched, class Epi>
; __device__ __forceinline__ void gemm_phase(LAS unsigned char* lds, const Gemm g, const Sched& S, const Epi& E, int wave_s) {
;     ...
;             const char* a1 = cA + (size_t)(t + 1) * kstep;
;             const char* a2 = last ? nA : cA + (size_t)(t + 2) * kstep; const char* b2 = last ? nB : cB + (size_t)(t + 2) * kstep;
;             const char* a3 = a2 + kstep; const char* b3 = b2 + kstep;
;             PG8_LDB(B0, 0, 0); PG8_LDB(B1, 0, 1); PG8_SCHED; PG8_LDA(At, 0, 0); PG8_STAGE(PG8_SA(1, 1), a1 + hstepA, voffA);
;             PG8_WAIT_V(8); PG8_WAIT_L(0); PG8_BAR; PG8_MMA(0, 0, At, B0); PG8_MMA(0, 1, At, B1); PG8_BAR; PG8_SCHED;
;             PG8_LDA(At, 0, 1); PG8_STAGE(PG8_SB(0, 0), b2, voffB); PG8_STAGE(PG8_SB(0, 1), b2 + hstepB, voffB); PG8_STAGE(PG8_SA(0, 0), a2, voffA);
;             PG8_WAIT_V(8); PG8_WAIT_L(0); PG8_BAR; PG8_MMA(1, 0, At, B0); PG8_MMA(1, 1, At, B1); PG8_BAR; PG8_SCHED;
.LBB0_869:
	s_add_i32 s64, 0, 0x10000
	s_add_i32 s68, 0, 0x14000
	v_add_u32_e32 v44, s64, v208
	v_add_u32_e32 v156, s68, v208
	ds_read_b128 v[32:35], v44
	ds_read_b128 v[36:39], v44 offset:1024
	ds_read_b128 v[40:43], v44 offset:2048
	ds_read_b128 v[44:47], v44 offset:3072
	ds_read_b128 v[144:147], v156
	ds_read_b128 v[148:151], v156 offset:1024
	ds_read_b128 v[152:155], v156 offset:2048
	ds_read_b128 v[156:159], v156 offset:3072
	s_add_i32 m0, s44, 0xc000
	ds_read_b128 v[160:163], v210
	ds_read_b128 v[164:167], v210 offset:1024
	ds_read_b128 v[168:171], v210 offset:2048
	ds_read_b128 v[172:175], v210 offset:3072
	ds_read_b128 v[188:191], v210 offset:4096
	ds_read_b128 v[192:195], v210 offset:5120
	ds_read_b128 v[198:201], v210 offset:6144
	ds_read_b128 v[212:215], v210 offset:7168
	global_load_lds_dwordx4 v184, s[4:5]
	s_add_i32 m0, s44, 0xe000
	s_nop 0
	global_load_lds_dwordx4 v186, s[4:5]
	s_waitcnt vmcnt(8)
	s_waitcnt lgkmcnt(0)
	s_barrier
	s_setprio 1
	s_waitcnt lgkmcnt(0)
	v_mfma_f32_16x16x32_bf16 v[140:143], v[32:35], v[160:163], v[140:143]
	v_mfma_f32_16x16x32_bf16 v[136:139], v[40:43], v[160:163], v[136:139]
	v_mfma_f32_16x16x32_bf16 v[124:127], v[32:35], v[168:171], v[124:127]
	v_mfma_f32_16x16x32_bf16 v[120:123], v[40:43], v[168:171], v[120:123]
	v_mfma_f32_16x16x32_bf16 v[108:111], v[32:35], v[188:191], v[108:111]
	v_mfma_f32_16x16x32_bf16 v[104:107], v[40:43], v[188:191], v[104:107]
	v_mfma_f32_16x16x32_bf16 v[92:95], v[32:35], v[198:201], v[92:95]
	v_mfma_f32_16x16x32_bf16 v[88:91], v[40:43], v[198:201], v[88:91]
	v_mfma_f32_16x16x32_bf16 v[140:143], v[36:39], v[164:167], v[140:143]
	v_mfma_f32_16x16x32_bf16 v[136:139], v[44:47], v[164:167], v[136:139]
	v_mfma_f32_16x16x32_bf16 v[124:127], v[36:39], v[172:175], v[124:127]
	v_mfma_f32_16x16x32_bf16 v[120:123], v[44:47], v[172:175], v[120:123]
	v_mfma_f32_16x16x32_bf16 v[108:111], v[36:39], v[192:195], v[108:111]
	v_mfma_f32_16x16x32_bf16 v[104:107], v[44:47], v[192:195], v[104:107]
	v_mfma_f32_16x16x32_bf16 v[92:95], v[36:39], v[212:215], v[92:95]
	v_mfma_f32_16x16x32_bf16 v[88:91], v[44:47], v[212:215], v[88:91]
	s_setprio 0
	s_setprio 1
	v_mfma_f32_16x16x32_bf16 v[132:135], v[144:147], v[160:163], v[132:135]
	v_mfma_f32_16x16x32_bf16 v[128:131], v[152:155], v[160:163], v[128:131]
	v_mfma_f32_16x16x32_bf16 v[116:119], v[144:147], v[168:171], v[116:119]
	v_mfma_f32_16x16x32_bf16 v[112:115], v[152:155], v[168:171], v[112:115]
	v_mfma_f32_16x16x32_bf16 v[100:103], v[144:147], v[188:191], v[100:103]
	v_mfma_f32_16x16x32_bf16 v[96:99], v[152:155], v[188:191], v[96:99]
	v_mfma_f32_16x16x32_bf16 v[84:87], v[144:147], v[198:201], v[84:87]
	v_mfma_f32_16x16x32_bf16 v[80:83], v[152:155], v[198:201], v[80:83]
	v_mfma_f32_16x16x32_bf16 v[132:135], v[148:151], v[164:167], v[132:135]
	v_mfma_f32_16x16x32_bf16 v[128:131], v[156:159], v[164:167], v[128:131]
	v_mfma_f32_16x16x32_bf16 v[116:119], v[148:151], v[172:175], v[116:119]
	v_mfma_f32_16x16x32_bf16 v[112:115], v[156:159], v[172:175], v[112:115]
	v_mfma_f32_16x16x32_bf16 v[100:103], v[148:151], v[192:195], v[100:103]
	v_mfma_f32_16x16x32_bf16 v[96:99], v[156:159], v[192:195], v[96:99]
	v_mfma_f32_16x16x32_bf16 v[84:87], v[148:151], v[212:215], v[84:87]
	v_mfma_f32_16x16x32_bf16 v[80:83], v[156:159], v[212:215], v[80:83]
	s_setprio 0
	s_barrier
	s_add_u32 s30, s4, 0xfff80080
	s_addc_u32 s31, s5, -1
	s_cmp_eq_u32 s63, 28
	s_cselect_b32 s35, s53, s31
	s_cselect_b32 s34, s58, s30
	s_cselect_b32 s31, s59, s62
	s_cselect_b32 s30, s60, s61
	s_add_i32 s64, s64, s41
	v_lshl_add_u64 v[202:203], s[30:31], 0, v[176:177]
	s_mov_b32 m0, s64
	ds_read_b128 v[160:163], v210 offset:16384
	ds_read_b128 v[164:167], v210 offset:17408
	ds_read_b128 v[168:171], v210 offset:18432
	ds_read_b128 v[172:175], v210 offset:19456
	ds_read_b128 v[188:191], v210 offset:20480
	ds_read_b128 v[192:195], v210 offset:21504
	ds_read_b128 v[198:201], v210 offset:22528
	ds_read_b128 v[212:215], v210 offset:23552
	global_load_lds_dwordx4 v[202:203], off
	s_add_i32 m0, s64, 0x2000
	s_add_u32 s64, s30, 0x80000
	v_lshl_add_u64 v[216:217], s[30:31], 0, v[178:179]
	s_addc_u32 s65, s31, 0
	s_add_i32 s68, s68, s41
	global_load_lds_dwordx4 v[216:217], off
	v_lshl_add_u64 v[218:219], s[64:65], 0, v[176:177]
	s_mov_b32 m0, s68
	v_lshl_add_u64 v[220:221], s[34:35], 0, v[180:181]
	global_load_lds_dwordx4 v[218:219], off
	v_lshl_add_u64 v[218:219], s[64:65], 0, v[178:179]
	s_add_i32 m0, s68, 0x2000
	s_nop 0
	global_load_lds_dwordx4 v[218:219], off
	v_lshl_add_u64 v[218:219], s[34:35], 0, v[182:183]
	s_mov_b32 m0, s44
	s_nop 0
	global_load_lds_dwordx4 v[218:219], off
	s_mov_b32 m0, s45
	s_nop 0
	global_load_lds_dwordx4 v[220:221], off
	s_add_u32 s34, s34, 0x80000
	s_addc_u32 s35, s35, 0
	s_waitcnt vmcnt(8)
	s_waitcnt lgkmcnt(0)
	s_barrier
; #define PG8_STAGE(bufoff, gbase, voff) do { _Pragma("unroll") for (int _i = 0; _i < 2; ++_i) \
;         __builtin_amdgcn_global_load_lds((const unsigned*)((const char*)(gbase) + (voff)[_i]), (LAS unsigned*)(lds + (bufoff) + ldsw + _i * 8192), 16, 0, 0); } while (0)
; #define PG8_LDA(dst, b, h) do { _Pragma("unroll") for (int m = 0; m < 4; ++m) _Pragma("unroll") for (int k = 0; k < 2; ++k) dst[m][k] = *(const LAS bf16x8*)(lds + PG8_SA(b, h) + aoff + m * 2048 + k * 1024); } while (0)
; #define PG8_LDB(dst, b, h) do { _Pragma("unroll") for (int n = 0; n < 2; ++n) _Pragma("unroll") for (int k = 0; k < 2; ++k) dst[n][k] = *(const LAS bf16x8*)(lds + PG8_SB(b, h) + boff + n * 2048 + k * 1024); } while (0)
; #define PG8_WAIT_V(n) asm volatile("s_waitcnt vmcnt(" #n ")" ::: "memory")
; #define PG8_WAIT_L(n) asm volatile("s_waitcnt lgkmcnt(" #n ")" ::: "memory")
; #define PG8_BAR __builtin_amdgcn_s_barrier()
; #define PG8_SCHED __builtin_amdgcn_sched_barrier(0)
; template <bool F16, class Sched, class Epi>
; __device__ __forceinline__ void gemm_phase(LAS unsigned char* lds, const Gemm g, const Sched& S, const Epi& E, int wave_s) {
;     ...
;             PG8_WAIT_V(8); PG8_WAIT_L(0); PG8_BAR; PG8_MMA(1, 0, At, B0); PG8_MMA(1, 1, At, B1); PG8_BAR; PG8_SCHED;
;             PG8_LDB(B0, 1, 0); PG8_LDB(B1, 1, 1); PG8_SCHED; PG8_LDA(At, 1, 0); PG8_STAGE(PG8_SA(0, 1), a2 + hstepA, voffA);
;             PG8_WAIT_V(8); PG8_WAIT_L(0); PG8_BAR; PG8_MMA(0, 0, At, B0); PG8_MMA(0, 1, At, B1); PG8_BAR; PG8_SCHED;
	s_setprio 1
	s_waitcnt lgkmcnt(0)
	v_mfma_f32_16x16x32_bf16 v[76:79], v[32:35], v[160:163], v[76:79]
	v_mfma_f32_16x16x32_bf16 v[72:75], v[40:43], v[160:163], v[72:75]
	v_mfma_f32_16x16x32_bf16 v[60:63], v[32:35], v[168:171], v[60:63]
	v_mfma_f32_16x16x32_bf16 v[56:59], v[40:43], v[168:171], v[56:59]
	v_mfma_f32_16x16x32_bf16 v[28:31], v[32:35], v[188:191], v[28:31]
	v_mfma_f32_16x16x32_bf16 v[24:27], v[40:43], v[188:191], v[24:27]
	v_mfma_f32_16x16x32_bf16 v[12:15], v[32:35], v[198:201], v[12:15]
	v_mfma_f32_16x16x32_bf16 v[8:11], v[40:43], v[198:201], v[8:11]
	v_mfma_f32_16x16x32_bf16 v[76:79], v[36:39], v[164:167], v[76:79]
	v_mfma_f32_16x16x32_bf16 v[72:75], v[44:47], v[164:167], v[72:75]
	v_mfma_f32_16x16x32_bf16 v[60:63], v[36:39], v[172:175], v[60:63]
	v_mfma_f32_16x16x32_bf16 v[56:59], v[44:47], v[172:175], v[56:59]
	v_mfma_f32_16x16x32_bf16 v[28:31], v[36:39], v[192:195], v[28:31]
	v_mfma_f32_16x16x32_bf16 v[24:27], v[44:47], v[192:195], v[24:27]
	v_mfma_f32_16x16x32_bf16 v[12:15], v[36:39], v[212:215], v[12:15]
	v_mfma_f32_16x16x32_bf16 v[8:11], v[44:47], v[212:215], v[8:11]
	s_setprio 0
	s_setprio 1
	v_mfma_f32_16x16x32_bf16 v[20:23], v[144:147], v[188:191], v[20:23]
	v_mfma_f32_16x16x32_bf16 v[16:19], v[152:155], v[188:191], v[16:19]
	v_mfma_f32_16x16x32_bf16 v[4:7], v[144:147], v[198:201], v[4:7]
	v_mfma_f32_16x16x32_bf16 v[0:3], v[152:155], v[198:201], v[0:3]
	v_mfma_f32_16x16x32_bf16 v[32:35], v[144:147], v[160:163], v[68:71]
	v_mfma_f32_16x16x32_bf16 v[36:39], v[152:155], v[160:163], v[64:67]
	v_mfma_f32_16x16x32_bf16 v[40:43], v[144:147], v[168:171], v[52:55]
	v_mfma_f32_16x16x32_bf16 v[44:47], v[152:155], v[168:171], v[48:51]
	v_mfma_f32_16x16x32_bf16 v[20:23], v[148:151], v[192:195], v[20:23]
	v_mfma_f32_16x16x32_bf16 v[16:19], v[156:159], v[192:195], v[16:19]
	v_mfma_f32_16x16x32_bf16 v[4:7], v[148:151], v[212:215], v[4:7]
	v_mfma_f32_16x16x32_bf16 v[0:3], v[156:159], v[212:215], v[0:3]
	v_mfma_f32_16x16x32_bf16 v[32:35], v[148:151], v[164:167], v[32:35]
	v_mfma_f32_16x16x32_bf16 v[36:39], v[156:159], v[164:167], v[36:39]
	v_mfma_f32_16x16x32_bf16 v[40:43], v[148:151], v[172:175], v[40:43]
	v_mfma_f32_16x16x32_bf16 v[44:47], v[156:159], v[172:175], v[44:47]
	s_setprio 0
	s_barrier
	s_add_i32 s64, 0, 0x18000
	s_add_i32 s65, 0, 0x1c000
	v_add_u32_e32 v68, s64, v208
	v_add_u32_e32 v156, s65, v208
	ds_read_b128 v[48:51], v68
	ds_read_b128 v[52:55], v68 offset:1024
	ds_read_b128 v[64:67], v68 offset:2048
	ds_read_b128 v[68:71], v68 offset:3072
	ds_read_b128 v[144:147], v156
	ds_read_b128 v[148:151], v156 offset:1024
	ds_read_b128 v[152:155], v156 offset:2048
	ds_read_b128 v[156:159], v156 offset:3072
	s_mov_b32 m0, s46
	ds_read_b128 v[160:163], v210 offset:32768
	ds_read_b128 v[164:167], v210 offset:33792
	ds_read_b128 v[168:171], v210 offset:34816
	ds_read_b128 v[172:175], v210 offset:35840
	ds_read_b128 v[188:191], v210 offset:36864
	ds_read_b128 v[192:195], v210 offset:37888
	ds_read_b128 v[198:201], v210 offset:38912
	ds_read_b128 v[212:215], v210 offset:39936
	global_load_lds_dwordx4 v182, s[34:35]
	s_mov_b32 m0, s47
	s_nop 0
	global_load_lds_dwordx4 v180, s[34:35]
	s_waitcnt vmcnt(8)
	s_waitcnt lgkmcnt(0)
	s_barrier
	s_setprio 1
	s_waitcnt lgkmcnt(0)
	v_mfma_f32_16x16x32_bf16 v[140:143], v[48:51], v[160:163], v[140:143]
	v_mfma_f32_16x16x32_bf16 v[136:139], v[64:67], v[160:163], v[136:139]
	v_mfma_f32_16x16x32_bf16 v[124:127], v[48:51], v[168:171], v[124:127]
	v_mfma_f32_16x16x32_bf16 v[120:123], v[64:67], v[168:171], v[120:123]
	v_mfma_f32_16x16x32_bf16 v[108:111], v[48:51], v[188:191], v[108:111]
	v_mfma_f32_16x16x32_bf16 v[104:107], v[64:67], v[188:191], v[104:107]
	v_mfma_f32_16x16x32_bf16 v[92:95], v[48:51], v[198:201], v[92:95]
	v_mfma_f32_16x16x32_bf16 v[88:91], v[64:67], v[198:201], v[88:91]
	v_mfma_f32_16x16x32_bf16 v[140:143], v[52:55], v[164:167], v[140:143]
	v_mfma_f32_16x16x32_bf16 v[136:139], v[68:71], v[164:167], v[136:139]
	v_mfma_f32_16x16x32_bf16 v[124:127], v[52:55], v[172:175], v[124:127]
	v_mfma_f32_16x16x32_bf16 v[120:123], v[68:71], v[172:175], v[120:123]
	v_mfma_f32_16x16x32_bf16 v[108:111], v[52:55], v[192:195], v[108:111]
	v_mfma_f32_16x16x32_bf16 v[104:107], v[68:71], v[192:195], v[104:107]
	v_mfma_f32_16x16x32_bf16 v[92:95], v[52:55], v[212:215], v[92:95]
	v_mfma_f32_16x16x32_bf16 v[88:91], v[68:71], v[212:215], v[88:91]
	s_setprio 0
	s_setprio 1
	v_mfma_f32_16x16x32_bf16 v[132:135], v[144:147], v[160:163], v[132:135]
	v_mfma_f32_16x16x32_bf16 v[128:131], v[152:155], v[160:163], v[128:131]
	v_mfma_f32_16x16x32_bf16 v[116:119], v[144:147], v[168:171], v[116:119]
	v_mfma_f32_16x16x32_bf16 v[112:115], v[152:155], v[168:171], v[112:115]
	v_mfma_f32_16x16x32_bf16 v[100:103], v[144:147], v[188:191], v[100:103]
	v_mfma_f32_16x16x32_bf16 v[96:99], v[152:155], v[188:191], v[96:99]
	v_mfma_f32_16x16x32_bf16 v[84:87], v[144:147], v[198:201], v[84:87]
	v_mfma_f32_16x16x32_bf16 v[80:83], v[152:155], v[198:201], v[80:83]
	v_mfma_f32_16x16x32_bf16 v[132:135], v[148:151], v[164:167], v[132:135]
	v_mfma_f32_16x16x32_bf16 v[128:131], v[156:159], v[164:167], v[128:131]
	v_mfma_f32_16x16x32_bf16 v[116:119], v[148:151], v[172:175], v[116:119]
	v_mfma_f32_16x16x32_bf16 v[112:115], v[156:159], v[172:175], v[112:115]
	v_mfma_f32_16x16x32_bf16 v[100:103], v[148:151], v[192:195], v[100:103]
	v_mfma_f32_16x16x32_bf16 v[96:99], v[156:159], v[192:195], v[96:99]
	v_mfma_f32_16x16x32_bf16 v[84:87], v[148:151], v[212:215], v[84:87]
	v_mfma_f32_16x16x32_bf16 v[80:83], v[156:159], v[212:215], v[80:83]
	s_setprio 0
	s_barrier
; #define PG8_STAGE(bufoff, gbase, voff) do { _Pragma("unroll") for (int _i = 0; _i < 2; ++_i) \
;         __builtin_amdgcn_global_load_lds((const unsigned*)((const char*)(gbase) + (voff)[_i]), (LAS unsigned*)(lds + (bufoff) + ldsw + _i * 8192), 16, 0, 0); } while (0)
; #define PG8_LDA(dst, b, h) do { _Pragma("unroll") for (int m = 0; m < 4; ++m) _Pragma("unroll") for (int k = 0; k < 2; ++k) dst[m][k] = *(const LAS bf16x8*)(lds + PG8_SA(b, h) + aoff + m * 2048 + k * 1024); } while (0)
; #define PG8_WAIT_V(n) asm volatile("s_waitcnt vmcnt(" #n ")" ::: "memory")
; #define PG8_WAIT_L(n) asm volatile("s_waitcnt lgkmcnt(" #n ")" ::: "memory")
; #define PG8_BAR __builtin_amdgcn_s_barrier()
; #define PG8_SCHED __builtin_amdgcn_sched_barrier(0)
; template <bool F16, class Sched, class Epi>
; __device__ __forceinline__ void gemm_phase(LAS unsigned char* lds, const Gemm g, const Sched& S, const Epi& E, int wave_s) {
;     ...
;             PG8_LDA(At, 1, 1); PG8_STAGE(PG8_SB(1, 0), b3, voffB); PG8_STAGE(PG8_SB(1, 1), b3 + hstepB, voffB); PG8_STAGE(PG8_SA(1, 0), a3, voffA);
;             PG8_WAIT_V(8); PG8_WAIT_L(0); PG8_BAR; PG8_MMA(1, 0, At, B0); PG8_MMA(1, 1, At, B1); PG8_BAR; PG8_SCHED;
;         }
	s_add_i32 s34, s64, s41
	v_lshl_add_u64 v[202:203], v[202:203], 0, s[54:55]
	s_mov_b32 m0, s34
	ds_read_b128 v[160:163], v210 offset:49152
	ds_read_b128 v[164:167], v210 offset:50176
	ds_read_b128 v[168:171], v210 offset:51200
	ds_read_b128 v[172:175], v210 offset:52224
	ds_read_b128 v[188:191], v210 offset:53248
	ds_read_b128 v[192:195], v210 offset:54272
	ds_read_b128 v[198:201], v210 offset:55296
	ds_read_b128 v[212:215], v210 offset:56320
	global_load_lds_dwordx4 v[202:203], off
	s_add_i32 m0, s34, 0x2000
	s_add_u32 s30, s30, 0x80080
	v_lshl_add_u64 v[202:203], v[216:217], 0, s[54:55]
	s_addc_u32 s31, s31, 0
	s_add_i32 s34, s65, s41
	global_load_lds_dwordx4 v[202:203], off
	v_lshl_add_u64 v[202:203], s[30:31], 0, v[176:177]
	s_mov_b32 m0, s34
	s_nop 0
	global_load_lds_dwordx4 v[202:203], off
	v_lshl_add_u64 v[202:203], s[30:31], 0, v[178:179]
	s_add_i32 m0, s34, 0x2000
	s_nop 0
	global_load_lds_dwordx4 v[202:203], off
	v_lshl_add_u64 v[202:203], v[218:219], 0, s[54:55]
	s_mov_b32 m0, s49
	s_nop 0
	global_load_lds_dwordx4 v[202:203], off
	v_lshl_add_u64 v[202:203], v[220:221], 0, s[54:55]
	s_mov_b32 m0, s52
	s_nop 0
	global_load_lds_dwordx4 v[202:203], off
	s_waitcnt vmcnt(8)
	s_waitcnt lgkmcnt(0)
	s_barrier
	s_setprio 1
	s_waitcnt lgkmcnt(0)
	v_mfma_f32_16x16x32_bf16 v[76:79], v[48:51], v[160:163], v[76:79]
	v_mfma_f32_16x16x32_bf16 v[72:75], v[64:67], v[160:163], v[72:75]
	v_mfma_f32_16x16x32_bf16 v[60:63], v[48:51], v[168:171], v[60:63]
	v_mfma_f32_16x16x32_bf16 v[56:59], v[64:67], v[168:171], v[56:59]
	v_mfma_f32_16x16x32_bf16 v[28:31], v[48:51], v[188:191], v[28:31]
	v_mfma_f32_16x16x32_bf16 v[24:27], v[64:67], v[188:191], v[24:27]
	v_mfma_f32_16x16x32_bf16 v[12:15], v[48:51], v[198:201], v[12:15]
	v_mfma_f32_16x16x32_bf16 v[8:11], v[64:67], v[198:201], v[8:11]
	v_mfma_f32_16x16x32_bf16 v[76:79], v[52:55], v[164:167], v[76:79]
	v_mfma_f32_16x16x32_bf16 v[72:75], v[68:71], v[164:167], v[72:75]
	v_mfma_f32_16x16x32_bf16 v[60:63], v[52:55], v[172:175], v[60:63]
	v_mfma_f32_16x16x32_bf16 v[56:59], v[68:71], v[172:175], v[56:59]
	v_mfma_f32_16x16x32_bf16 v[28:31], v[52:55], v[192:195], v[28:31]
	v_mfma_f32_16x16x32_bf16 v[24:27], v[68:71], v[192:195], v[24:27]
	v_mfma_f32_16x16x32_bf16 v[12:15], v[52:55], v[212:215], v[12:15]
	v_mfma_f32_16x16x32_bf16 v[8:11], v[68:71], v[212:215], v[8:11]
	s_setprio 0
	s_setprio 1
	v_mfma_f32_16x16x32_bf16 v[32:35], v[144:147], v[160:163], v[32:35]
	v_mfma_f32_16x16x32_bf16 v[68:71], v[148:151], v[164:167], v[32:35]
	v_mfma_f32_16x16x32_bf16 v[32:35], v[152:155], v[160:163], v[36:39]
	v_mfma_f32_16x16x32_bf16 v[64:67], v[156:159], v[164:167], v[32:35]
	v_mfma_f32_16x16x32_bf16 v[32:35], v[144:147], v[168:171], v[40:43]
	v_mfma_f32_16x16x32_bf16 v[52:55], v[148:151], v[172:175], v[32:35]
	v_mfma_f32_16x16x32_bf16 v[32:35], v[152:155], v[168:171], v[44:47]
	v_mfma_f32_16x16x32_bf16 v[20:23], v[144:147], v[188:191], v[20:23]
	v_mfma_f32_16x16x32_bf16 v[16:19], v[152:155], v[188:191], v[16:19]
	v_mfma_f32_16x16x32_bf16 v[4:7], v[144:147], v[198:201], v[4:7]
	v_mfma_f32_16x16x32_bf16 v[0:3], v[152:155], v[198:201], v[0:3]
	v_mfma_f32_16x16x32_bf16 v[48:51], v[156:159], v[172:175], v[32:35]
	v_mfma_f32_16x16x32_bf16 v[20:23], v[148:151], v[192:195], v[20:23]
	v_mfma_f32_16x16x32_bf16 v[16:19], v[156:159], v[192:195], v[16:19]
	v_mfma_f32_16x16x32_bf16 v[4:7], v[148:151], v[212:215], v[4:7]
	v_mfma_f32_16x16x32_bf16 v[0:3], v[156:159], v[212:215], v[0:3]
	s_setprio 0
	s_barrier
	s_add_i32 s63, s63, 2
	s_add_u32 s4, s4, 0x100
	s_addc_u32 s5, s5, 0
	s_add_u32 s61, s61, 0x100
	s_addc_u32 s62, s62, 0
	s_cmp_gt_u32 s63, 29
	s_cbranch_scc0 .LBB0_869
	s_and_b64 vcc, exec, s[26:27]
	s_cbranch_vccz .LBB0_872
	s_barrier

; #define PG8_STAGE(bufoff, gbase, voff) do { _Pragma("unroll") for (int _i = 0; _i < 2; ++_i) \
;         __builtin_amdgcn_global_load_lds((const unsigned*)((const char*)(gbase) + (voff)[_i]), (LAS unsigned*)(lds + (bufoff) + ldsw + _i * 8192), 16, 0, 0); } while (0)
; #define PG8_LDA(dst, b, h) do { _Pragma("unroll") for (int m = 0; m < 4; ++m) _Pragma("unroll") for (int k = 0; k < 2; ++k) dst[m][k] = *(const LAS bf16x8*)(lds + PG8_SA(b, h) + aoff + m * 2048 + k * 1024); } while (0)
; #define PG8_LDB(dst, b, h) do { _Pragma("unroll") for (int n = 0; n < 2; ++n) _Pragma("unroll") for (int k = 0; k < 2; ++k) dst[n][k] = *(const LAS bf16x8*)(lds + PG8_SB(b, h) + boff + n * 2048 + k * 1024); } while (0)
; #define PG8_WAIT_V(n) asm volatile("s_waitcnt vmcnt(" #n ")" ::: "memory")
; #define PG8_WAIT_L(n) asm volatile("s_waitcnt lgkmcnt(" #n ")" ::: "memory")
; #define PG8_BAR __builtin_amdgcn_s_barrier()
; #define PG8_SCHED __builtin_amdgcn_sched_barrier(0)
; template <bool F16, class Sched, class Epi>
; __device__ __forceinline__ void gemm_phase(LAS unsigned char* lds, const Gemm g, const Sched& S, const Epi& E, int wave_s) {
;     ...
;             const char* a1 = cA + (size_t)(t + 1) * kstep;
;             const char* a2 = last ? nA : cA + (size_t)(t + 2) * kstep; const char* b2 = last ? nB : cB + (size_t)(t + 2) * kstep;
;             const char* a3 = a2 + kstep; const char* b3 = b2 + kstep;
;             PG8_LDB(B0, 0, 0); PG8_LDB(B1, 0, 1); PG8_SCHED; PG8_LDA(At, 0, 0); PG8_STAGE(PG8_SA(1, 1), a1 + hstepA, voffA);
;             PG8_WAIT_V(8); PG8_WAIT_L(0); PG8_BAR; PG8_MMA(0, 0, At, B0); PG8_MMA(0, 1, At, B1); PG8_BAR; PG8_SCHED;
;             PG8_LDA(At, 0, 1); PG8_STAGE(PG8_SB(0, 0), b2, voffB); PG8_STAGE(PG8_SB(0, 1), b2 + hstepB, voffB); PG8_STAGE(PG8_SA(0, 0), a2, voffA);
;             PG8_WAIT_V(8); PG8_WAIT_L(0); PG8_BAR; PG8_MMA(1, 0, At, B0); PG8_MMA(1, 1, At, B1); PG8_BAR; PG8_SCHED;
.LBB0_993:
	s_add_i32 s43, 0, 0x10000
	s_add_i32 s26, 0, 0x14000
	v_add_u32_e32 v68, s43, v208
	v_add_u32_e32 v156, s26, v208
	ds_read_b128 v[56:59], v68
	ds_read_b128 v[60:63], v68 offset:1024
	ds_read_b128 v[64:67], v68 offset:2048
	ds_read_b128 v[68:71], v68 offset:3072
	ds_read_b128 v[144:147], v156
	ds_read_b128 v[148:151], v156 offset:1024
	ds_read_b128 v[152:155], v156 offset:2048
	ds_read_b128 v[156:159], v156 offset:3072
	s_add_i32 m0, s18, 0xc000
	ds_read_b128 v[160:163], v210
	ds_read_b128 v[164:167], v210 offset:1024
	ds_read_b128 v[168:171], v210 offset:2048
	ds_read_b128 v[172:175], v210 offset:3072
	ds_read_b128 v[188:191], v210 offset:4096
	ds_read_b128 v[192:195], v210 offset:5120
	ds_read_b128 v[198:201], v210 offset:6144
	ds_read_b128 v[212:215], v210 offset:7168
	global_load_lds_dwordx4 v184, s[38:39]
	s_add_i32 m0, s18, 0xe000
	s_nop 0
	global_load_lds_dwordx4 v186, s[38:39]
	s_waitcnt vmcnt(8)
	s_waitcnt lgkmcnt(0)
	s_barrier
	s_setprio 1
	s_waitcnt lgkmcnt(0)
	v_mfma_f32_16x16x32_bf16 v[140:143], v[56:59], v[160:163], v[140:143]
	v_mfma_f32_16x16x32_bf16 v[136:139], v[64:67], v[160:163], v[136:139]
	v_mfma_f32_16x16x32_bf16 v[124:127], v[56:59], v[168:171], v[124:127]
	v_mfma_f32_16x16x32_bf16 v[120:123], v[64:67], v[168:171], v[120:123]
	v_mfma_f32_16x16x32_bf16 v[108:111], v[56:59], v[188:191], v[108:111]
	v_mfma_f32_16x16x32_bf16 v[104:107], v[64:67], v[188:191], v[104:107]
	v_mfma_f32_16x16x32_bf16 v[92:95], v[56:59], v[198:201], v[92:95]
	v_mfma_f32_16x16x32_bf16 v[88:91], v[64:67], v[198:201], v[88:91]
	v_mfma_f32_16x16x32_bf16 v[140:143], v[60:63], v[164:167], v[140:143]
	v_mfma_f32_16x16x32_bf16 v[136:139], v[68:71], v[164:167], v[136:139]
	v_mfma_f32_16x16x32_bf16 v[124:127], v[60:63], v[172:175], v[124:127]
	v_mfma_f32_16x16x32_bf16 v[120:123], v[68:71], v[172:175], v[120:123]
	v_mfma_f32_16x16x32_bf16 v[108:111], v[60:63], v[192:195], v[108:111]
	v_mfma_f32_16x16x32_bf16 v[104:107], v[68:71], v[192:195], v[104:107]
	v_mfma_f32_16x16x32_bf16 v[92:95], v[60:63], v[212:215], v[92:95]
	v_mfma_f32_16x16x32_bf16 v[88:91], v[68:71], v[212:215], v[88:91]
	s_setprio 0
	s_setprio 1
	v_mfma_f32_16x16x32_bf16 v[132:135], v[144:147], v[160:163], v[132:135]
	v_mfma_f32_16x16x32_bf16 v[128:131], v[152:155], v[160:163], v[128:131]
	v_mfma_f32_16x16x32_bf16 v[116:119], v[144:147], v[168:171], v[116:119]
	v_mfma_f32_16x16x32_bf16 v[112:115], v[152:155], v[168:171], v[112:115]
	v_mfma_f32_16x16x32_bf16 v[100:103], v[144:147], v[188:191], v[100:103]
	v_mfma_f32_16x16x32_bf16 v[96:99], v[152:155], v[188:191], v[96:99]
	v_mfma_f32_16x16x32_bf16 v[84:87], v[144:147], v[198:201], v[84:87]
	v_mfma_f32_16x16x32_bf16 v[80:83], v[152:155], v[198:201], v[80:83]
	v_mfma_f32_16x16x32_bf16 v[132:135], v[148:151], v[164:167], v[132:135]
	v_mfma_f32_16x16x32_bf16 v[128:131], v[156:159], v[164:167], v[128:131]
	v_mfma_f32_16x16x32_bf16 v[116:119], v[148:151], v[172:175], v[116:119]
	v_mfma_f32_16x16x32_bf16 v[112:115], v[156:159], v[172:175], v[112:115]
	v_mfma_f32_16x16x32_bf16 v[100:103], v[148:151], v[192:195], v[100:103]
	v_mfma_f32_16x16x32_bf16 v[96:99], v[156:159], v[192:195], v[96:99]
	v_mfma_f32_16x16x32_bf16 v[84:87], v[148:151], v[212:215], v[84:87]
	v_mfma_f32_16x16x32_bf16 v[80:83], v[156:159], v[212:215], v[80:83]
	s_setprio 0
	s_barrier
	s_add_u32 s24, s38, 0xfff80080
	s_addc_u32 s25, s39, -1
	s_cmp_eq_u32 s42, 28
	s_cselect_b32 s65, s4, s25
	s_cselect_b32 s64, s5, s24
	s_cselect_b32 vcc_hi, s6, s9
	s_cselect_b32 vcc_lo, s7, s8
	s_add_i32 s24, s43, s15
	v_lshl_add_u64 v[202:203], vcc, 0, v[176:177]
	s_mov_b32 m0, s24
	ds_read_b128 v[160:163], v210 offset:16384
	ds_read_b128 v[164:167], v210 offset:17408
	ds_read_b128 v[168:171], v210 offset:18432
	ds_read_b128 v[172:175], v210 offset:19456
	ds_read_b128 v[188:191], v210 offset:20480
	ds_read_b128 v[192:195], v210 offset:21504
	ds_read_b128 v[198:201], v210 offset:22528
	ds_read_b128 v[212:215], v210 offset:23552
	global_load_lds_dwordx4 v[202:203], off
	s_add_i32 m0, s24, 0x2000
	s_add_u32 s24, vcc_lo, 0x80000
	v_lshl_add_u64 v[216:217], vcc, 0, v[178:179]
	s_addc_u32 s25, vcc_hi, 0
	s_add_i32 s26, s26, s15
	global_load_lds_dwordx4 v[216:217], off
	v_lshl_add_u64 v[218:219], s[24:25], 0, v[176:177]
	s_mov_b32 m0, s26
	v_lshl_add_u64 v[220:221], s[64:65], 0, v[180:181]
	global_load_lds_dwordx4 v[218:219], off
	v_lshl_add_u64 v[218:219], s[24:25], 0, v[178:179]
	s_add_i32 m0, s26, 0x2000
	s_nop 0
	global_load_lds_dwordx4 v[218:219], off
	v_lshl_add_u64 v[218:219], s[64:65], 0, v[182:183]
	s_mov_b32 m0, s18
	s_nop 0
	global_load_lds_dwordx4 v[218:219], off
	s_mov_b32 m0, s19
	s_nop 0
	global_load_lds_dwordx4 v[220:221], off
	s_add_u32 s24, s64, 0x80000
	s_addc_u32 s25, s65, 0
	s_waitcnt vmcnt(8)
	s_waitcnt lgkmcnt(0)
	s_barrier
; #define PG8_STAGE(bufoff, gbase, voff) do { _Pragma("unroll") for (int _i = 0; _i < 2; ++_i) \
;         __builtin_amdgcn_global_load_lds((const unsigned*)((const char*)(gbase) + (voff)[_i]), (LAS unsigned*)(lds + (bufoff) + ldsw + _i * 8192), 16, 0, 0); } while (0)
; #define PG8_LDA(dst, b, h) do { _Pragma("unroll") for (int m = 0; m < 4; ++m) _Pragma("unroll") for (int k = 0; k < 2; ++k) dst[m][k] = *(const LAS bf16x8*)(lds + PG8_SA(b, h) + aoff + m * 2048 + k * 1024); } while (0)
; #define PG8_LDB(dst, b, h) do { _Pragma("unroll") for (int n = 0; n < 2; ++n) _Pragma("unroll") for (int k = 0; k < 2; ++k) dst[n][k] = *(const LAS bf16x8*)(lds + PG8_SB(b, h) + boff + n * 2048 + k * 1024); } while (0)
; #define PG8_WAIT_V(n) asm volatile("s_waitcnt vmcnt(" #n ")" ::: "memory")
; #define PG8_WAIT_L(n) asm volatile("s_waitcnt lgkmcnt(" #n ")" ::: "memory")
; #define PG8_BAR __builtin_amdgcn_s_barrier()
; #define PG8_SCHED __builtin_amdgcn_sched_barrier(0)
; template <bool F16, class Sched, class Epi>
; __device__ __forceinline__ void gemm_phase(LAS unsigned char* lds, const Gemm g, const Sched& S, const Epi& E, int wave_s) {
;     ...
;             PG8_WAIT_V(8); PG8_WAIT_L(0); PG8_BAR; PG8_MMA(1, 0, At, B0); PG8_MMA(1, 1, At, B1); PG8_BAR; PG8_SCHED;
;             PG8_LDB(B0, 1, 0); PG8_LDB(B1, 1, 1); PG8_SCHED; PG8_LDA(At, 1, 0); PG8_STAGE(PG8_SA(0, 1), a2 + hstepA, voffA);
;             PG8_WAIT_V(8); PG8_WAIT_L(0); PG8_BAR; PG8_MMA(0, 0, At, B0); PG8_MMA(0, 1, At, B1); PG8_BAR; PG8_SCHED;
	s_setprio 1
	s_waitcnt lgkmcnt(0)
	v_mfma_f32_16x16x32_bf16 v[76:79], v[56:59], v[160:163], v[76:79]
	v_mfma_f32_16x16x32_bf16 v[72:75], v[64:67], v[160:163], v[72:75]
	v_mfma_f32_16x16x32_bf16 v[44:47], v[56:59], v[168:171], v[44:47]
	v_mfma_f32_16x16x32_bf16 v[40:43], v[64:67], v[168:171], v[40:43]
	v_mfma_f32_16x16x32_bf16 v[28:31], v[56:59], v[188:191], v[28:31]
	v_mfma_f32_16x16x32_bf16 v[24:27], v[64:67], v[188:191], v[24:27]
	v_mfma_f32_16x16x32_bf16 v[12:15], v[56:59], v[198:201], v[12:15]
	v_mfma_f32_16x16x32_bf16 v[8:11], v[64:67], v[198:201], v[8:11]
	v_mfma_f32_16x16x32_bf16 v[76:79], v[60:63], v[164:167], v[76:79]
	v_mfma_f32_16x16x32_bf16 v[72:75], v[68:71], v[164:167], v[72:75]
	v_mfma_f32_16x16x32_bf16 v[44:47], v[60:63], v[172:175], v[44:47]
	v_mfma_f32_16x16x32_bf16 v[40:43], v[68:71], v[172:175], v[40:43]
	v_mfma_f32_16x16x32_bf16 v[28:31], v[60:63], v[192:195], v[28:31]
	v_mfma_f32_16x16x32_bf16 v[24:27], v[68:71], v[192:195], v[24:27]
	v_mfma_f32_16x16x32_bf16 v[12:15], v[60:63], v[212:215], v[12:15]
	v_mfma_f32_16x16x32_bf16 v[8:11], v[68:71], v[212:215], v[8:11]
	s_setprio 0
	s_setprio 1
	v_mfma_f32_16x16x32_bf16 v[52:55], v[144:147], v[160:163], v[52:55]
	v_mfma_f32_16x16x32_bf16 v[48:51], v[152:155], v[160:163], v[48:51]
	v_mfma_f32_16x16x32_bf16 v[36:39], v[144:147], v[168:171], v[36:39]
	v_mfma_f32_16x16x32_bf16 v[32:35], v[152:155], v[168:171], v[32:35]
	v_mfma_f32_16x16x32_bf16 v[20:23], v[144:147], v[188:191], v[20:23]
	v_mfma_f32_16x16x32_bf16 v[16:19], v[152:155], v[188:191], v[16:19]
	v_mfma_f32_16x16x32_bf16 v[4:7], v[144:147], v[198:201], v[4:7]
	v_mfma_f32_16x16x32_bf16 v[0:3], v[152:155], v[198:201], v[0:3]
	v_mfma_f32_16x16x32_bf16 v[52:55], v[148:151], v[164:167], v[52:55]
	v_mfma_f32_16x16x32_bf16 v[48:51], v[156:159], v[164:167], v[48:51]
	v_mfma_f32_16x16x32_bf16 v[36:39], v[148:151], v[172:175], v[36:39]
	v_mfma_f32_16x16x32_bf16 v[32:35], v[156:159], v[172:175], v[32:35]
	v_mfma_f32_16x16x32_bf16 v[20:23], v[148:151], v[192:195], v[20:23]
	v_mfma_f32_16x16x32_bf16 v[16:19], v[156:159], v[192:195], v[16:19]
	v_mfma_f32_16x16x32_bf16 v[4:7], v[148:151], v[212:215], v[4:7]
	v_mfma_f32_16x16x32_bf16 v[0:3], v[156:159], v[212:215], v[0:3]
	s_setprio 0
	s_barrier
	s_add_i32 s26, 0, 0x18000
	s_add_i32 s27, 0, 0x1c000
	v_add_u32_e32 v68, s26, v208
	v_add_u32_e32 v156, s27, v208
	ds_read_b128 v[56:59], v68
	ds_read_b128 v[60:63], v68 offset:1024
	ds_read_b128 v[64:67], v68 offset:2048
	ds_read_b128 v[68:71], v68 offset:3072
	ds_read_b128 v[144:147], v156
	ds_read_b128 v[148:151], v156 offset:1024
	ds_read_b128 v[152:155], v156 offset:2048
	ds_read_b128 v[156:159], v156 offset:3072
	s_mov_b32 m0, s20
	ds_read_b128 v[160:163], v210 offset:32768
	ds_read_b128 v[164:167], v210 offset:33792
	ds_read_b128 v[168:171], v210 offset:34816
	ds_read_b128 v[172:175], v210 offset:35840
	ds_read_b128 v[188:191], v210 offset:36864
	ds_read_b128 v[192:195], v210 offset:37888
	ds_read_b128 v[198:201], v210 offset:38912
	ds_read_b128 v[212:215], v210 offset:39936
	global_load_lds_dwordx4 v182, s[24:25]
	s_mov_b32 m0, s21
	s_nop 0
	global_load_lds_dwordx4 v180, s[24:25]
	s_waitcnt vmcnt(8)
	s_waitcnt lgkmcnt(0)
	s_barrier
	s_setprio 1
	s_waitcnt lgkmcnt(0)
	v_mfma_f32_16x16x32_bf16 v[140:143], v[56:59], v[160:163], v[140:143]
	v_mfma_f32_16x16x32_bf16 v[136:139], v[64:67], v[160:163], v[136:139]
	v_mfma_f32_16x16x32_bf16 v[124:127], v[56:59], v[168:171], v[124:127]
	v_mfma_f32_16x16x32_bf16 v[120:123], v[64:67], v[168:171], v[120:123]
	v_mfma_f32_16x16x32_bf16 v[108:111], v[56:59], v[188:191], v[108:111]
	v_mfma_f32_16x16x32_bf16 v[104:107], v[64:67], v[188:191], v[104:107]
	v_mfma_f32_16x16x32_bf16 v[92:95], v[56:59], v[198:201], v[92:95]
	v_mfma_f32_16x16x32_bf16 v[88:91], v[64:67], v[198:201], v[88:91]
	v_mfma_f32_16x16x32_bf16 v[140:143], v[60:63], v[164:167], v[140:143]
	v_mfma_f32_16x16x32_bf16 v[136:139], v[68:71], v[164:167], v[136:139]
	v_mfma_f32_16x16x32_bf16 v[124:127], v[60:63], v[172:175], v[124:127]
	v_mfma_f32_16x16x32_bf16 v[120:123], v[68:71], v[172:175], v[120:123]
	v_mfma_f32_16x16x32_bf16 v[108:111], v[60:63], v[192:195], v[108:111]
	v_mfma_f32_16x16x32_bf16 v[104:107], v[68:71], v[192:195], v[104:107]
	v_mfma_f32_16x16x32_bf16 v[92:95], v[60:63], v[212:215], v[92:95]
	v_mfma_f32_16x16x32_bf16 v[88:91], v[68:71], v[212:215], v[88:91]
	s_setprio 0
	s_setprio 1
	v_mfma_f32_16x16x32_bf16 v[132:135], v[144:147], v[160:163], v[132:135]
	v_mfma_f32_16x16x32_bf16 v[128:131], v[152:155], v[160:163], v[128:131]
	v_mfma_f32_16x16x32_bf16 v[116:119], v[144:147], v[168:171], v[116:119]
	v_mfma_f32_16x16x32_bf16 v[112:115], v[152:155], v[168:171], v[112:115]
	v_mfma_f32_16x16x32_bf16 v[100:103], v[144:147], v[188:191], v[100:103]
	v_mfma_f32_16x16x32_bf16 v[96:99], v[152:155], v[188:191], v[96:99]
	v_mfma_f32_16x16x32_bf16 v[84:87], v[144:147], v[198:201], v[84:87]
	v_mfma_f32_16x16x32_bf16 v[80:83], v[152:155], v[198:201], v[80:83]
	v_mfma_f32_16x16x32_bf16 v[132:135], v[148:151], v[164:167], v[132:135]
	v_mfma_f32_16x16x32_bf16 v[128:131], v[156:159], v[164:167], v[128:131]
	v_mfma_f32_16x16x32_bf16 v[116:119], v[148:151], v[172:175], v[116:119]
	v_mfma_f32_16x16x32_bf16 v[112:115], v[156:159], v[172:175], v[112:115]
	v_mfma_f32_16x16x32_bf16 v[100:103], v[148:151], v[192:195], v[100:103]
	v_mfma_f32_16x16x32_bf16 v[96:99], v[156:159], v[192:195], v[96:99]
	v_mfma_f32_16x16x32_bf16 v[84:87], v[148:151], v[212:215], v[84:87]
	v_mfma_f32_16x16x32_bf16 v[80:83], v[156:159], v[212:215], v[80:83]
	s_setprio 0
	s_barrier
; #define PG8_STAGE(bufoff, gbase, voff) do { _Pragma("unroll") for (int _i = 0; _i < 2; ++_i) \
;         __builtin_amdgcn_global_load_lds((const unsigned*)((const char*)(gbase) + (voff)[_i]), (LAS unsigned*)(lds + (bufoff) + ldsw + _i * 8192), 16, 0, 0); } while (0)
; #define PG8_LDA(dst, b, h) do { _Pragma("unroll") for (int m = 0; m < 4; ++m) _Pragma("unroll") for (int k = 0; k < 2; ++k) dst[m][k] = *(const LAS bf16x8*)(lds + PG8_SA(b, h) + aoff + m * 2048 + k * 1024); } while (0)
; #define PG8_WAIT_V(n) asm volatile("s_waitcnt vmcnt(" #n ")" ::: "memory")
; #define PG8_WAIT_L(n) asm volatile("s_waitcnt lgkmcnt(" #n ")" ::: "memory")
; #define PG8_BAR __builtin_amdgcn_s_barrier()
; #define PG8_SCHED __builtin_amdgcn_sched_barrier(0)
; template <bool F16, class Sched, class Epi>
; __device__ __forceinline__ void gemm_phase(LAS unsigned char* lds, const Gemm g, const Sched& S, const Epi& E, int wave_s) {
;     ...
;             PG8_LDA(At, 1, 1); PG8_STAGE(PG8_SB(1, 0), b3, voffB); PG8_STAGE(PG8_SB(1, 1), b3 + hstepB, voffB); PG8_STAGE(PG8_SA(1, 0), a3, voffA);
;             PG8_WAIT_V(8); PG8_WAIT_L(0); PG8_BAR; PG8_MMA(1, 0, At, B0); PG8_MMA(1, 1, At, B1); PG8_BAR; PG8_SCHED;
;         }
;         if (wr == 0) PG8_BAR;
	s_add_i32 s24, s26, s15
	v_lshl_add_u64 v[202:203], v[202:203], 0, s[54:55]
	s_mov_b32 m0, s24
	ds_read_b128 v[160:163], v210 offset:49152
	ds_read_b128 v[164:167], v210 offset:50176
	ds_read_b128 v[168:171], v210 offset:51200
	ds_read_b128 v[172:175], v210 offset:52224
	ds_read_b128 v[188:191], v210 offset:53248
	ds_read_b128 v[192:195], v210 offset:54272
	ds_read_b128 v[198:201], v210 offset:55296
	ds_read_b128 v[212:215], v210 offset:56320
	global_load_lds_dwordx4 v[202:203], off
	s_add_i32 m0, s24, 0x2000
	s_add_u32 s24, vcc_lo, 0x80080
	v_lshl_add_u64 v[202:203], v[216:217], 0, s[54:55]
	s_addc_u32 s25, vcc_hi, 0
	s_add_i32 s26, s27, s15
	global_load_lds_dwordx4 v[202:203], off
	v_lshl_add_u64 v[202:203], s[24:25], 0, v[176:177]
	s_mov_b32 m0, s26
	s_nop 0
	global_load_lds_dwordx4 v[202:203], off
	v_lshl_add_u64 v[202:203], s[24:25], 0, v[178:179]
	s_add_i32 m0, s26, 0x2000
	s_nop 0
	global_load_lds_dwordx4 v[202:203], off
	v_lshl_add_u64 v[202:203], v[218:219], 0, s[54:55]
	s_mov_b32 m0, s50
	s_nop 0
	global_load_lds_dwordx4 v[202:203], off
	v_lshl_add_u64 v[202:203], v[220:221], 0, s[54:55]
	s_mov_b32 m0, s22
	s_nop 0
	global_load_lds_dwordx4 v[202:203], off
	s_waitcnt vmcnt(8)
	s_waitcnt lgkmcnt(0)
	s_barrier
	s_setprio 1
	s_waitcnt lgkmcnt(0)
	v_mfma_f32_16x16x32_bf16 v[76:79], v[56:59], v[160:163], v[76:79]
	v_mfma_f32_16x16x32_bf16 v[72:75], v[64:67], v[160:163], v[72:75]
	v_mfma_f32_16x16x32_bf16 v[44:47], v[56:59], v[168:171], v[44:47]
	v_mfma_f32_16x16x32_bf16 v[40:43], v[64:67], v[168:171], v[40:43]
	v_mfma_f32_16x16x32_bf16 v[28:31], v[56:59], v[188:191], v[28:31]
	v_mfma_f32_16x16x32_bf16 v[24:27], v[64:67], v[188:191], v[24:27]
	v_mfma_f32_16x16x32_bf16 v[12:15], v[56:59], v[198:201], v[12:15]
	v_mfma_f32_16x16x32_bf16 v[8:11], v[64:67], v[198:201], v[8:11]
	v_mfma_f32_16x16x32_bf16 v[76:79], v[60:63], v[164:167], v[76:79]
	v_mfma_f32_16x16x32_bf16 v[72:75], v[68:71], v[164:167], v[72:75]
	v_mfma_f32_16x16x32_bf16 v[44:47], v[60:63], v[172:175], v[44:47]
	v_mfma_f32_16x16x32_bf16 v[40:43], v[68:71], v[172:175], v[40:43]
	v_mfma_f32_16x16x32_bf16 v[28:31], v[60:63], v[192:195], v[28:31]
	v_mfma_f32_16x16x32_bf16 v[24:27], v[68:71], v[192:195], v[24:27]
	v_mfma_f32_16x16x32_bf16 v[12:15], v[60:63], v[212:215], v[12:15]
	v_mfma_f32_16x16x32_bf16 v[8:11], v[68:71], v[212:215], v[8:11]
	s_setprio 0
	s_setprio 1
	v_mfma_f32_16x16x32_bf16 v[52:55], v[144:147], v[160:163], v[52:55]
	v_mfma_f32_16x16x32_bf16 v[48:51], v[152:155], v[160:163], v[48:51]
	v_mfma_f32_16x16x32_bf16 v[36:39], v[144:147], v[168:171], v[36:39]
	v_mfma_f32_16x16x32_bf16 v[32:35], v[152:155], v[168:171], v[32:35]
	v_mfma_f32_16x16x32_bf16 v[20:23], v[144:147], v[188:191], v[20:23]
	v_mfma_f32_16x16x32_bf16 v[16:19], v[152:155], v[188:191], v[16:19]
	v_mfma_f32_16x16x32_bf16 v[4:7], v[144:147], v[198:201], v[4:7]
	v_mfma_f32_16x16x32_bf16 v[0:3], v[152:155], v[198:201], v[0:3]
	v_mfma_f32_16x16x32_bf16 v[52:55], v[148:151], v[164:167], v[52:55]
	v_mfma_f32_16x16x32_bf16 v[48:51], v[156:159], v[164:167], v[48:51]
	v_mfma_f32_16x16x32_bf16 v[36:39], v[148:151], v[172:175], v[36:39]
	v_mfma_f32_16x16x32_bf16 v[32:35], v[156:159], v[172:175], v[32:35]
	v_mfma_f32_16x16x32_bf16 v[20:23], v[148:151], v[192:195], v[20:23]
	v_mfma_f32_16x16x32_bf16 v[16:19], v[156:159], v[192:195], v[16:19]
	v_mfma_f32_16x16x32_bf16 v[4:7], v[148:151], v[212:215], v[4:7]
	v_mfma_f32_16x16x32_bf16 v[0:3], v[156:159], v[212:215], v[0:3]
	s_setprio 0
	s_barrier
	s_add_i32 s42, s42, 2
	s_add_u32 s38, s38, 0x100
	s_addc_u32 s39, s39, 0
	s_add_u32 s8, s8, 0x100
	s_addc_u32 s9, s9, 0
	s_cmp_gt_u32 s42, 29
	s_cbranch_scc0 .LBB0_993
	s_and_b64 vcc, exec, s[88:89]
	s_cbranch_vccz .LBB0_996
	s_barrier
